# v24 + G2 tail fill: blocks>=64 run norm2 for the 112 complete row tiles during G2's third tile round (device counter after each block's 2nd tile), norm2 phase only does the remaining 32 row tiles (lay
# baseline (speedup 1.0000x reference)
; __device__ __forceinline__ void phase_init(const Params& P, unsigned char* lds) {
;     ...
;     if (blk == 0) { if (tid < 4 * DEPTH) ctl[CW_QUEUE + 64 * tid] = 0u; for (int i = tid; i < XCD_BAR_WORDS_C; i += 512) ctl[CW_BAR + i] = 0u; }
.LBB0_2:
	s_or_b64 exec, exec, s[4:5]
	s_mov_b64 s[4:5], s[28:29]
	s_load_dwordx2 s[14:15], s[4:5], 0x8
	s_load_dwordx4 s[8:11], s[4:5], 0x18
	s_load_dwordx2 s[12:13], s[4:5], 0x28
	s_load_dwordx2 s[16:17], s[4:5], 0x40
	s_load_dwordx2 s[18:19], s[4:5], 0x50
	s_load_dwordx2 s[6:7], s[4:5], 0xa0
	v_mov_b32_e32 v30, v200
	s_cmp_lg_u32 s2, 0
	s_cbranch_scc1 .LBB0_14
	v_cmp_gt_i32_e32 vcc, 16, v30
	s_and_saveexec_b64 s[4:5], vcc
	s_cbranch_execz .LBB0_5
	v_lshlrev_b32_e32 v2, 6, v30
	v_ashrrev_i32_e32 v3, 31, v2
	s_waitcnt lgkmcnt(0)
	v_lshl_add_u64 v[2:3], v[2:3], 2, s[6:7]
	v_mov_b32_e32 v1, 0
	global_store_dword v[2:3], v1, off
	global_store_dword v[2:3], v1, off offset:64

;     __device__ __forceinline__ void operator()(const pg8::f32x4 (&acc)[2][2][4][2], const pg8::Unit& u, int wr, int wc, int fr, int fq) const {
;         const int b = u.pm / 9, j = u.pm - b * 9;
;         float* base = (j == 0) ? xc + (size_t)b * CTX * DM : out + ((size_t)b * SEQ + (size_t)(j - 1) * 256) * DM;
;         const float* g = gate + (size_t)((j == 0) ? 16 : b) * MODW;
;         const int col0 = u.pn * 256 + wc * 32 + 4 * fq;
;         pg8::f32x4 gv[2][2];
; #pragma unroll
;         for (int bj = 0; bj < 2; ++bj)
; #pragma unroll
;             for (int n = 0; n < 2; ++n) gv[bj][n] = *(const pg8::f32x4*)(g + col0 + bj * 128 + n * 16);
; #pragma unroll
;         for (int ai = 0; ai < 2; ++ai)
; #pragma unroll
;             for (int m = 0; m < 4; ++m) {
;                 float* rowp = base + (size_t)(ai * 128 + wr * 64 + m * 16 + fr) * DM + col0;
; #pragma unroll
;                 for (int bj = 0; bj < 2; ++bj)
; #pragma unroll
;                     for (int n = 0; n < 2; ++n) {
;                         pg8::f32x4* p = (pg8::f32x4*)(rowp + bj * 128 + n * 16);
;                         pg8::f32x4 xv = *p; xv = xv + gv[bj][n] * acc[ai][bj][m][n]; *p = xv;
;                     }
;                 if (m & 1) asm volatile("" ::: "memory");
;             }
.LBB0_854:
	s_lshl_b64 s[12:13], s[54:55], 2
	v_lshl_or_b32 v88, s62, 8, v171
	s_add_u32 s12, s41, s12
	v_ashrrev_i32_e32 v89, 31, v88
	s_addc_u32 s13, s0, s13
	v_lshlrev_b64 v[168:169], 2, v[88:89]
	v_lshl_add_u64 v[88:89], s[12:13], 0, v[168:169]
	v_lshl_add_u64 v[168:169], s[50:51], 0, v[168:169]
	v_lshl_add_u64 v[178:179], v[168:169], 0, v[148:149]
	global_load_dwordx4 v[108:111], v[88:89], off
	global_load_dwordx4 v[104:107], v[88:89], off offset:64
	global_load_dwordx4 v[100:103], v[88:89], off offset:512
	s_nop 0
	global_load_dwordx4 v[88:91], v[88:89], off offset:576
	s_mov_b64 s[50:51], -1
	global_load_dwordx4 v[174:177], v[178:179], off
	s_andn2_b64 vcc, exec, s[38:39]
	s_waitcnt vmcnt(0)
	v_pk_fma_f32 v[144:145], v[144:145], v[110:111], v[176:177]
	v_pk_fma_f32 v[142:143], v[142:143], v[108:109], v[174:175]
	global_store_dwordx4 v[178:179], v[142:145], off
	global_load_dwordx4 v[142:145], v[178:179], off offset:64
	s_waitcnt vmcnt(0)
	v_pk_fma_f32 v[140:141], v[140:141], v[106:107], v[144:145]
	v_pk_fma_f32 v[138:139], v[138:139], v[104:105], v[142:143]
	global_store_dwordx4 v[178:179], v[138:141], off offset:64
	global_load_dwordx4 v[138:141], v[178:179], off offset:512
	s_waitcnt vmcnt(0)
	v_pk_fma_f32 v[136:137], v[136:137], v[102:103], v[140:141]
	v_pk_fma_f32 v[134:135], v[134:135], v[100:101], v[138:139]
	global_store_dwordx4 v[178:179], v[134:137], off offset:512
	global_load_dwordx4 v[134:137], v[178:179], off offset:576
	s_waitcnt vmcnt(0)
	v_pk_fma_f32 v[126:127], v[126:127], v[90:91], v[136:137]
	v_pk_fma_f32 v[124:125], v[124:125], v[88:89], v[134:135]
	v_lshl_add_u64 v[134:135], v[168:169], 0, v[150:151]
	global_store_dwordx4 v[178:179], v[124:127], off offset:576
	global_load_dwordx4 v[124:127], v[134:135], off
	s_waitcnt vmcnt(0)
	v_pk_fma_f32 v[126:127], v[132:133], v[110:111], v[126:127]
	v_pk_fma_f32 v[124:125], v[130:131], v[108:109], v[124:125]
	global_store_dwordx4 v[134:135], v[124:127], off
	global_load_dwordx4 v[124:127], v[134:135], off offset:64
	s_waitcnt vmcnt(0)
	v_pk_fma_f32 v[122:123], v[122:123], v[106:107], v[126:127]
	v_pk_fma_f32 v[120:121], v[120:121], v[104:105], v[124:125]
	global_store_dwordx4 v[134:135], v[120:123], off offset:64
	global_load_dwordx4 v[120:123], v[134:135], off offset:512
	s_waitcnt vmcnt(0)
	v_pk_fma_f32 v[118:119], v[118:119], v[102:103], v[122:123]
	v_pk_fma_f32 v[116:117], v[116:117], v[100:101], v[120:121]
	global_store_dwordx4 v[134:135], v[116:119], off offset:512
	global_load_dwordx4 v[116:119], v[134:135], off offset:576
	s_waitcnt vmcnt(0)
	v_pk_fma_f32 v[114:115], v[114:115], v[90:91], v[118:119]
	v_pk_fma_f32 v[112:113], v[112:113], v[88:89], v[116:117]
	global_store_dwordx4 v[134:135], v[112:115], off offset:576
	v_lshl_add_u64 v[116:117], v[168:169], 0, v[152:153]
	global_load_dwordx4 v[112:115], v[116:117], off
	s_waitcnt vmcnt(0)
	v_pk_fma_f32 v[98:99], v[98:99], v[110:111], v[114:115]
	v_pk_fma_f32 v[96:97], v[96:97], v[108:109], v[112:113]
	global_store_dwordx4 v[116:117], v[96:99], off
	global_load_dwordx4 v[96:99], v[116:117], off offset:64
	s_waitcnt vmcnt(0)
	v_pk_fma_f32 v[94:95], v[94:95], v[106:107], v[98:99]
	v_pk_fma_f32 v[92:93], v[92:93], v[104:105], v[96:97]
	global_store_dwordx4 v[116:117], v[92:95], off offset:64
	global_load_dwordx4 v[92:95], v[116:117], off offset:512
	s_waitcnt vmcnt(0)
	v_pk_fma_f32 v[86:87], v[86:87], v[102:103], v[94:95]
	v_pk_fma_f32 v[84:85], v[84:85], v[100:101], v[92:93]
	global_store_dwordx4 v[116:117], v[84:87], off offset:512
	global_load_dwordx4 v[84:87], v[116:117], off offset:576
	s_waitcnt vmcnt(0)
	v_pk_fma_f32 v[78:79], v[78:79], v[90:91], v[86:87]
	v_pk_fma_f32 v[76:77], v[76:77], v[88:89], v[84:85]
	v_lshl_add_u64 v[84:85], v[168:169], 0, v[154:155]
	global_store_dwordx4 v[116:117], v[76:79], off offset:576
	global_load_dwordx4 v[76:79], v[84:85], off
	s_waitcnt vmcnt(0)
	v_pk_fma_f32 v[78:79], v[82:83], v[110:111], v[78:79]
	v_pk_fma_f32 v[76:77], v[80:81], v[108:109], v[76:77]
	global_store_dwordx4 v[84:85], v[76:79], off
	global_load_dwordx4 v[76:79], v[84:85], off offset:64
	s_waitcnt vmcnt(0)
	v_pk_fma_f32 v[74:75], v[74:75], v[106:107], v[78:79]
	v_pk_fma_f32 v[72:73], v[72:73], v[104:105], v[76:77]
	global_store_dwordx4 v[84:85], v[72:75], off offset:64
	global_load_dwordx4 v[72:75], v[84:85], off offset:512
	s_waitcnt vmcnt(0)
	v_pk_fma_f32 v[70:71], v[70:71], v[102:103], v[74:75]
	v_pk_fma_f32 v[68:69], v[68:69], v[100:101], v[72:73]
	global_store_dwordx4 v[84:85], v[68:71], off offset:512
	global_load_dwordx4 v[68:71], v[84:85], off offset:576
	s_waitcnt vmcnt(0)
; template <class Epi, class Sched, bool ALIGN_EPI = false, bool SP2 = false>
; __device__ __forceinline__ void gemm_phase(PG8_LAS unsigned char* lds, const Gemm g, const Sched& S, const Epi& E) {
;     ...
;         if constexpr (!Epi::AFTER_DRAIN) { E(acc, cur, wr, wc, fr, fq); S.done(cur); }
;     __device__ __forceinline__ void operator()(const pg8::f32x4 (&acc)[2][2][4][2], const pg8::Unit& u, int wr, int wc, int fr, int fq) const {
;     ...
;         for (int ai = 0; ai < 2; ++ai)
; #pragma unroll
;             for (int m = 0; m < 4; ++m) {
;                 float* rowp = base + (size_t)(ai * 128 + wr * 64 + m * 16 + fr) * DM + col0;
; #pragma unroll
;                 for (int bj = 0; bj < 2; ++bj)
; #pragma unroll
;                     for (int n = 0; n < 2; ++n) {
;                         pg8::f32x4* p = (pg8::f32x4*)(rowp + bj * 128 + n * 16);
;                         pg8::f32x4 xv = *p; xv = xv + gv[bj][n] * acc[ai][bj][m][n]; *p = xv;
;                     }
;                 if (m & 1) asm volatile("" ::: "memory");
;             }
	v_pk_fma_f32 v[66:67], v[66:67], v[90:91], v[70:71]
	v_pk_fma_f32 v[64:65], v[64:65], v[88:89], v[68:69]
	global_store_dwordx4 v[84:85], v[64:67], off offset:576
	v_lshl_add_u64 v[68:69], v[168:169], 0, v[156:157]
	global_load_dwordx4 v[64:67], v[68:69], off
	s_waitcnt vmcnt(0)
	v_pk_fma_f32 v[62:63], v[62:63], v[110:111], v[66:67]
	v_pk_fma_f32 v[60:61], v[60:61], v[108:109], v[64:65]
	global_store_dwordx4 v[68:69], v[60:63], off
	global_load_dwordx4 v[60:63], v[68:69], off offset:64
	s_waitcnt vmcnt(0)
	v_pk_fma_f32 v[58:59], v[58:59], v[106:107], v[62:63]
	v_pk_fma_f32 v[56:57], v[56:57], v[104:105], v[60:61]
	global_store_dwordx4 v[68:69], v[56:59], off offset:64
	global_load_dwordx4 v[56:59], v[68:69], off offset:512
	s_waitcnt vmcnt(0)
	v_pk_fma_f32 v[54:55], v[54:55], v[102:103], v[58:59]
	v_pk_fma_f32 v[52:53], v[52:53], v[100:101], v[56:57]
	global_store_dwordx4 v[68:69], v[52:55], off offset:512
	global_load_dwordx4 v[52:55], v[68:69], off offset:576
	s_waitcnt vmcnt(0)
	v_pk_fma_f32 v[46:47], v[46:47], v[90:91], v[54:55]
	v_pk_fma_f32 v[44:45], v[44:45], v[88:89], v[52:53]
	v_lshl_add_u64 v[52:53], v[168:169], 0, v[158:159]
	global_store_dwordx4 v[68:69], v[44:47], off offset:576
	global_load_dwordx4 v[44:47], v[52:53], off
	s_waitcnt vmcnt(0)
	v_pk_fma_f32 v[46:47], v[50:51], v[110:111], v[46:47]
	v_pk_fma_f32 v[44:45], v[48:49], v[108:109], v[44:45]
	global_store_dwordx4 v[52:53], v[44:47], off
	global_load_dwordx4 v[44:47], v[52:53], off offset:64
	s_waitcnt vmcnt(0)
	v_pk_fma_f32 v[42:43], v[42:43], v[106:107], v[46:47]
	v_pk_fma_f32 v[40:41], v[40:41], v[104:105], v[44:45]
	global_store_dwordx4 v[52:53], v[40:43], off offset:64
	global_load_dwordx4 v[40:43], v[52:53], off offset:512
	s_waitcnt vmcnt(0)
	v_pk_fma_f32 v[38:39], v[38:39], v[102:103], v[42:43]
	v_pk_fma_f32 v[36:37], v[36:37], v[100:101], v[40:41]
	global_store_dwordx4 v[52:53], v[36:39], off offset:512
	global_load_dwordx4 v[36:39], v[52:53], off offset:576
	s_waitcnt vmcnt(0)
	v_pk_fma_f32 v[34:35], v[34:35], v[90:91], v[38:39]
	v_pk_fma_f32 v[32:33], v[32:33], v[88:89], v[36:37]
	global_store_dwordx4 v[52:53], v[32:35], off offset:576
	v_lshl_add_u64 v[36:37], v[168:169], 0, v[160:161]
	global_load_dwordx4 v[32:35], v[36:37], off
	s_waitcnt vmcnt(0)
	v_pk_fma_f32 v[30:31], v[30:31], v[110:111], v[34:35]
	v_pk_fma_f32 v[28:29], v[28:29], v[108:109], v[32:33]
	global_store_dwordx4 v[36:37], v[28:31], off
	global_load_dwordx4 v[28:31], v[36:37], off offset:64
	s_waitcnt vmcnt(0)
	v_pk_fma_f32 v[26:27], v[26:27], v[106:107], v[30:31]
	v_pk_fma_f32 v[24:25], v[24:25], v[104:105], v[28:29]
	global_store_dwordx4 v[36:37], v[24:27], off offset:64
	global_load_dwordx4 v[24:27], v[36:37], off offset:512
	s_waitcnt vmcnt(0)
	v_pk_fma_f32 v[22:23], v[22:23], v[102:103], v[26:27]
	v_pk_fma_f32 v[20:21], v[20:21], v[100:101], v[24:25]
	global_store_dwordx4 v[36:37], v[20:23], off offset:512
	global_load_dwordx4 v[20:23], v[36:37], off offset:576
	s_waitcnt vmcnt(0)
	v_pk_fma_f32 v[14:15], v[14:15], v[90:91], v[22:23]
	v_pk_fma_f32 v[12:13], v[12:13], v[88:89], v[20:21]
	v_lshl_add_u64 v[20:21], v[168:169], 0, v[162:163]
	global_store_dwordx4 v[36:37], v[12:15], off offset:576
	global_load_dwordx4 v[12:15], v[20:21], off
	s_waitcnt vmcnt(0)
	v_pk_fma_f32 v[14:15], v[18:19], v[110:111], v[14:15]
	v_pk_fma_f32 v[12:13], v[16:17], v[108:109], v[12:13]
	global_store_dwordx4 v[20:21], v[12:15], off
	global_load_dwordx4 v[12:15], v[20:21], off offset:64
	s_waitcnt vmcnt(0)
	v_pk_fma_f32 v[10:11], v[10:11], v[106:107], v[14:15]
	v_pk_fma_f32 v[8:9], v[8:9], v[104:105], v[12:13]
	global_store_dwordx4 v[20:21], v[8:11], off offset:64
	global_load_dwordx4 v[8:11], v[20:21], off offset:512
	s_waitcnt vmcnt(0)
	v_pk_fma_f32 v[6:7], v[6:7], v[102:103], v[10:11]
	v_pk_fma_f32 v[4:5], v[4:5], v[100:101], v[8:9]
	global_store_dwordx4 v[20:21], v[4:7], off offset:512
	global_load_dwordx4 v[4:7], v[20:21], off offset:576
	s_waitcnt vmcnt(0)
	v_pk_fma_f32 v[2:3], v[2:3], v[90:91], v[6:7]
	v_pk_fma_f32 v[0:1], v[0:1], v[88:89], v[4:5]
	global_store_dwordx4 v[20:21], v[0:3], off offset:576
	s_cmp_lg_u32 s15, 2
	s_cbranch_scc1 .Lg2sig_skip
	s_waitcnt vmcnt(0)
	s_barrier
	v_readfirstlane_b32 s20, v200
	v_readlane_b32 s12, v254, 55
	v_readlane_b32 s13, v254, 56
	s_nop 3
	s_lshr_b32 s20, s20, 6
	s_cmp_lg_u32 s20, 0
	s_cbranch_scc1 .Lg2sig_skip
	s_load_dwordx2 s[12:13], s[12:13], 0xa0
	buffer_wbl2 sc1
	v_mov_b32_e32 v0, 1
	s_waitcnt vmcnt(0) lgkmcnt(0)
	s_mov_b64 s[34:35], exec
	s_mov_b64 exec, 1
	global_atomic_add v129, v0, s[12:13] offset:64
	s_mov_b64 exec, s[34:35]
.Lg2sig_skip:
	s_cbranch_vccnz .LBB0_844
	s_andn2_b64 vcc, exec, s[10:11]
	s_cbranch_vccnz .LBB0_843
	s_barrier
	s_branch .LBB0_843

; __device__ __forceinline__ int opaque_tid() { int t = threadIdx.x; asm volatile("" : "+v"(t)); return t; }
; __device__ __forceinline__ unsigned pk2(float lo, float hi) { f32x2_t v = {lo, hi}; bf16x2_t b = __builtin_convertvector(v, bf16x2_t); return __builtin_bit_cast(unsigned, b); }
; __device__ __forceinline__ float* xrow_ptr(const Params& P, int r) {
;     const int b = r / TT, t = r - b * TT;
;     return (t < CTX) ? (float*)(P.ws + WS_XC) + ((size_t)b * CTX + t) * DM : P.out + ((size_t)b * SEQ + (t - CTX)) * DM;
; __device__ __forceinline__ void phase_norm(const Params& P, int l, int which, bool first) {
;     const int tid = opaque_tid(), lane = tid & 63, wave = tid >> 6;
;     const int gw = blockIdx.x * 8 + wave, NGW = gridDim.x * 8;
;     const float* gain = (which == 0 ? P.norm1 : P.norm2) + (size_t)l * DM;
;     const float* mod = (const float*)(P.ws + WS_MOD) + (size_t)l * 17 * MODW + (which == 0 ? 0 : 3 * DM);
;     bf16_t* H = (bf16_t*)(P.ws + WS_H);
;     for (int r = gw; r < ROWS; r += NGW) {
;         const int b = r / TT, t = r - b * TT; const int bb = (t < CTX) ? 16 : b;
;         float* xr = xrow_ptr(P, r);
;         const float* src = first ? ((t < CTX) ? P.ctx + ((size_t)b * CTX + t) * DM : P.x + ((size_t)b * SEQ + (t - CTX)) * DM) : xr;
;         f32x4 v[4]; float s2 = 0.f;
; #pragma unroll
;         for (int j = 0; j < 4; ++j) { v[j] = *((const f32x4*)src + lane + 64 * j); s2 += (v[j].x * v[j].x + v[j].y * v[j].y) + (v[j].z * v[j].z + v[j].w * v[j].w); }
;         if (first) {
; #pragma unroll
;             for (int j = 0; j < 4; ++j) *((f32x4*)xr + lane + 64 * j) = v[j];
;         }
;         const float rstd = 1.0f / sqrtf(wave_sum(s2, lane) * (1.0f / DM) + RMS_EPS);
;         const float* mrow = mod + (size_t)bb * MODW;
; #pragma unroll
;         for (int j = 0; j < 4; ++j) {
;             const int c0 = 4 * (lane + 64 * j);
;             const f32x4 g = *(const f32x4*)(gain + c0), sh = *(const f32x4*)(mrow + c0), scl = *(const f32x4*)(mrow + DM + c0);
;             const f32x4 y = v[j] * rstd * g * (scl + 1.0f) + sh;
;             u32x2 w; w.x = pk2(y.x, y.y); w.y = pk2(y.z, y.w);
;             *(u32x2*)(H + (size_t)r * DM + c0) = w;
;         }
.LBB0_858:
	s_waitcnt vmcnt(0)
	v_readlane_b32 s68, v254, 57
	v_readlane_b32 s62, v254, 59
	v_readlane_b32 s69, v254, 58
	v_readlane_b32 s63, v254, 60
	s_barrier
	s_cmp_lg_u32 s60, 0x100
	s_cbranch_scc1 .Lg2t_done
	s_cmp_lt_u32 s2, 64
	s_cbranch_scc1 .Lg2t_done
	v_readlane_b32 s24, v254, 55
	v_readlane_b32 s25, v254, 56
	v_readlane_b32 s8, v255, 0
	s_nop 3
	s_load_dwordx2 s[0:1], s[24:25], 0xa0
	s_add_u32 s8, s8, 1
	s_lshl_b32 s8, s8, 8
	s_mov_b32 s9, 0
	s_waitcnt lgkmcnt(0)
.Lg2t_spin:
	global_load_dword v0, v129, s[0:1] offset:64 sc1
	s_waitcnt vmcnt(0)
	v_readfirstlane_b32 s36, v0
	s_nop 3
	s_cmp_ge_u32 s36, s8
	s_cbranch_scc1 .Lg2t_go
	s_sleep 2
	s_add_u32 s9, s9, 1
	s_cmp_lt_u32 s9, 0x8000
	s_cbranch_scc1 .Lg2t_spin
.Lg2t_go:
	buffer_inv sc1
	s_waitcnt vmcnt(0)
	s_load_dwordx4 s[44:47], s[24:25], 0x98
	s_load_dwordx2 s[0:1], s[24:25], 0x78
	v_readlane_b32 s8, v255, 2
	v_readlane_b32 s9, v254, 63
	v_readlane_b32 s100, v255, 0
	v_readfirstlane_b32 s101, v200
	s_nop 3
	s_lshr_b32 s101, s101, 6
	s_sub_u32 s42, s2, 64
	s_lshl_b32 s42, s42, 3
	s_add_u32 s101, s101, s42
	v_and_b32_e32 v120, 63, v200
	v_lshlrev_b32_e32 v121, 3, v120
	v_lshlrev_b32_e32 v32, 2, v120
	v_xor_b32_e32 v122, 4, v32
	v_xor_b32_e32 v123, 8, v32
	v_xor_b32_e32 v124, 16, v32
	v_xor_b32_e32 v125, 32, v32
	v_xor_b32_e32 v126, 64, v32
	v_xor_b32_e32 v127, 0x80, v32
	v_lshlrev_b32_e32 v120, 4, v120
	s_waitcnt lgkmcnt(0)
	s_add_u32 s8, s46, s8
	s_addc_u32 s9, s47, s9
	s_add_u32 s24, s8, 0x104000
	s_addc_u32 s25, s9, 0
	s_lshl_b32 s100, s100, 12
	s_add_u32 s0, s0, s100
	s_addc_u32 s1, s1, 0
	s_add_u32 s36, s46, 0x4500000
	s_addc_u32 s37, s47, 0
	global_load_dwordx4 v[162:165], v120, s[0:1]
	global_load_dwordx4 v[166:169], v120, s[0:1] offset:1024
	global_load_dwordx4 v[170:173], v120, s[0:1] offset:2048
	global_load_dwordx4 v[174:177], v120, s[0:1] offset:3072
	s_lshr_b32 s42, s101, 8
	s_mov_b32 vcc_lo, s42
	s_cmp_ge_u32 s42, 16
	s_cselect_b32 vcc_hi, 4, 0
	s_add_u32 vcc_lo, vcc_lo, vcc_hi
	s_cmp_ge_u32 s42, 28
	s_cselect_b32 vcc_hi, 4, 0
	s_add_u32 vcc_lo, vcc_lo, vcc_hi
	s_cmp_ge_u32 s42, 44
	s_cselect_b32 vcc_hi, 4, 0
	s_add_u32 vcc_lo, vcc_lo, vcc_hi
	s_cmp_ge_u32 s42, 56
	s_cselect_b32 vcc_hi, 4, 0
	s_add_u32 vcc_lo, vcc_lo, vcc_hi
	s_cmp_ge_u32 s42, 72
	s_cselect_b32 vcc_hi, 4, 0
	s_add_u32 vcc_lo, vcc_lo, vcc_hi
	s_cmp_ge_u32 s42, 84
	s_cselect_b32 vcc_hi, 4, 0
	s_add_u32 vcc_lo, vcc_lo, vcc_hi
	s_cmp_ge_u32 s42, 100
	s_cselect_b32 vcc_hi, 4, 0
	s_add_u32 vcc_lo, vcc_lo, vcc_hi
	s_cmp_ge_u32 s42, 112
	s_cselect_b32 vcc_hi, 4, 0
	s_add_u32 vcc_lo, vcc_lo, vcc_hi
	s_and_b32 s43, s101, 0xff
	s_lshl_b32 vcc_lo, vcc_lo, 8
	s_or_b32 s43, s43, vcc_lo
	s_lshr_b32 s8, s43, 8
	s_mul_i32 s8, s8, 57
	s_lshr_b32 s8, s8, 9
	s_mul_i32 s9, s8, 0x900
	s_sub_u32 s9, s43, s9
	s_lshl_b32 s0, s8, 11
	s_add_u32 s0, s0, s9
	s_sub_u32 s0, s0, 0x100
	s_lshl_b32 s8, s8, 8
	s_add_u32 s8, s8, s9
	s_cmp_lt_u32 s9, 0x100
	s_cselect_b32 s8, s8, s0
	s_cselect_b32 s0, s36, s44
	s_cselect_b32 s1, s37, s45
	s_lshl_b32 s8, s8, 12
	s_add_u32 s0, s0, s8
	s_addc_u32 s1, s1, 0
	global_load_dwordx4 v[0:3], v120, s[0:1]
	global_load_dwordx4 v[4:7], v120, s[0:1] offset:1024
	global_load_dwordx4 v[8:11], v120, s[0:1] offset:2048
	global_load_dwordx4 v[12:15], v120, s[0:1] offset:3072
	s_add_u32 s100, s101, 1536
	s_cmp_le_u32 s100, 28671
	s_cselect_b32 s100, s100, s101
	s_lshr_b32 s42, s100, 8
	s_mov_b32 vcc_lo, s42
	s_cmp_ge_u32 s42, 16
	s_cselect_b32 vcc_hi, 4, 0
	s_add_u32 vcc_lo, vcc_lo, vcc_hi
	s_cmp_ge_u32 s42, 28
	s_cselect_b32 vcc_hi, 4, 0
	s_add_u32 vcc_lo, vcc_lo, vcc_hi
	s_cmp_ge_u32 s42, 44
	s_cselect_b32 vcc_hi, 4, 0
	s_add_u32 vcc_lo, vcc_lo, vcc_hi
	s_cmp_ge_u32 s42, 56
	s_cselect_b32 vcc_hi, 4, 0
	s_add_u32 vcc_lo, vcc_lo, vcc_hi
	s_cmp_ge_u32 s42, 72
	s_cselect_b32 vcc_hi, 4, 0
	s_add_u32 vcc_lo, vcc_lo, vcc_hi
	s_cmp_ge_u32 s42, 84
	s_cselect_b32 vcc_hi, 4, 0
	s_add_u32 vcc_lo, vcc_lo, vcc_hi
	s_cmp_ge_u32 s42, 100
	s_cselect_b32 vcc_hi, 4, 0
	s_add_u32 vcc_lo, vcc_lo, vcc_hi
	s_cmp_ge_u32 s42, 112
	s_cselect_b32 vcc_hi, 4, 0
	s_add_u32 vcc_lo, vcc_lo, vcc_hi
	s_and_b32 s43, s100, 0xff
	s_lshl_b32 vcc_lo, vcc_lo, 8
	s_or_b32 s43, s43, vcc_lo
	s_lshr_b32 s8, s43, 8
	s_mul_i32 s8, s8, 57
	s_lshr_b32 s8, s8, 9
	s_mul_i32 s9, s8, 0x900
	s_sub_u32 s9, s43, s9
	s_lshl_b32 s0, s8, 11
	s_add_u32 s0, s0, s9
	s_sub_u32 s0, s0, 0x100
	s_lshl_b32 s8, s8, 8
	s_add_u32 s8, s8, s9
	s_cmp_lt_u32 s9, 0x100
	s_cselect_b32 s8, s8, s0
	s_cselect_b32 s0, s36, s44
	s_cselect_b32 s1, s37, s45
	s_lshl_b32 s8, s8, 12
	s_add_u32 s0, s0, s8
	s_addc_u32 s1, s1, 0
	global_load_dwordx4 v[16:19], v120, s[0:1]
	global_load_dwordx4 v[20:23], v120, s[0:1] offset:1024
	global_load_dwordx4 v[24:27], v120, s[0:1] offset:2048
	global_load_dwordx4 v[28:31], v120, s[0:1] offset:3072
	s_add_u32 s100, s101, 3072
	s_cmp_le_u32 s100, 28671
	s_cselect_b32 s100, s100, s101
	s_lshr_b32 s42, s100, 8
	s_mov_b32 vcc_lo, s42
	s_cmp_ge_u32 s42, 16
	s_cselect_b32 vcc_hi, 4, 0
	s_add_u32 vcc_lo, vcc_lo, vcc_hi
	s_cmp_ge_u32 s42, 28
	s_cselect_b32 vcc_hi, 4, 0
	s_add_u32 vcc_lo, vcc_lo, vcc_hi
	s_cmp_ge_u32 s42, 44
	s_cselect_b32 vcc_hi, 4, 0
	s_add_u32 vcc_lo, vcc_lo, vcc_hi
	s_cmp_ge_u32 s42, 56
	s_cselect_b32 vcc_hi, 4, 0
	s_add_u32 vcc_lo, vcc_lo, vcc_hi
	s_cmp_ge_u32 s42, 72
	s_cselect_b32 vcc_hi, 4, 0
	s_add_u32 vcc_lo, vcc_lo, vcc_hi
	s_cmp_ge_u32 s42, 84
	s_cselect_b32 vcc_hi, 4, 0
	s_add_u32 vcc_lo, vcc_lo, vcc_hi
	s_cmp_ge_u32 s42, 100
	s_cselect_b32 vcc_hi, 4, 0
	s_add_u32 vcc_lo, vcc_lo, vcc_hi
	s_cmp_ge_u32 s42, 112
	s_cselect_b32 vcc_hi, 4, 0
	s_add_u32 vcc_lo, vcc_lo, vcc_hi
	s_and_b32 s43, s100, 0xff
	s_lshl_b32 vcc_lo, vcc_lo, 8
; __device__ __forceinline__ void phase_norm(const Params& P, int l, int which, bool first) {
;     ...
;     for (int r = gw; r < ROWS; r += NGW) {
;         const int b = r / TT, t = r - b * TT; const int bb = (t < CTX) ? 16 : b;
;         float* xr = xrow_ptr(P, r);
;         const float* src = first ? ((t < CTX) ? P.ctx + ((size_t)b * CTX + t) * DM : P.x + ((size_t)b * SEQ + (t - CTX)) * DM) : xr;
;         f32x4 v[4]; float s2 = 0.f;
; #pragma unroll
;         for (int j = 0; j < 4; ++j) { v[j] = *((const f32x4*)src + lane + 64 * j); s2 += (v[j].x * v[j].x + v[j].y * v[j].y) + (v[j].z * v[j].z + v[j].w * v[j].w); }
;     ...
;         const float* mrow = mod + (size_t)bb * MODW;
; #pragma unroll
;         for (int j = 0; j < 4; ++j) {
;             const int c0 = 4 * (lane + 64 * j);
;             const f32x4 g = *(const f32x4*)(gain + c0), sh = *(const f32x4*)(mrow + c0), scl = *(const f32x4*)(mrow + DM + c0);
	s_or_b32 s43, s43, vcc_lo
	s_lshr_b32 s8, s43, 8
	s_mul_i32 s8, s8, 57
	s_lshr_b32 s8, s8, 9
	s_mul_i32 s9, s8, 0x900
	s_sub_u32 s9, s43, s9
	s_lshl_b32 s0, s8, 11
	s_add_u32 s0, s0, s9
	s_sub_u32 s0, s0, 0x100
	s_lshl_b32 s8, s8, 8
	s_add_u32 s8, s8, s9
	s_cmp_lt_u32 s9, 0x100
	s_cselect_b32 s8, s8, s0
	s_cselect_b32 s0, s36, s44
	s_cselect_b32 s1, s37, s45
	s_lshl_b32 s8, s8, 12
	s_add_u32 s0, s0, s8
	s_addc_u32 s1, s1, 0
	global_load_dwordx4 v[40:43], v120, s[0:1]
	global_load_dwordx4 v[44:47], v120, s[0:1] offset:1024
	global_load_dwordx4 v[48:51], v120, s[0:1] offset:2048
	global_load_dwordx4 v[52:55], v120, s[0:1] offset:3072
	s_lshr_b32 s42, s101, 8
	s_mov_b32 vcc_lo, s42
	s_cmp_ge_u32 s42, 16
	s_cselect_b32 vcc_hi, 4, 0
	s_add_u32 vcc_lo, vcc_lo, vcc_hi
	s_cmp_ge_u32 s42, 28
	s_cselect_b32 vcc_hi, 4, 0
	s_add_u32 vcc_lo, vcc_lo, vcc_hi
	s_cmp_ge_u32 s42, 44
	s_cselect_b32 vcc_hi, 4, 0
	s_add_u32 vcc_lo, vcc_lo, vcc_hi
	s_cmp_ge_u32 s42, 56
	s_cselect_b32 vcc_hi, 4, 0
	s_add_u32 vcc_lo, vcc_lo, vcc_hi
	s_cmp_ge_u32 s42, 72
	s_cselect_b32 vcc_hi, 4, 0
	s_add_u32 vcc_lo, vcc_lo, vcc_hi
	s_cmp_ge_u32 s42, 84
	s_cselect_b32 vcc_hi, 4, 0
	s_add_u32 vcc_lo, vcc_lo, vcc_hi
	s_cmp_ge_u32 s42, 100
	s_cselect_b32 vcc_hi, 4, 0
	s_add_u32 vcc_lo, vcc_lo, vcc_hi
	s_cmp_ge_u32 s42, 112
	s_cselect_b32 vcc_hi, 4, 0
	s_add_u32 vcc_lo, vcc_lo, vcc_hi
	s_and_b32 s43, s101, 0xff
	s_lshl_b32 vcc_lo, vcc_lo, 8
	s_or_b32 s43, s43, vcc_lo
	s_lshr_b32 s8, s43, 8
	s_mul_i32 s8, s8, 57
	s_lshr_b32 s8, s8, 9
	s_mul_i32 s9, s8, 0x900
	s_sub_u32 s9, s43, s9
	s_cmp_lt_u32 s9, 0x100
	s_cselect_b32 s8, 16, s8
	s_mul_i32 s8, s8, 0x6000
	s_add_u32 s0, s24, s8
	s_addc_u32 s1, s25, 0
	global_load_dwordx4 v[56:59], v120, s[0:1] offset:-4096
	global_load_dwordx4 v[60:63], v120, s[0:1] offset:-3072
	global_load_dwordx4 v[64:67], v120, s[0:1] offset:-2048
	global_load_dwordx4 v[68:71], v120, s[0:1] offset:-1024
	global_load_dwordx4 v[72:75], v120, s[0:1]
	global_load_dwordx4 v[76:79], v120, s[0:1] offset:1024
	global_load_dwordx4 v[80:83], v120, s[0:1] offset:2048
	global_load_dwordx4 v[84:87], v120, s[0:1] offset:3072
	s_waitcnt vmcnt(16)
	s_add_u32 s100, s101, 1536
	s_cmp_le_u32 s100, 28671
	s_cselect_b32 s100, s100, s101
	s_lshr_b32 s42, s100, 8
	s_mov_b32 vcc_lo, s42
	s_cmp_ge_u32 s42, 16
	s_cselect_b32 vcc_hi, 4, 0
	s_add_u32 vcc_lo, vcc_lo, vcc_hi
	s_cmp_ge_u32 s42, 28
	s_cselect_b32 vcc_hi, 4, 0
	s_add_u32 vcc_lo, vcc_lo, vcc_hi
	s_cmp_ge_u32 s42, 44
	s_cselect_b32 vcc_hi, 4, 0
	s_add_u32 vcc_lo, vcc_lo, vcc_hi
	s_cmp_ge_u32 s42, 56
	s_cselect_b32 vcc_hi, 4, 0
	s_add_u32 vcc_lo, vcc_lo, vcc_hi
	s_cmp_ge_u32 s42, 72
	s_cselect_b32 vcc_hi, 4, 0
	s_add_u32 vcc_lo, vcc_lo, vcc_hi
	s_cmp_ge_u32 s42, 84
	s_cselect_b32 vcc_hi, 4, 0
	s_add_u32 vcc_lo, vcc_lo, vcc_hi
	s_cmp_ge_u32 s42, 100
	s_cselect_b32 vcc_hi, 4, 0
	s_add_u32 vcc_lo, vcc_lo, vcc_hi
	s_cmp_ge_u32 s42, 112
	s_cselect_b32 vcc_hi, 4, 0
	s_add_u32 vcc_lo, vcc_lo, vcc_hi
	s_and_b32 s43, s100, 0xff
	s_lshl_b32 vcc_lo, vcc_lo, 8
	s_or_b32 s43, s43, vcc_lo
	s_lshr_b32 s8, s43, 8
	s_mul_i32 s8, s8, 57
	s_lshr_b32 s8, s8, 9
	s_mul_i32 s9, s8, 0x900
	s_sub_u32 s9, s43, s9
	s_cmp_lt_u32 s9, 0x100
	s_cselect_b32 s8, 16, s8
	s_mul_i32 s8, s8, 0x6000
	s_add_u32 s0, s24, s8
	s_addc_u32 s1, s25, 0
	global_load_dwordx4 v[88:91], v120, s[0:1] offset:-4096
	global_load_dwordx4 v[92:95], v120, s[0:1] offset:-3072
	global_load_dwordx4 v[96:99], v120, s[0:1] offset:-2048
	global_load_dwordx4 v[100:103], v120, s[0:1] offset:-1024
	global_load_dwordx4 v[104:107], v120, s[0:1]
	global_load_dwordx4 v[108:111], v120, s[0:1] offset:1024
	global_load_dwordx4 v[112:115], v120, s[0:1] offset:2048
	global_load_dwordx4 v[116:119], v120, s[0:1] offset:3072
	v_mul_f32_e32 v32, v1, v1
	v_mul_f32_e32 v33, v3, v3
	v_fmac_f32_e32 v32, v0, v0
	v_fmac_f32_e32 v33, v2, v2
	v_add_f32_e32 v34, v32, v33
	v_mul_f32_e32 v32, v5, v5
	v_mul_f32_e32 v33, v7, v7
	v_fmac_f32_e32 v32, v4, v4
	v_fmac_f32_e32 v33, v6, v6
	v_add_f32_e32 v32, v32, v33
	v_add_f32_e32 v34, v34, v32
	v_mul_f32_e32 v32, v9, v9
	v_mul_f32_e32 v33, v11, v11
	v_fmac_f32_e32 v32, v8, v8
	v_fmac_f32_e32 v33, v10, v10
	v_add_f32_e32 v32, v32, v33
	v_add_f32_e32 v34, v34, v32
	v_mul_f32_e32 v32, v13, v13
	v_mul_f32_e32 v33, v15, v15
	v_fmac_f32_e32 v32, v12, v12
	v_fmac_f32_e32 v33, v14, v14
	v_add_f32_e32 v32, v32, v33
	v_add_f32_e32 v34, v34, v32
	ds_bpermute_b32 v32, v122, v34
	s_waitcnt lgkmcnt(0)
	v_add_f32_e32 v34, v34, v32
	ds_bpermute_b32 v32, v123, v34
	s_waitcnt lgkmcnt(0)
	v_add_f32_e32 v34, v34, v32
	ds_bpermute_b32 v32, v124, v34
	s_waitcnt lgkmcnt(0)
	v_add_f32_e32 v34, v34, v32
	ds_bpermute_b32 v32, v125, v34
	s_waitcnt lgkmcnt(0)
	v_add_f32_e32 v34, v34, v32
	ds_bpermute_b32 v32, v126, v34
	s_waitcnt lgkmcnt(0)
	v_add_f32_e32 v34, v34, v32
	ds_bpermute_b32 v32, v127, v34
	s_waitcnt lgkmcnt(0)
; __device__ __forceinline__ unsigned pk2(float lo, float hi) { f32x2_t v = {lo, hi}; bf16x2_t b = __builtin_convertvector(v, bf16x2_t); return __builtin_bit_cast(unsigned, b); }
; __device__ __forceinline__ void phase_norm(const Params& P, int l, int which, bool first) {
;     ...
;         const float rstd = 1.0f / sqrtf(wave_sum(s2, lane) * (1.0f / DM) + RMS_EPS);
;         const float* mrow = mod + (size_t)bb * MODW;
; #pragma unroll
;         for (int j = 0; j < 4; ++j) {
;             const int c0 = 4 * (lane + 64 * j);
;             const f32x4 g = *(const f32x4*)(gain + c0), sh = *(const f32x4*)(mrow + c0), scl = *(const f32x4*)(mrow + DM + c0);
;             const f32x4 y = v[j] * rstd * g * (scl + 1.0f) + sh;
;             u32x2 w; w.x = pk2(y.x, y.y); w.y = pk2(y.z, y.w);
;             *(u32x2*)(H + (size_t)r * DM + c0) = w;
;         }
	v_add_f32_e32 v34, v34, v32
	v_fmamk_f32 v34, v34, 0x3a800000, v201
	v_cmp_gt_f32_e32 vcc, 0xf800000, v34
	v_mul_f32_e32 v32, 0x4f800000, v34
	s_nop 0
	v_cndmask_b32_e32 v34, v34, v32, vcc
	v_sqrt_f32_e32 v32, v34
	s_nop 0
	v_add_u32_e32 v35, -1, v32
	v_fma_f32 v36, -v35, v32, v34
	v_cmp_ge_f32_e64 s[42:43], 0, v36
	v_add_u32_e32 v36, 1, v32
	s_nop 0
	v_cndmask_b32_e64 v35, v32, v35, s[42:43]
	v_fma_f32 v32, -v36, v32, v34
	v_cmp_lt_f32_e64 s[42:43], 0, v32
	s_nop 1
	v_cndmask_b32_e64 v32, v35, v36, s[42:43]
	v_mul_f32_e32 v35, 0x37800000, v32
	v_cndmask_b32_e32 v32, v32, v35, vcc
	v_cmp_class_f32_e32 vcc, v34, v202
	s_nop 1
	v_cndmask_b32_e32 v34, v32, v34, vcc
	v_div_scale_f32 v32, s[42:43], v34, v34, 1.0
	v_rcp_f32_e32 v35, v32
	s_nop 0
	v_fma_f32 v36, -v32, v35, 1.0
	v_fmac_f32_e32 v35, v36, v35
	v_div_scale_f32 v36, vcc, 1.0, v34, 1.0
	v_mul_f32_e32 v37, v36, v35
	v_fma_f32 v178, -v32, v37, v36
	v_fmac_f32_e32 v37, v178, v35
	v_fma_f32 v32, -v32, v37, v36
	v_div_fmas_f32 v32, v32, v35, v37
	v_div_fixup_f32 v179, v32, v34, 1.0
	s_lshr_b32 s42, s101, 8
	s_mov_b32 vcc_lo, s42
	s_cmp_ge_u32 s42, 16
	s_cselect_b32 vcc_hi, 4, 0
	s_add_u32 vcc_lo, vcc_lo, vcc_hi
	s_cmp_ge_u32 s42, 28
	s_cselect_b32 vcc_hi, 4, 0
	s_add_u32 vcc_lo, vcc_lo, vcc_hi
	s_cmp_ge_u32 s42, 44
	s_cselect_b32 vcc_hi, 4, 0
	s_add_u32 vcc_lo, vcc_lo, vcc_hi
	s_cmp_ge_u32 s42, 56
	s_cselect_b32 vcc_hi, 4, 0
	s_add_u32 vcc_lo, vcc_lo, vcc_hi
	s_cmp_ge_u32 s42, 72
	s_cselect_b32 vcc_hi, 4, 0
	s_add_u32 vcc_lo, vcc_lo, vcc_hi
	s_cmp_ge_u32 s42, 84
	s_cselect_b32 vcc_hi, 4, 0
	s_add_u32 vcc_lo, vcc_lo, vcc_hi
	s_cmp_ge_u32 s42, 100
	s_cselect_b32 vcc_hi, 4, 0
	s_add_u32 vcc_lo, vcc_lo, vcc_hi
	s_cmp_ge_u32 s42, 112
	s_cselect_b32 vcc_hi, 4, 0
	s_add_u32 vcc_lo, vcc_lo, vcc_hi
	s_and_b32 s43, s101, 0xff
	s_lshl_b32 vcc_lo, vcc_lo, 8
	s_or_b32 s43, s43, vcc_lo
	s_lshl_b32 s8, s43, 11
	s_add_u32 s0, s46, s8
	s_addc_u32 s1, s47, 0
	s_add_u32 s0, s0, 0x5500000
	s_addc_u32 s1, s1, 0
	s_waitcnt vmcnt(8)
	v_mul_f32_e32 v193, v0, v179
	v_add_f32_e32 v192, 1.0, v72
	v_mul_f32_e32 v193, v162, v193
	v_fma_f32 v180, v192, v193, v56
	v_mul_f32_e32 v193, v1, v179
	v_add_f32_e32 v192, 1.0, v73
	v_mul_f32_e32 v193, v163, v193
	v_fma_f32 v181, v192, v193, v57
	v_mul_f32_e32 v193, v2, v179
	v_add_f32_e32 v192, 1.0, v74
	v_mul_f32_e32 v193, v164, v193
	v_fma_f32 v182, v192, v193, v58
	v_mul_f32_e32 v193, v3, v179
	v_add_f32_e32 v192, 1.0, v75
	v_mul_f32_e32 v193, v165, v193
	v_fma_f32 v183, v192, v193, v59
	v_cvt_pk_bf16_f32 v184, v180, v181
	v_cvt_pk_bf16_f32 v185, v182, v183
	global_store_dwordx2 v121, v[184:185], s[0:1]
	v_mul_f32_e32 v193, v4, v179
	v_add_f32_e32 v192, 1.0, v76
	v_mul_f32_e32 v193, v166, v193
	v_fma_f32 v180, v192, v193, v60
	v_mul_f32_e32 v193, v5, v179
	v_add_f32_e32 v192, 1.0, v77
	v_mul_f32_e32 v193, v167, v193
	v_fma_f32 v181, v192, v193, v61
	v_mul_f32_e32 v193, v6, v179
	v_add_f32_e32 v192, 1.0, v78
	v_mul_f32_e32 v193, v168, v193
	v_fma_f32 v182, v192, v193, v62
	v_mul_f32_e32 v193, v7, v179
	v_add_f32_e32 v192, 1.0, v79
	v_mul_f32_e32 v193, v169, v193
	v_fma_f32 v183, v192, v193, v63
	v_cvt_pk_bf16_f32 v186, v180, v181
	v_cvt_pk_bf16_f32 v187, v182, v183
	global_store_dwordx2 v121, v[186:187], s[0:1] offset:512
	v_mul_f32_e32 v193, v8, v179
	v_add_f32_e32 v192, 1.0, v80
	v_mul_f32_e32 v193, v170, v193
	v_fma_f32 v180, v192, v193, v64
	v_mul_f32_e32 v193, v9, v179
	v_add_f32_e32 v192, 1.0, v81
	v_mul_f32_e32 v193, v171, v193
	v_fma_f32 v181, v192, v193, v65
	v_mul_f32_e32 v193, v10, v179
	v_add_f32_e32 v192, 1.0, v82
	v_mul_f32_e32 v193, v172, v193
	v_fma_f32 v182, v192, v193, v66
	v_mul_f32_e32 v193, v11, v179
	v_add_f32_e32 v192, 1.0, v83
	v_mul_f32_e32 v193, v173, v193
	v_fma_f32 v183, v192, v193, v67
	v_cvt_pk_bf16_f32 v188, v180, v181
	v_cvt_pk_bf16_f32 v189, v182, v183
	global_store_dwordx2 v121, v[188:189], s[0:1] offset:1024
	v_mul_f32_e32 v193, v12, v179
	v_add_f32_e32 v192, 1.0, v84
	v_mul_f32_e32 v193, v174, v193
	v_fma_f32 v180, v192, v193, v68
	v_mul_f32_e32 v193, v13, v179
	v_add_f32_e32 v192, 1.0, v85
	v_mul_f32_e32 v193, v175, v193
	v_fma_f32 v181, v192, v193, v69
	v_mul_f32_e32 v193, v14, v179
	v_add_f32_e32 v192, 1.0, v86
	v_mul_f32_e32 v193, v176, v193
	v_fma_f32 v182, v192, v193, v70
	v_mul_f32_e32 v193, v15, v179
	v_add_f32_e32 v192, 1.0, v87
	v_mul_f32_e32 v193, v177, v193
	v_fma_f32 v183, v192, v193, v71
	v_cvt_pk_bf16_f32 v190, v180, v181
	v_cvt_pk_bf16_f32 v191, v182, v183
	global_store_dwordx2 v121, v[190:191], s[0:1] offset:1536
	s_add_u32 s100, s101, 4608
	s_cmp_le_u32 s100, 28671
	s_cselect_b32 s100, s100, s101
	s_lshr_b32 s42, s100, 8
	s_mov_b32 vcc_lo, s42
	s_cmp_ge_u32 s42, 16
	s_cselect_b32 vcc_hi, 4, 0
	s_add_u32 vcc_lo, vcc_lo, vcc_hi
	s_cmp_ge_u32 s42, 28
	s_cselect_b32 vcc_hi, 4, 0
	s_add_u32 vcc_lo, vcc_lo, vcc_hi
	s_cmp_ge_u32 s42, 44
	s_cselect_b32 vcc_hi, 4, 0
	s_add_u32 vcc_lo, vcc_lo, vcc_hi
	s_cmp_ge_u32 s42, 56
	s_cselect_b32 vcc_hi, 4, 0
	s_add_u32 vcc_lo, vcc_lo, vcc_hi
	s_cmp_ge_u32 s42, 72
	s_cselect_b32 vcc_hi, 4, 0
	s_add_u32 vcc_lo, vcc_lo, vcc_hi
	s_cmp_ge_u32 s42, 84
	s_cselect_b32 vcc_hi, 4, 0
	s_add_u32 vcc_lo, vcc_lo, vcc_hi
	s_cmp_ge_u32 s42, 100
	s_cselect_b32 vcc_hi, 4, 0
	s_add_u32 vcc_lo, vcc_lo, vcc_hi
	s_cmp_ge_u32 s42, 112
	s_cselect_b32 vcc_hi, 4, 0
	s_add_u32 vcc_lo, vcc_lo, vcc_hi
	s_and_b32 s43, s100, 0xff
	s_lshl_b32 vcc_lo, vcc_lo, 8
	s_or_b32 s43, s43, vcc_lo
	s_lshr_b32 s8, s43, 8
	s_mul_i32 s8, s8, 57
	s_lshr_b32 s8, s8, 9
	s_mul_i32 s9, s8, 0x900
	s_sub_u32 s9, s43, s9
	s_lshl_b32 s0, s8, 11
	s_add_u32 s0, s0, s9
	s_sub_u32 s0, s0, 0x100
	s_lshl_b32 s8, s8, 8
	s_add_u32 s8, s8, s9
	s_cmp_lt_u32 s9, 0x100
	s_cselect_b32 s8, s8, s0
	s_cselect_b32 s0, s36, s44
	s_cselect_b32 s1, s37, s45
	s_lshl_b32 s8, s8, 12
	s_add_u32 s0, s0, s8
	s_addc_u32 s1, s1, 0
	global_load_dwordx4 v[0:3], v120, s[0:1]
	global_load_dwordx4 v[4:7], v120, s[0:1] offset:1024
	global_load_dwordx4 v[8:11], v120, s[0:1] offset:2048
	global_load_dwordx4 v[12:15], v120, s[0:1] offset:3072
	s_add_u32 s101, s101, 1536
	s_cmp_gt_u32 s101, 28671
	s_cbranch_scc1 .Lnf_g2t_exit
; __device__ __forceinline__ unsigned pk2(float lo, float hi) { f32x2_t v = {lo, hi}; bf16x2_t b = __builtin_convertvector(v, bf16x2_t); return __builtin_bit_cast(unsigned, b); }
; __device__ __forceinline__ void phase_norm(const Params& P, int l, int which, bool first) {
;     ...
;     for (int r = gw; r < ROWS; r += NGW) {
;         const int b = r / TT, t = r - b * TT; const int bb = (t < CTX) ? 16 : b;
;         float* xr = xrow_ptr(P, r);
;         const float* src = first ? ((t < CTX) ? P.ctx + ((size_t)b * CTX + t) * DM : P.x + ((size_t)b * SEQ + (t - CTX)) * DM) : xr;
;         f32x4 v[4]; float s2 = 0.f;
; #pragma unroll
;         for (int j = 0; j < 4; ++j) { v[j] = *((const f32x4*)src + lane + 64 * j); s2 += (v[j].x * v[j].x + v[j].y * v[j].y) + (v[j].z * v[j].z + v[j].w * v[j].w); }
;         if (first) {
; #pragma unroll
;             for (int j = 0; j < 4; ++j) *((f32x4*)xr + lane + 64 * j) = v[j];
;         }
;         const float rstd = 1.0f / sqrtf(wave_sum(s2, lane) * (1.0f / DM) + RMS_EPS);
;         const float* mrow = mod + (size_t)bb * MODW;
; #pragma unroll
;         for (int j = 0; j < 4; ++j) {
;             const int c0 = 4 * (lane + 64 * j);
;             const f32x4 g = *(const f32x4*)(gain + c0), sh = *(const f32x4*)(mrow + c0), scl = *(const f32x4*)(mrow + DM + c0);
;             const f32x4 y = v[j] * rstd * g * (scl + 1.0f) + sh;
;             u32x2 w; w.x = pk2(y.x, y.y); w.y = pk2(y.z, y.w);
;             *(u32x2*)(H + (size_t)r * DM + c0) = w;
;         }
	s_waitcnt vmcnt(28)
	s_add_u32 s100, s101, 1536
	s_cmp_le_u32 s100, 28671
	s_cselect_b32 s100, s100, s101
	s_lshr_b32 s42, s100, 8
	s_mov_b32 vcc_lo, s42
	s_cmp_ge_u32 s42, 16
	s_cselect_b32 vcc_hi, 4, 0
	s_add_u32 vcc_lo, vcc_lo, vcc_hi
	s_cmp_ge_u32 s42, 28
	s_cselect_b32 vcc_hi, 4, 0
	s_add_u32 vcc_lo, vcc_lo, vcc_hi
	s_cmp_ge_u32 s42, 44
	s_cselect_b32 vcc_hi, 4, 0
	s_add_u32 vcc_lo, vcc_lo, vcc_hi
	s_cmp_ge_u32 s42, 56
	s_cselect_b32 vcc_hi, 4, 0
	s_add_u32 vcc_lo, vcc_lo, vcc_hi
	s_cmp_ge_u32 s42, 72
	s_cselect_b32 vcc_hi, 4, 0
	s_add_u32 vcc_lo, vcc_lo, vcc_hi
	s_cmp_ge_u32 s42, 84
	s_cselect_b32 vcc_hi, 4, 0
	s_add_u32 vcc_lo, vcc_lo, vcc_hi
	s_cmp_ge_u32 s42, 100
	s_cselect_b32 vcc_hi, 4, 0
	s_add_u32 vcc_lo, vcc_lo, vcc_hi
	s_cmp_ge_u32 s42, 112
	s_cselect_b32 vcc_hi, 4, 0
	s_add_u32 vcc_lo, vcc_lo, vcc_hi
	s_and_b32 s43, s100, 0xff
	s_lshl_b32 vcc_lo, vcc_lo, 8
	s_or_b32 s43, s43, vcc_lo
	s_lshr_b32 s8, s43, 8
	s_mul_i32 s8, s8, 57
	s_lshr_b32 s8, s8, 9
	s_mul_i32 s9, s8, 0x900
	s_sub_u32 s9, s43, s9
	s_cmp_lt_u32 s9, 0x100
	s_cselect_b32 s8, 16, s8
	s_mul_i32 s8, s8, 0x6000
	s_add_u32 s0, s24, s8
	s_addc_u32 s1, s25, 0
	global_load_dwordx4 v[130:133], v120, s[0:1] offset:-4096
	global_load_dwordx4 v[134:137], v120, s[0:1] offset:-3072
	global_load_dwordx4 v[138:141], v120, s[0:1] offset:-2048
	global_load_dwordx4 v[142:145], v120, s[0:1] offset:-1024
	global_load_dwordx4 v[146:149], v120, s[0:1]
	global_load_dwordx4 v[150:153], v120, s[0:1] offset:1024
	global_load_dwordx4 v[154:157], v120, s[0:1] offset:2048
	global_load_dwordx4 v[158:161], v120, s[0:1] offset:3072
	v_mul_f32_e32 v32, v17, v17
	v_mul_f32_e32 v33, v19, v19
	v_fmac_f32_e32 v32, v16, v16
	v_fmac_f32_e32 v33, v18, v18
	v_add_f32_e32 v34, v32, v33
	v_mul_f32_e32 v32, v21, v21
	v_mul_f32_e32 v33, v23, v23
	v_fmac_f32_e32 v32, v20, v20
	v_fmac_f32_e32 v33, v22, v22
	v_add_f32_e32 v32, v32, v33
	v_add_f32_e32 v34, v34, v32
	v_mul_f32_e32 v32, v25, v25
	v_mul_f32_e32 v33, v27, v27
	v_fmac_f32_e32 v32, v24, v24
	v_fmac_f32_e32 v33, v26, v26
	v_add_f32_e32 v32, v32, v33
	v_add_f32_e32 v34, v34, v32
	v_mul_f32_e32 v32, v29, v29
	v_mul_f32_e32 v33, v31, v31
	v_fmac_f32_e32 v32, v28, v28
	v_fmac_f32_e32 v33, v30, v30
	v_add_f32_e32 v32, v32, v33
	v_add_f32_e32 v34, v34, v32
	ds_bpermute_b32 v32, v122, v34
	s_waitcnt lgkmcnt(0)
	v_add_f32_e32 v34, v34, v32
	ds_bpermute_b32 v32, v123, v34
	s_waitcnt lgkmcnt(0)
	v_add_f32_e32 v34, v34, v32
	ds_bpermute_b32 v32, v124, v34
	s_waitcnt lgkmcnt(0)
	v_add_f32_e32 v34, v34, v32
	ds_bpermute_b32 v32, v125, v34
	s_waitcnt lgkmcnt(0)
	v_add_f32_e32 v34, v34, v32
	ds_bpermute_b32 v32, v126, v34
	s_waitcnt lgkmcnt(0)
	v_add_f32_e32 v34, v34, v32
	ds_bpermute_b32 v32, v127, v34
	s_waitcnt lgkmcnt(0)
	v_add_f32_e32 v34, v34, v32
	v_fmamk_f32 v34, v34, 0x3a800000, v201
	v_cmp_gt_f32_e32 vcc, 0xf800000, v34
	v_mul_f32_e32 v32, 0x4f800000, v34
	s_nop 0
	v_cndmask_b32_e32 v34, v34, v32, vcc
	v_sqrt_f32_e32 v32, v34
	s_nop 0
	v_add_u32_e32 v35, -1, v32
	v_fma_f32 v36, -v35, v32, v34
	v_cmp_ge_f32_e64 s[42:43], 0, v36
	v_add_u32_e32 v36, 1, v32
	s_nop 0
	v_cndmask_b32_e64 v35, v32, v35, s[42:43]
	v_fma_f32 v32, -v36, v32, v34
	v_cmp_lt_f32_e64 s[42:43], 0, v32
	s_nop 1
	v_cndmask_b32_e64 v32, v35, v36, s[42:43]
	v_mul_f32_e32 v35, 0x37800000, v32
	v_cndmask_b32_e32 v32, v32, v35, vcc
	v_cmp_class_f32_e32 vcc, v34, v202
	s_nop 1
	v_cndmask_b32_e32 v34, v32, v34, vcc
	v_div_scale_f32 v32, s[42:43], v34, v34, 1.0
	v_rcp_f32_e32 v35, v32
	s_nop 0
	v_fma_f32 v36, -v32, v35, 1.0
	v_fmac_f32_e32 v35, v36, v35
	v_div_scale_f32 v36, vcc, 1.0, v34, 1.0
	v_mul_f32_e32 v37, v36, v35
	v_fma_f32 v178, -v32, v37, v36
	v_fmac_f32_e32 v37, v178, v35
	v_fma_f32 v32, -v32, v37, v36
	v_div_fmas_f32 v32, v32, v35, v37
	v_div_fixup_f32 v179, v32, v34, 1.0
	s_lshr_b32 s42, s101, 8
	s_mov_b32 vcc_lo, s42
	s_cmp_ge_u32 s42, 16
	s_cselect_b32 vcc_hi, 4, 0
	s_add_u32 vcc_lo, vcc_lo, vcc_hi
	s_cmp_ge_u32 s42, 28
	s_cselect_b32 vcc_hi, 4, 0
	s_add_u32 vcc_lo, vcc_lo, vcc_hi
	s_cmp_ge_u32 s42, 44
	s_cselect_b32 vcc_hi, 4, 0
	s_add_u32 vcc_lo, vcc_lo, vcc_hi
	s_cmp_ge_u32 s42, 56
	s_cselect_b32 vcc_hi, 4, 0
	s_add_u32 vcc_lo, vcc_lo, vcc_hi
	s_cmp_ge_u32 s42, 72
	s_cselect_b32 vcc_hi, 4, 0
	s_add_u32 vcc_lo, vcc_lo, vcc_hi
	s_cmp_ge_u32 s42, 84
	s_cselect_b32 vcc_hi, 4, 0
	s_add_u32 vcc_lo, vcc_lo, vcc_hi
	s_cmp_ge_u32 s42, 100
	s_cselect_b32 vcc_hi, 4, 0
	s_add_u32 vcc_lo, vcc_lo, vcc_hi
	s_cmp_ge_u32 s42, 112
	s_cselect_b32 vcc_hi, 4, 0
	s_add_u32 vcc_lo, vcc_lo, vcc_hi
	s_and_b32 s43, s101, 0xff
	s_lshl_b32 vcc_lo, vcc_lo, 8
	s_or_b32 s43, s43, vcc_lo
	s_lshl_b32 s8, s43, 11
	s_add_u32 s0, s46, s8
	s_addc_u32 s1, s47, 0
	s_add_u32 s0, s0, 0x5500000
	s_addc_u32 s1, s1, 0
	s_waitcnt vmcnt(16)
; __device__ __forceinline__ unsigned pk2(float lo, float hi) { f32x2_t v = {lo, hi}; bf16x2_t b = __builtin_convertvector(v, bf16x2_t); return __builtin_bit_cast(unsigned, b); }
; __device__ __forceinline__ void phase_norm(const Params& P, int l, int which, bool first) {
;     ...
;         const float rstd = 1.0f / sqrtf(wave_sum(s2, lane) * (1.0f / DM) + RMS_EPS);
;         const float* mrow = mod + (size_t)bb * MODW;
; #pragma unroll
;         for (int j = 0; j < 4; ++j) {
;             const int c0 = 4 * (lane + 64 * j);
;             const f32x4 g = *(const f32x4*)(gain + c0), sh = *(const f32x4*)(mrow + c0), scl = *(const f32x4*)(mrow + DM + c0);
;             const f32x4 y = v[j] * rstd * g * (scl + 1.0f) + sh;
;             u32x2 w; w.x = pk2(y.x, y.y); w.y = pk2(y.z, y.w);
;             *(u32x2*)(H + (size_t)r * DM + c0) = w;
;         }
	v_mul_f32_e32 v193, v16, v179
	v_add_f32_e32 v192, 1.0, v104
	v_mul_f32_e32 v193, v162, v193
	v_fma_f32 v180, v192, v193, v88
	v_mul_f32_e32 v193, v17, v179
	v_add_f32_e32 v192, 1.0, v105
	v_mul_f32_e32 v193, v163, v193
	v_fma_f32 v181, v192, v193, v89
	v_mul_f32_e32 v193, v18, v179
	v_add_f32_e32 v192, 1.0, v106
	v_mul_f32_e32 v193, v164, v193
	v_fma_f32 v182, v192, v193, v90
	v_mul_f32_e32 v193, v19, v179
	v_add_f32_e32 v192, 1.0, v107
	v_mul_f32_e32 v193, v165, v193
	v_fma_f32 v183, v192, v193, v91
	v_cvt_pk_bf16_f32 v184, v180, v181
	v_cvt_pk_bf16_f32 v185, v182, v183
	global_store_dwordx2 v121, v[184:185], s[0:1]
	v_mul_f32_e32 v193, v20, v179
	v_add_f32_e32 v192, 1.0, v108
	v_mul_f32_e32 v193, v166, v193
	v_fma_f32 v180, v192, v193, v92
	v_mul_f32_e32 v193, v21, v179
	v_add_f32_e32 v192, 1.0, v109
	v_mul_f32_e32 v193, v167, v193
	v_fma_f32 v181, v192, v193, v93
	v_mul_f32_e32 v193, v22, v179
	v_add_f32_e32 v192, 1.0, v110
	v_mul_f32_e32 v193, v168, v193
	v_fma_f32 v182, v192, v193, v94
	v_mul_f32_e32 v193, v23, v179
	v_add_f32_e32 v192, 1.0, v111
	v_mul_f32_e32 v193, v169, v193
	v_fma_f32 v183, v192, v193, v95
	v_cvt_pk_bf16_f32 v186, v180, v181
	v_cvt_pk_bf16_f32 v187, v182, v183
	global_store_dwordx2 v121, v[186:187], s[0:1] offset:512
	v_mul_f32_e32 v193, v24, v179
	v_add_f32_e32 v192, 1.0, v112
	v_mul_f32_e32 v193, v170, v193
	v_fma_f32 v180, v192, v193, v96
	v_mul_f32_e32 v193, v25, v179
	v_add_f32_e32 v192, 1.0, v113
	v_mul_f32_e32 v193, v171, v193
	v_fma_f32 v181, v192, v193, v97
	v_mul_f32_e32 v193, v26, v179
	v_add_f32_e32 v192, 1.0, v114
	v_mul_f32_e32 v193, v172, v193
	v_fma_f32 v182, v192, v193, v98
	v_mul_f32_e32 v193, v27, v179
	v_add_f32_e32 v192, 1.0, v115
	v_mul_f32_e32 v193, v173, v193
	v_fma_f32 v183, v192, v193, v99
	v_cvt_pk_bf16_f32 v188, v180, v181
	v_cvt_pk_bf16_f32 v189, v182, v183
	global_store_dwordx2 v121, v[188:189], s[0:1] offset:1024
	v_mul_f32_e32 v193, v28, v179
	v_add_f32_e32 v192, 1.0, v116
	v_mul_f32_e32 v193, v174, v193
	v_fma_f32 v180, v192, v193, v100
	v_mul_f32_e32 v193, v29, v179
	v_add_f32_e32 v192, 1.0, v117
	v_mul_f32_e32 v193, v175, v193
	v_fma_f32 v181, v192, v193, v101
	v_mul_f32_e32 v193, v30, v179
	v_add_f32_e32 v192, 1.0, v118
	v_mul_f32_e32 v193, v176, v193
	v_fma_f32 v182, v192, v193, v102
	v_mul_f32_e32 v193, v31, v179
	v_add_f32_e32 v192, 1.0, v119
	v_mul_f32_e32 v193, v177, v193
	v_fma_f32 v183, v192, v193, v103
	v_cvt_pk_bf16_f32 v190, v180, v181
	v_cvt_pk_bf16_f32 v191, v182, v183
	global_store_dwordx2 v121, v[190:191], s[0:1] offset:1536
	s_add_u32 s100, s101, 4608
	s_cmp_le_u32 s100, 28671
	s_cselect_b32 s100, s100, s101
	s_lshr_b32 s42, s100, 8
	s_mov_b32 vcc_lo, s42
	s_cmp_ge_u32 s42, 16
	s_cselect_b32 vcc_hi, 4, 0
	s_add_u32 vcc_lo, vcc_lo, vcc_hi
	s_cmp_ge_u32 s42, 28
	s_cselect_b32 vcc_hi, 4, 0
	s_add_u32 vcc_lo, vcc_lo, vcc_hi
	s_cmp_ge_u32 s42, 44
	s_cselect_b32 vcc_hi, 4, 0
	s_add_u32 vcc_lo, vcc_lo, vcc_hi
	s_cmp_ge_u32 s42, 56
	s_cselect_b32 vcc_hi, 4, 0
	s_add_u32 vcc_lo, vcc_lo, vcc_hi
	s_cmp_ge_u32 s42, 72
	s_cselect_b32 vcc_hi, 4, 0
	s_add_u32 vcc_lo, vcc_lo, vcc_hi
	s_cmp_ge_u32 s42, 84
	s_cselect_b32 vcc_hi, 4, 0
	s_add_u32 vcc_lo, vcc_lo, vcc_hi
	s_cmp_ge_u32 s42, 100
	s_cselect_b32 vcc_hi, 4, 0
	s_add_u32 vcc_lo, vcc_lo, vcc_hi
	s_cmp_ge_u32 s42, 112
	s_cselect_b32 vcc_hi, 4, 0
	s_add_u32 vcc_lo, vcc_lo, vcc_hi
	s_and_b32 s43, s100, 0xff
	s_lshl_b32 vcc_lo, vcc_lo, 8
	s_or_b32 s43, s43, vcc_lo
	s_lshr_b32 s8, s43, 8
	s_mul_i32 s8, s8, 57
	s_lshr_b32 s8, s8, 9
	s_mul_i32 s9, s8, 0x900
	s_sub_u32 s9, s43, s9
	s_lshl_b32 s0, s8, 11
	s_add_u32 s0, s0, s9
	s_sub_u32 s0, s0, 0x100
	s_lshl_b32 s8, s8, 8
	s_add_u32 s8, s8, s9
	s_cmp_lt_u32 s9, 0x100
	s_cselect_b32 s8, s8, s0
	s_cselect_b32 s0, s36, s44
	s_cselect_b32 s1, s37, s45
	s_lshl_b32 s8, s8, 12
	s_add_u32 s0, s0, s8
	s_addc_u32 s1, s1, 0
	global_load_dwordx4 v[16:19], v120, s[0:1]
	global_load_dwordx4 v[20:23], v120, s[0:1] offset:1024
	global_load_dwordx4 v[24:27], v120, s[0:1] offset:2048
	global_load_dwordx4 v[28:31], v120, s[0:1] offset:3072
	s_add_u32 s101, s101, 1536
	s_cmp_gt_u32 s101, 28671
	s_cbranch_scc1 .Lnf_g2t_exit
	s_waitcnt vmcnt(32)
	s_add_u32 s100, s101, 1536
	s_cmp_le_u32 s100, 28671
	s_cselect_b32 s100, s100, s101
	s_lshr_b32 s42, s100, 8
	s_mov_b32 vcc_lo, s42
	s_cmp_ge_u32 s42, 16
	s_cselect_b32 vcc_hi, 4, 0
	s_add_u32 vcc_lo, vcc_lo, vcc_hi
	s_cmp_ge_u32 s42, 28
	s_cselect_b32 vcc_hi, 4, 0
	s_add_u32 vcc_lo, vcc_lo, vcc_hi
	s_cmp_ge_u32 s42, 44
	s_cselect_b32 vcc_hi, 4, 0
	s_add_u32 vcc_lo, vcc_lo, vcc_hi
	s_cmp_ge_u32 s42, 56
	s_cselect_b32 vcc_hi, 4, 0
	s_add_u32 vcc_lo, vcc_lo, vcc_hi
	s_cmp_ge_u32 s42, 72
	s_cselect_b32 vcc_hi, 4, 0
	s_add_u32 vcc_lo, vcc_lo, vcc_hi
	s_cmp_ge_u32 s42, 84
	s_cselect_b32 vcc_hi, 4, 0
	s_add_u32 vcc_lo, vcc_lo, vcc_hi
	s_cmp_ge_u32 s42, 100
	s_cselect_b32 vcc_hi, 4, 0
	s_add_u32 vcc_lo, vcc_lo, vcc_hi
	s_cmp_ge_u32 s42, 112
	s_cselect_b32 vcc_hi, 4, 0
	s_add_u32 vcc_lo, vcc_lo, vcc_hi
	s_and_b32 s43, s100, 0xff
	s_lshl_b32 vcc_lo, vcc_lo, 8
	s_or_b32 s43, s43, vcc_lo
	s_lshr_b32 s8, s43, 8
	s_mul_i32 s8, s8, 57
	s_lshr_b32 s8, s8, 9
	s_mul_i32 s9, s8, 0x900
	s_sub_u32 s9, s43, s9
	s_cmp_lt_u32 s9, 0x100
	s_cselect_b32 s8, 16, s8
	s_mul_i32 s8, s8, 0x6000
	s_add_u32 s0, s24, s8
	s_addc_u32 s1, s25, 0
	global_load_dwordx4 v[56:59], v120, s[0:1] offset:-4096
	global_load_dwordx4 v[60:63], v120, s[0:1] offset:-3072
	global_load_dwordx4 v[64:67], v120, s[0:1] offset:-2048
	global_load_dwordx4 v[68:71], v120, s[0:1] offset:-1024
	global_load_dwordx4 v[72:75], v120, s[0:1]
	global_load_dwordx4 v[76:79], v120, s[0:1] offset:1024
	global_load_dwordx4 v[80:83], v120, s[0:1] offset:2048
	global_load_dwordx4 v[84:87], v120, s[0:1] offset:3072
	v_mul_f32_e32 v32, v41, v41
	v_mul_f32_e32 v33, v43, v43
	v_fmac_f32_e32 v32, v40, v40
	v_fmac_f32_e32 v33, v42, v42
	v_add_f32_e32 v34, v32, v33
	v_mul_f32_e32 v32, v45, v45
	v_mul_f32_e32 v33, v47, v47
	v_fmac_f32_e32 v32, v44, v44
	v_fmac_f32_e32 v33, v46, v46
	v_add_f32_e32 v32, v32, v33
	v_add_f32_e32 v34, v34, v32
	v_mul_f32_e32 v32, v49, v49
	v_mul_f32_e32 v33, v51, v51
	v_fmac_f32_e32 v32, v48, v48
	v_fmac_f32_e32 v33, v50, v50
	v_add_f32_e32 v32, v32, v33
	v_add_f32_e32 v34, v34, v32
	v_mul_f32_e32 v32, v53, v53
	v_mul_f32_e32 v33, v55, v55
	v_fmac_f32_e32 v32, v52, v52
	v_fmac_f32_e32 v33, v54, v54
	v_add_f32_e32 v32, v32, v33
	v_add_f32_e32 v34, v34, v32
	ds_bpermute_b32 v32, v122, v34
	s_waitcnt lgkmcnt(0)
; __device__ __forceinline__ unsigned pk2(float lo, float hi) { f32x2_t v = {lo, hi}; bf16x2_t b = __builtin_convertvector(v, bf16x2_t); return __builtin_bit_cast(unsigned, b); }
; __device__ __forceinline__ void phase_norm(const Params& P, int l, int which, bool first) {
;     ...
;         for (int j = 0; j < 4; ++j) { v[j] = *((const f32x4*)src + lane + 64 * j); s2 += (v[j].x * v[j].x + v[j].y * v[j].y) + (v[j].z * v[j].z + v[j].w * v[j].w); }
;         if (first) {
; #pragma unroll
;             for (int j = 0; j < 4; ++j) *((f32x4*)xr + lane + 64 * j) = v[j];
;         }
;         const float rstd = 1.0f / sqrtf(wave_sum(s2, lane) * (1.0f / DM) + RMS_EPS);
;         const float* mrow = mod + (size_t)bb * MODW;
; #pragma unroll
;         for (int j = 0; j < 4; ++j) {
;             const int c0 = 4 * (lane + 64 * j);
;             const f32x4 g = *(const f32x4*)(gain + c0), sh = *(const f32x4*)(mrow + c0), scl = *(const f32x4*)(mrow + DM + c0);
;             const f32x4 y = v[j] * rstd * g * (scl + 1.0f) + sh;
;             u32x2 w; w.x = pk2(y.x, y.y); w.y = pk2(y.z, y.w);
;             *(u32x2*)(H + (size_t)r * DM + c0) = w;
;         }
	v_add_f32_e32 v34, v34, v32
	ds_bpermute_b32 v32, v123, v34
	s_waitcnt lgkmcnt(0)
	v_add_f32_e32 v34, v34, v32
	ds_bpermute_b32 v32, v124, v34
	s_waitcnt lgkmcnt(0)
	v_add_f32_e32 v34, v34, v32
	ds_bpermute_b32 v32, v125, v34
	s_waitcnt lgkmcnt(0)
	v_add_f32_e32 v34, v34, v32
	ds_bpermute_b32 v32, v126, v34
	s_waitcnt lgkmcnt(0)
	v_add_f32_e32 v34, v34, v32
	ds_bpermute_b32 v32, v127, v34
	s_waitcnt lgkmcnt(0)
	v_add_f32_e32 v34, v34, v32
	v_fmamk_f32 v34, v34, 0x3a800000, v201
	v_cmp_gt_f32_e32 vcc, 0xf800000, v34
	v_mul_f32_e32 v32, 0x4f800000, v34
	s_nop 0
	v_cndmask_b32_e32 v34, v34, v32, vcc
	v_sqrt_f32_e32 v32, v34
	s_nop 0
	v_add_u32_e32 v35, -1, v32
	v_fma_f32 v36, -v35, v32, v34
	v_cmp_ge_f32_e64 s[42:43], 0, v36
	v_add_u32_e32 v36, 1, v32
	s_nop 0
	v_cndmask_b32_e64 v35, v32, v35, s[42:43]
	v_fma_f32 v32, -v36, v32, v34
	v_cmp_lt_f32_e64 s[42:43], 0, v32
	s_nop 1
	v_cndmask_b32_e64 v32, v35, v36, s[42:43]
	v_mul_f32_e32 v35, 0x37800000, v32
	v_cndmask_b32_e32 v32, v32, v35, vcc
	v_cmp_class_f32_e32 vcc, v34, v202
	s_nop 1
	v_cndmask_b32_e32 v34, v32, v34, vcc
	v_div_scale_f32 v32, s[42:43], v34, v34, 1.0
	v_rcp_f32_e32 v35, v32
	s_nop 0
	v_fma_f32 v36, -v32, v35, 1.0
	v_fmac_f32_e32 v35, v36, v35
	v_div_scale_f32 v36, vcc, 1.0, v34, 1.0
	v_mul_f32_e32 v37, v36, v35
	v_fma_f32 v178, -v32, v37, v36
	v_fmac_f32_e32 v37, v178, v35
	v_fma_f32 v32, -v32, v37, v36
	v_div_fmas_f32 v32, v32, v35, v37
	v_div_fixup_f32 v179, v32, v34, 1.0
	s_lshr_b32 s42, s101, 8
	s_mov_b32 vcc_lo, s42
	s_cmp_ge_u32 s42, 16
	s_cselect_b32 vcc_hi, 4, 0
	s_add_u32 vcc_lo, vcc_lo, vcc_hi
	s_cmp_ge_u32 s42, 28
	s_cselect_b32 vcc_hi, 4, 0
	s_add_u32 vcc_lo, vcc_lo, vcc_hi
	s_cmp_ge_u32 s42, 44
	s_cselect_b32 vcc_hi, 4, 0
	s_add_u32 vcc_lo, vcc_lo, vcc_hi
	s_cmp_ge_u32 s42, 56
	s_cselect_b32 vcc_hi, 4, 0
	s_add_u32 vcc_lo, vcc_lo, vcc_hi
	s_cmp_ge_u32 s42, 72
	s_cselect_b32 vcc_hi, 4, 0
	s_add_u32 vcc_lo, vcc_lo, vcc_hi
	s_cmp_ge_u32 s42, 84
	s_cselect_b32 vcc_hi, 4, 0
	s_add_u32 vcc_lo, vcc_lo, vcc_hi
	s_cmp_ge_u32 s42, 100
	s_cselect_b32 vcc_hi, 4, 0
	s_add_u32 vcc_lo, vcc_lo, vcc_hi
	s_cmp_ge_u32 s42, 112
	s_cselect_b32 vcc_hi, 4, 0
	s_add_u32 vcc_lo, vcc_lo, vcc_hi
	s_and_b32 s43, s101, 0xff
	s_lshl_b32 vcc_lo, vcc_lo, 8
	s_or_b32 s43, s43, vcc_lo
	s_lshl_b32 s8, s43, 11
	s_add_u32 s0, s46, s8
	s_addc_u32 s1, s47, 0
	s_add_u32 s0, s0, 0x5500000
	s_addc_u32 s1, s1, 0
	s_waitcnt vmcnt(16)
	v_mul_f32_e32 v193, v40, v179
	v_add_f32_e32 v192, 1.0, v146
	v_mul_f32_e32 v193, v162, v193
	v_fma_f32 v180, v192, v193, v130
	v_mul_f32_e32 v193, v41, v179
	v_add_f32_e32 v192, 1.0, v147
	v_mul_f32_e32 v193, v163, v193
	v_fma_f32 v181, v192, v193, v131
	v_mul_f32_e32 v193, v42, v179
	v_add_f32_e32 v192, 1.0, v148
	v_mul_f32_e32 v193, v164, v193
	v_fma_f32 v182, v192, v193, v132
	v_mul_f32_e32 v193, v43, v179
	v_add_f32_e32 v192, 1.0, v149
	v_mul_f32_e32 v193, v165, v193
	v_fma_f32 v183, v192, v193, v133
	v_cvt_pk_bf16_f32 v184, v180, v181
	v_cvt_pk_bf16_f32 v185, v182, v183
	global_store_dwordx2 v121, v[184:185], s[0:1]
	v_mul_f32_e32 v193, v44, v179
	v_add_f32_e32 v192, 1.0, v150
	v_mul_f32_e32 v193, v166, v193
	v_fma_f32 v180, v192, v193, v134
	v_mul_f32_e32 v193, v45, v179
	v_add_f32_e32 v192, 1.0, v151
	v_mul_f32_e32 v193, v167, v193
	v_fma_f32 v181, v192, v193, v135
	v_mul_f32_e32 v193, v46, v179
	v_add_f32_e32 v192, 1.0, v152
	v_mul_f32_e32 v193, v168, v193
	v_fma_f32 v182, v192, v193, v136
	v_mul_f32_e32 v193, v47, v179
	v_add_f32_e32 v192, 1.0, v153
	v_mul_f32_e32 v193, v169, v193
	v_fma_f32 v183, v192, v193, v137
	v_cvt_pk_bf16_f32 v186, v180, v181
	v_cvt_pk_bf16_f32 v187, v182, v183
	global_store_dwordx2 v121, v[186:187], s[0:1] offset:512
	v_mul_f32_e32 v193, v48, v179
	v_add_f32_e32 v192, 1.0, v154
	v_mul_f32_e32 v193, v170, v193
	v_fma_f32 v180, v192, v193, v138
	v_mul_f32_e32 v193, v49, v179
	v_add_f32_e32 v192, 1.0, v155
	v_mul_f32_e32 v193, v171, v193
	v_fma_f32 v181, v192, v193, v139
	v_mul_f32_e32 v193, v50, v179
	v_add_f32_e32 v192, 1.0, v156
	v_mul_f32_e32 v193, v172, v193
	v_fma_f32 v182, v192, v193, v140
	v_mul_f32_e32 v193, v51, v179
	v_add_f32_e32 v192, 1.0, v157
	v_mul_f32_e32 v193, v173, v193
	v_fma_f32 v183, v192, v193, v141
	v_cvt_pk_bf16_f32 v188, v180, v181
	v_cvt_pk_bf16_f32 v189, v182, v183
	global_store_dwordx2 v121, v[188:189], s[0:1] offset:1024
	v_mul_f32_e32 v193, v52, v179
	v_add_f32_e32 v192, 1.0, v158
	v_mul_f32_e32 v193, v174, v193
	v_fma_f32 v180, v192, v193, v142
	v_mul_f32_e32 v193, v53, v179
	v_add_f32_e32 v192, 1.0, v159
	v_mul_f32_e32 v193, v175, v193
	v_fma_f32 v181, v192, v193, v143
	v_mul_f32_e32 v193, v54, v179
	v_add_f32_e32 v192, 1.0, v160
	v_mul_f32_e32 v193, v176, v193
	v_fma_f32 v182, v192, v193, v144
	v_mul_f32_e32 v193, v55, v179
	v_add_f32_e32 v192, 1.0, v161
	v_mul_f32_e32 v193, v177, v193
	v_fma_f32 v183, v192, v193, v145
	v_cvt_pk_bf16_f32 v190, v180, v181
	v_cvt_pk_bf16_f32 v191, v182, v183
	global_store_dwordx2 v121, v[190:191], s[0:1] offset:1536
	s_add_u32 s100, s101, 4608
	s_cmp_le_u32 s100, 28671
	s_cselect_b32 s100, s100, s101
	s_lshr_b32 s42, s100, 8
	s_mov_b32 vcc_lo, s42
	s_cmp_ge_u32 s42, 16
	s_cselect_b32 vcc_hi, 4, 0
	s_add_u32 vcc_lo, vcc_lo, vcc_hi
	s_cmp_ge_u32 s42, 28
	s_cselect_b32 vcc_hi, 4, 0
	s_add_u32 vcc_lo, vcc_lo, vcc_hi
	s_cmp_ge_u32 s42, 44
	s_cselect_b32 vcc_hi, 4, 0
	s_add_u32 vcc_lo, vcc_lo, vcc_hi
	s_cmp_ge_u32 s42, 56
	s_cselect_b32 vcc_hi, 4, 0
	s_add_u32 vcc_lo, vcc_lo, vcc_hi
	s_cmp_ge_u32 s42, 72
	s_cselect_b32 vcc_hi, 4, 0
	s_add_u32 vcc_lo, vcc_lo, vcc_hi
	s_cmp_ge_u32 s42, 84
	s_cselect_b32 vcc_hi, 4, 0
	s_add_u32 vcc_lo, vcc_lo, vcc_hi
	s_cmp_ge_u32 s42, 100
	s_cselect_b32 vcc_hi, 4, 0
	s_add_u32 vcc_lo, vcc_lo, vcc_hi
	s_cmp_ge_u32 s42, 112
	s_cselect_b32 vcc_hi, 4, 0
	s_add_u32 vcc_lo, vcc_lo, vcc_hi
	s_and_b32 s43, s100, 0xff
	s_lshl_b32 vcc_lo, vcc_lo, 8
	s_or_b32 s43, s43, vcc_lo
	s_lshr_b32 s8, s43, 8
	s_mul_i32 s8, s8, 57
	s_lshr_b32 s8, s8, 9
	s_mul_i32 s9, s8, 0x900
	s_sub_u32 s9, s43, s9
	s_lshl_b32 s0, s8, 11
	s_add_u32 s0, s0, s9
	s_sub_u32 s0, s0, 0x100
	s_lshl_b32 s8, s8, 8
	s_add_u32 s8, s8, s9
	s_cmp_lt_u32 s9, 0x100
	s_cselect_b32 s8, s8, s0
	s_cselect_b32 s0, s36, s44
	s_cselect_b32 s1, s37, s45
	s_lshl_b32 s8, s8, 12
	s_add_u32 s0, s0, s8
	s_addc_u32 s1, s1, 0
	global_load_dwordx4 v[40:43], v120, s[0:1]
	global_load_dwordx4 v[44:47], v120, s[0:1] offset:1024
	global_load_dwordx4 v[48:51], v120, s[0:1] offset:2048
	global_load_dwordx4 v[52:55], v120, s[0:1] offset:3072
	s_add_u32 s101, s101, 1536
	s_cmp_gt_u32 s101, 28671
	s_cbranch_scc1 .Lnf_g2t_exit
; __device__ __forceinline__ unsigned pk2(float lo, float hi) { f32x2_t v = {lo, hi}; bf16x2_t b = __builtin_convertvector(v, bf16x2_t); return __builtin_bit_cast(unsigned, b); }
; __device__ __forceinline__ void phase_norm(const Params& P, int l, int which, bool first) {
;     ...
;     for (int r = gw; r < ROWS; r += NGW) {
;         const int b = r / TT, t = r - b * TT; const int bb = (t < CTX) ? 16 : b;
;         float* xr = xrow_ptr(P, r);
;         const float* src = first ? ((t < CTX) ? P.ctx + ((size_t)b * CTX + t) * DM : P.x + ((size_t)b * SEQ + (t - CTX)) * DM) : xr;
;         f32x4 v[4]; float s2 = 0.f;
; #pragma unroll
;         for (int j = 0; j < 4; ++j) { v[j] = *((const f32x4*)src + lane + 64 * j); s2 += (v[j].x * v[j].x + v[j].y * v[j].y) + (v[j].z * v[j].z + v[j].w * v[j].w); }
;         if (first) {
; #pragma unroll
;             for (int j = 0; j < 4; ++j) *((f32x4*)xr + lane + 64 * j) = v[j];
;         }
;         const float rstd = 1.0f / sqrtf(wave_sum(s2, lane) * (1.0f / DM) + RMS_EPS);
;         const float* mrow = mod + (size_t)bb * MODW;
; #pragma unroll
;         for (int j = 0; j < 4; ++j) {
;             const int c0 = 4 * (lane + 64 * j);
;             const f32x4 g = *(const f32x4*)(gain + c0), sh = *(const f32x4*)(mrow + c0), scl = *(const f32x4*)(mrow + DM + c0);
;             const f32x4 y = v[j] * rstd * g * (scl + 1.0f) + sh;
;             u32x2 w; w.x = pk2(y.x, y.y); w.y = pk2(y.z, y.w);
;             *(u32x2*)(H + (size_t)r * DM + c0) = w;
;         }
.Lnf_g2t_loop:
	s_waitcnt vmcnt(32)
	s_add_u32 s100, s101, 1536
	s_cmp_le_u32 s100, 28671
	s_cselect_b32 s100, s100, s101
	s_lshr_b32 s42, s100, 8
	s_mov_b32 vcc_lo, s42
	s_cmp_ge_u32 s42, 16
	s_cselect_b32 vcc_hi, 4, 0
	s_add_u32 vcc_lo, vcc_lo, vcc_hi
	s_cmp_ge_u32 s42, 28
	s_cselect_b32 vcc_hi, 4, 0
	s_add_u32 vcc_lo, vcc_lo, vcc_hi
	s_cmp_ge_u32 s42, 44
	s_cselect_b32 vcc_hi, 4, 0
	s_add_u32 vcc_lo, vcc_lo, vcc_hi
	s_cmp_ge_u32 s42, 56
	s_cselect_b32 vcc_hi, 4, 0
	s_add_u32 vcc_lo, vcc_lo, vcc_hi
	s_cmp_ge_u32 s42, 72
	s_cselect_b32 vcc_hi, 4, 0
	s_add_u32 vcc_lo, vcc_lo, vcc_hi
	s_cmp_ge_u32 s42, 84
	s_cselect_b32 vcc_hi, 4, 0
	s_add_u32 vcc_lo, vcc_lo, vcc_hi
	s_cmp_ge_u32 s42, 100
	s_cselect_b32 vcc_hi, 4, 0
	s_add_u32 vcc_lo, vcc_lo, vcc_hi
	s_cmp_ge_u32 s42, 112
	s_cselect_b32 vcc_hi, 4, 0
	s_add_u32 vcc_lo, vcc_lo, vcc_hi
	s_and_b32 s43, s100, 0xff
	s_lshl_b32 vcc_lo, vcc_lo, 8
	s_or_b32 s43, s43, vcc_lo
	s_lshr_b32 s8, s43, 8
	s_mul_i32 s8, s8, 57
	s_lshr_b32 s8, s8, 9
	s_mul_i32 s9, s8, 0x900
	s_sub_u32 s9, s43, s9
	s_cmp_lt_u32 s9, 0x100
	s_cselect_b32 s8, 16, s8
	s_mul_i32 s8, s8, 0x6000
	s_add_u32 s0, s24, s8
	s_addc_u32 s1, s25, 0
	global_load_dwordx4 v[88:91], v120, s[0:1] offset:-4096
	global_load_dwordx4 v[92:95], v120, s[0:1] offset:-3072
	global_load_dwordx4 v[96:99], v120, s[0:1] offset:-2048
	global_load_dwordx4 v[100:103], v120, s[0:1] offset:-1024
	global_load_dwordx4 v[104:107], v120, s[0:1]
	global_load_dwordx4 v[108:111], v120, s[0:1] offset:1024
	global_load_dwordx4 v[112:115], v120, s[0:1] offset:2048
	global_load_dwordx4 v[116:119], v120, s[0:1] offset:3072
	v_mul_f32_e32 v32, v1, v1
	v_mul_f32_e32 v33, v3, v3
	v_fmac_f32_e32 v32, v0, v0
	v_fmac_f32_e32 v33, v2, v2
	v_add_f32_e32 v34, v32, v33
	v_mul_f32_e32 v32, v5, v5
	v_mul_f32_e32 v33, v7, v7
	v_fmac_f32_e32 v32, v4, v4
	v_fmac_f32_e32 v33, v6, v6
	v_add_f32_e32 v32, v32, v33
	v_add_f32_e32 v34, v34, v32
	v_mul_f32_e32 v32, v9, v9
	v_mul_f32_e32 v33, v11, v11
	v_fmac_f32_e32 v32, v8, v8
	v_fmac_f32_e32 v33, v10, v10
	v_add_f32_e32 v32, v32, v33
	v_add_f32_e32 v34, v34, v32
	v_mul_f32_e32 v32, v13, v13
	v_mul_f32_e32 v33, v15, v15
	v_fmac_f32_e32 v32, v12, v12
	v_fmac_f32_e32 v33, v14, v14
	v_add_f32_e32 v32, v32, v33
	v_add_f32_e32 v34, v34, v32
	ds_bpermute_b32 v32, v122, v34
	s_waitcnt lgkmcnt(0)
	v_add_f32_e32 v34, v34, v32
	ds_bpermute_b32 v32, v123, v34
	s_waitcnt lgkmcnt(0)
	v_add_f32_e32 v34, v34, v32
	ds_bpermute_b32 v32, v124, v34
	s_waitcnt lgkmcnt(0)
	v_add_f32_e32 v34, v34, v32
	ds_bpermute_b32 v32, v125, v34
	s_waitcnt lgkmcnt(0)
	v_add_f32_e32 v34, v34, v32
	ds_bpermute_b32 v32, v126, v34
	s_waitcnt lgkmcnt(0)
	v_add_f32_e32 v34, v34, v32
	ds_bpermute_b32 v32, v127, v34
	s_waitcnt lgkmcnt(0)
	v_add_f32_e32 v34, v34, v32
	v_fmamk_f32 v34, v34, 0x3a800000, v201
	v_cmp_gt_f32_e32 vcc, 0xf800000, v34
	v_mul_f32_e32 v32, 0x4f800000, v34
	s_nop 0
	v_cndmask_b32_e32 v34, v34, v32, vcc
	v_sqrt_f32_e32 v32, v34
	s_nop 0
	v_add_u32_e32 v35, -1, v32
	v_fma_f32 v36, -v35, v32, v34
	v_cmp_ge_f32_e64 s[42:43], 0, v36
	v_add_u32_e32 v36, 1, v32
	s_nop 0
	v_cndmask_b32_e64 v35, v32, v35, s[42:43]
	v_fma_f32 v32, -v36, v32, v34
	v_cmp_lt_f32_e64 s[42:43], 0, v32
	s_nop 1
	v_cndmask_b32_e64 v32, v35, v36, s[42:43]
	v_mul_f32_e32 v35, 0x37800000, v32
	v_cndmask_b32_e32 v32, v32, v35, vcc
	v_cmp_class_f32_e32 vcc, v34, v202
	s_nop 1
	v_cndmask_b32_e32 v34, v32, v34, vcc
	v_div_scale_f32 v32, s[42:43], v34, v34, 1.0
	v_rcp_f32_e32 v35, v32
	s_nop 0
	v_fma_f32 v36, -v32, v35, 1.0
	v_fmac_f32_e32 v35, v36, v35
	v_div_scale_f32 v36, vcc, 1.0, v34, 1.0
	v_mul_f32_e32 v37, v36, v35
	v_fma_f32 v178, -v32, v37, v36
	v_fmac_f32_e32 v37, v178, v35
	v_fma_f32 v32, -v32, v37, v36
	v_div_fmas_f32 v32, v32, v35, v37
	v_div_fixup_f32 v179, v32, v34, 1.0
	s_lshr_b32 s42, s101, 8
	s_mov_b32 vcc_lo, s42
	s_cmp_ge_u32 s42, 16
	s_cselect_b32 vcc_hi, 4, 0
	s_add_u32 vcc_lo, vcc_lo, vcc_hi
	s_cmp_ge_u32 s42, 28
	s_cselect_b32 vcc_hi, 4, 0
	s_add_u32 vcc_lo, vcc_lo, vcc_hi
	s_cmp_ge_u32 s42, 44
	s_cselect_b32 vcc_hi, 4, 0
	s_add_u32 vcc_lo, vcc_lo, vcc_hi
	s_cmp_ge_u32 s42, 56
	s_cselect_b32 vcc_hi, 4, 0
	s_add_u32 vcc_lo, vcc_lo, vcc_hi
	s_cmp_ge_u32 s42, 72
	s_cselect_b32 vcc_hi, 4, 0
	s_add_u32 vcc_lo, vcc_lo, vcc_hi
	s_cmp_ge_u32 s42, 84
	s_cselect_b32 vcc_hi, 4, 0
	s_add_u32 vcc_lo, vcc_lo, vcc_hi
	s_cmp_ge_u32 s42, 100
	s_cselect_b32 vcc_hi, 4, 0
	s_add_u32 vcc_lo, vcc_lo, vcc_hi
	s_cmp_ge_u32 s42, 112
	s_cselect_b32 vcc_hi, 4, 0
	s_add_u32 vcc_lo, vcc_lo, vcc_hi
	s_and_b32 s43, s101, 0xff
	s_lshl_b32 vcc_lo, vcc_lo, 8
	s_or_b32 s43, s43, vcc_lo
	s_lshl_b32 s8, s43, 11
	s_add_u32 s0, s46, s8
	s_addc_u32 s1, s47, 0
	s_add_u32 s0, s0, 0x5500000
	s_addc_u32 s1, s1, 0
	s_waitcnt vmcnt(16)
; __device__ __forceinline__ unsigned pk2(float lo, float hi) { f32x2_t v = {lo, hi}; bf16x2_t b = __builtin_convertvector(v, bf16x2_t); return __builtin_bit_cast(unsigned, b); }
; __device__ __forceinline__ void phase_norm(const Params& P, int l, int which, bool first) {
;     ...
;         const float rstd = 1.0f / sqrtf(wave_sum(s2, lane) * (1.0f / DM) + RMS_EPS);
;         const float* mrow = mod + (size_t)bb * MODW;
; #pragma unroll
;         for (int j = 0; j < 4; ++j) {
;             const int c0 = 4 * (lane + 64 * j);
;             const f32x4 g = *(const f32x4*)(gain + c0), sh = *(const f32x4*)(mrow + c0), scl = *(const f32x4*)(mrow + DM + c0);
;             const f32x4 y = v[j] * rstd * g * (scl + 1.0f) + sh;
;             u32x2 w; w.x = pk2(y.x, y.y); w.y = pk2(y.z, y.w);
;             *(u32x2*)(H + (size_t)r * DM + c0) = w;
;         }
	v_mul_f32_e32 v193, v0, v179
	v_add_f32_e32 v192, 1.0, v72
	v_mul_f32_e32 v193, v162, v193
	v_fma_f32 v180, v192, v193, v56
	v_mul_f32_e32 v193, v1, v179
	v_add_f32_e32 v192, 1.0, v73
	v_mul_f32_e32 v193, v163, v193
	v_fma_f32 v181, v192, v193, v57
	v_mul_f32_e32 v193, v2, v179
	v_add_f32_e32 v192, 1.0, v74
	v_mul_f32_e32 v193, v164, v193
	v_fma_f32 v182, v192, v193, v58
	v_mul_f32_e32 v193, v3, v179
	v_add_f32_e32 v192, 1.0, v75
	v_mul_f32_e32 v193, v165, v193
	v_fma_f32 v183, v192, v193, v59
	v_cvt_pk_bf16_f32 v184, v180, v181
	v_cvt_pk_bf16_f32 v185, v182, v183
	global_store_dwordx2 v121, v[184:185], s[0:1]
	v_mul_f32_e32 v193, v4, v179
	v_add_f32_e32 v192, 1.0, v76
	v_mul_f32_e32 v193, v166, v193
	v_fma_f32 v180, v192, v193, v60
	v_mul_f32_e32 v193, v5, v179
	v_add_f32_e32 v192, 1.0, v77
	v_mul_f32_e32 v193, v167, v193
	v_fma_f32 v181, v192, v193, v61
	v_mul_f32_e32 v193, v6, v179
	v_add_f32_e32 v192, 1.0, v78
	v_mul_f32_e32 v193, v168, v193
	v_fma_f32 v182, v192, v193, v62
	v_mul_f32_e32 v193, v7, v179
	v_add_f32_e32 v192, 1.0, v79
	v_mul_f32_e32 v193, v169, v193
	v_fma_f32 v183, v192, v193, v63
	v_cvt_pk_bf16_f32 v186, v180, v181
	v_cvt_pk_bf16_f32 v187, v182, v183
	global_store_dwordx2 v121, v[186:187], s[0:1] offset:512
	v_mul_f32_e32 v193, v8, v179
	v_add_f32_e32 v192, 1.0, v80
	v_mul_f32_e32 v193, v170, v193
	v_fma_f32 v180, v192, v193, v64
	v_mul_f32_e32 v193, v9, v179
	v_add_f32_e32 v192, 1.0, v81
	v_mul_f32_e32 v193, v171, v193
	v_fma_f32 v181, v192, v193, v65
	v_mul_f32_e32 v193, v10, v179
	v_add_f32_e32 v192, 1.0, v82
	v_mul_f32_e32 v193, v172, v193
	v_fma_f32 v182, v192, v193, v66
	v_mul_f32_e32 v193, v11, v179
	v_add_f32_e32 v192, 1.0, v83
	v_mul_f32_e32 v193, v173, v193
	v_fma_f32 v183, v192, v193, v67
	v_cvt_pk_bf16_f32 v188, v180, v181
	v_cvt_pk_bf16_f32 v189, v182, v183
	global_store_dwordx2 v121, v[188:189], s[0:1] offset:1024
	v_mul_f32_e32 v193, v12, v179
	v_add_f32_e32 v192, 1.0, v84
	v_mul_f32_e32 v193, v174, v193
	v_fma_f32 v180, v192, v193, v68
	v_mul_f32_e32 v193, v13, v179
	v_add_f32_e32 v192, 1.0, v85
	v_mul_f32_e32 v193, v175, v193
	v_fma_f32 v181, v192, v193, v69
	v_mul_f32_e32 v193, v14, v179
	v_add_f32_e32 v192, 1.0, v86
	v_mul_f32_e32 v193, v176, v193
	v_fma_f32 v182, v192, v193, v70
	v_mul_f32_e32 v193, v15, v179
	v_add_f32_e32 v192, 1.0, v87
	v_mul_f32_e32 v193, v177, v193
	v_fma_f32 v183, v192, v193, v71
	v_cvt_pk_bf16_f32 v190, v180, v181
	v_cvt_pk_bf16_f32 v191, v182, v183
	global_store_dwordx2 v121, v[190:191], s[0:1] offset:1536
	s_add_u32 s100, s101, 4608
	s_cmp_le_u32 s100, 28671
	s_cselect_b32 s100, s100, s101
	s_lshr_b32 s42, s100, 8
	s_mov_b32 vcc_lo, s42
	s_cmp_ge_u32 s42, 16
	s_cselect_b32 vcc_hi, 4, 0
	s_add_u32 vcc_lo, vcc_lo, vcc_hi
	s_cmp_ge_u32 s42, 28
	s_cselect_b32 vcc_hi, 4, 0
	s_add_u32 vcc_lo, vcc_lo, vcc_hi
	s_cmp_ge_u32 s42, 44
	s_cselect_b32 vcc_hi, 4, 0
	s_add_u32 vcc_lo, vcc_lo, vcc_hi
	s_cmp_ge_u32 s42, 56
	s_cselect_b32 vcc_hi, 4, 0
	s_add_u32 vcc_lo, vcc_lo, vcc_hi
	s_cmp_ge_u32 s42, 72
	s_cselect_b32 vcc_hi, 4, 0
	s_add_u32 vcc_lo, vcc_lo, vcc_hi
	s_cmp_ge_u32 s42, 84
	s_cselect_b32 vcc_hi, 4, 0
	s_add_u32 vcc_lo, vcc_lo, vcc_hi
	s_cmp_ge_u32 s42, 100
	s_cselect_b32 vcc_hi, 4, 0
	s_add_u32 vcc_lo, vcc_lo, vcc_hi
	s_cmp_ge_u32 s42, 112
	s_cselect_b32 vcc_hi, 4, 0
	s_add_u32 vcc_lo, vcc_lo, vcc_hi
	s_and_b32 s43, s100, 0xff
	s_lshl_b32 vcc_lo, vcc_lo, 8
	s_or_b32 s43, s43, vcc_lo
	s_lshr_b32 s8, s43, 8
	s_mul_i32 s8, s8, 57
	s_lshr_b32 s8, s8, 9
	s_mul_i32 s9, s8, 0x900
	s_sub_u32 s9, s43, s9
	s_lshl_b32 s0, s8, 11
	s_add_u32 s0, s0, s9
	s_sub_u32 s0, s0, 0x100
	s_lshl_b32 s8, s8, 8
	s_add_u32 s8, s8, s9
	s_cmp_lt_u32 s9, 0x100
	s_cselect_b32 s8, s8, s0
	s_cselect_b32 s0, s36, s44
	s_cselect_b32 s1, s37, s45
	s_lshl_b32 s8, s8, 12
	s_add_u32 s0, s0, s8
	s_addc_u32 s1, s1, 0
	global_load_dwordx4 v[0:3], v120, s[0:1]
	global_load_dwordx4 v[4:7], v120, s[0:1] offset:1024
	global_load_dwordx4 v[8:11], v120, s[0:1] offset:2048
	global_load_dwordx4 v[12:15], v120, s[0:1] offset:3072
	s_add_u32 s101, s101, 1536
	s_cmp_gt_u32 s101, 28671
	s_cbranch_scc1 .Lnf_g2t_exit
	s_waitcnt vmcnt(32)
	s_add_u32 s100, s101, 1536
	s_cmp_le_u32 s100, 28671
	s_cselect_b32 s100, s100, s101
	s_lshr_b32 s42, s100, 8
	s_mov_b32 vcc_lo, s42
	s_cmp_ge_u32 s42, 16
	s_cselect_b32 vcc_hi, 4, 0
	s_add_u32 vcc_lo, vcc_lo, vcc_hi
	s_cmp_ge_u32 s42, 28
	s_cselect_b32 vcc_hi, 4, 0
	s_add_u32 vcc_lo, vcc_lo, vcc_hi
	s_cmp_ge_u32 s42, 44
	s_cselect_b32 vcc_hi, 4, 0
	s_add_u32 vcc_lo, vcc_lo, vcc_hi
	s_cmp_ge_u32 s42, 56
	s_cselect_b32 vcc_hi, 4, 0
	s_add_u32 vcc_lo, vcc_lo, vcc_hi
	s_cmp_ge_u32 s42, 72
	s_cselect_b32 vcc_hi, 4, 0
	s_add_u32 vcc_lo, vcc_lo, vcc_hi
	s_cmp_ge_u32 s42, 84
	s_cselect_b32 vcc_hi, 4, 0
	s_add_u32 vcc_lo, vcc_lo, vcc_hi
	s_cmp_ge_u32 s42, 100
	s_cselect_b32 vcc_hi, 4, 0
	s_add_u32 vcc_lo, vcc_lo, vcc_hi
	s_cmp_ge_u32 s42, 112
	s_cselect_b32 vcc_hi, 4, 0
	s_add_u32 vcc_lo, vcc_lo, vcc_hi
	s_and_b32 s43, s100, 0xff
	s_lshl_b32 vcc_lo, vcc_lo, 8
	s_or_b32 s43, s43, vcc_lo
	s_lshr_b32 s8, s43, 8
	s_mul_i32 s8, s8, 57
	s_lshr_b32 s8, s8, 9
	s_mul_i32 s9, s8, 0x900
	s_sub_u32 s9, s43, s9
	s_cmp_lt_u32 s9, 0x100
	s_cselect_b32 s8, 16, s8
	s_mul_i32 s8, s8, 0x6000
	s_add_u32 s0, s24, s8
	s_addc_u32 s1, s25, 0
	global_load_dwordx4 v[130:133], v120, s[0:1] offset:-4096
	global_load_dwordx4 v[134:137], v120, s[0:1] offset:-3072
	global_load_dwordx4 v[138:141], v120, s[0:1] offset:-2048
	global_load_dwordx4 v[142:145], v120, s[0:1] offset:-1024
	global_load_dwordx4 v[146:149], v120, s[0:1]
	global_load_dwordx4 v[150:153], v120, s[0:1] offset:1024
	global_load_dwordx4 v[154:157], v120, s[0:1] offset:2048
	global_load_dwordx4 v[158:161], v120, s[0:1] offset:3072
	v_mul_f32_e32 v32, v17, v17
	v_mul_f32_e32 v33, v19, v19
	v_fmac_f32_e32 v32, v16, v16
	v_fmac_f32_e32 v33, v18, v18
	v_add_f32_e32 v34, v32, v33
	v_mul_f32_e32 v32, v21, v21
	v_mul_f32_e32 v33, v23, v23
	v_fmac_f32_e32 v32, v20, v20
	v_fmac_f32_e32 v33, v22, v22
	v_add_f32_e32 v32, v32, v33
	v_add_f32_e32 v34, v34, v32
	v_mul_f32_e32 v32, v25, v25
	v_mul_f32_e32 v33, v27, v27
	v_fmac_f32_e32 v32, v24, v24
	v_fmac_f32_e32 v33, v26, v26
	v_add_f32_e32 v32, v32, v33
	v_add_f32_e32 v34, v34, v32
	v_mul_f32_e32 v32, v29, v29
	v_mul_f32_e32 v33, v31, v31
	v_fmac_f32_e32 v32, v28, v28
	v_fmac_f32_e32 v33, v30, v30
	v_add_f32_e32 v32, v32, v33
	v_add_f32_e32 v34, v34, v32
	ds_bpermute_b32 v32, v122, v34
	s_waitcnt lgkmcnt(0)
; __device__ __forceinline__ unsigned pk2(float lo, float hi) { f32x2_t v = {lo, hi}; bf16x2_t b = __builtin_convertvector(v, bf16x2_t); return __builtin_bit_cast(unsigned, b); }
; __device__ __forceinline__ void phase_norm(const Params& P, int l, int which, bool first) {
;     ...
;         for (int j = 0; j < 4; ++j) { v[j] = *((const f32x4*)src + lane + 64 * j); s2 += (v[j].x * v[j].x + v[j].y * v[j].y) + (v[j].z * v[j].z + v[j].w * v[j].w); }
;         if (first) {
; #pragma unroll
;             for (int j = 0; j < 4; ++j) *((f32x4*)xr + lane + 64 * j) = v[j];
;         }
;         const float rstd = 1.0f / sqrtf(wave_sum(s2, lane) * (1.0f / DM) + RMS_EPS);
;         const float* mrow = mod + (size_t)bb * MODW;
; #pragma unroll
;         for (int j = 0; j < 4; ++j) {
;             const int c0 = 4 * (lane + 64 * j);
;             const f32x4 g = *(const f32x4*)(gain + c0), sh = *(const f32x4*)(mrow + c0), scl = *(const f32x4*)(mrow + DM + c0);
;             const f32x4 y = v[j] * rstd * g * (scl + 1.0f) + sh;
;             u32x2 w; w.x = pk2(y.x, y.y); w.y = pk2(y.z, y.w);
;             *(u32x2*)(H + (size_t)r * DM + c0) = w;
;         }
	v_add_f32_e32 v34, v34, v32
	ds_bpermute_b32 v32, v123, v34
	s_waitcnt lgkmcnt(0)
	v_add_f32_e32 v34, v34, v32
	ds_bpermute_b32 v32, v124, v34
	s_waitcnt lgkmcnt(0)
	v_add_f32_e32 v34, v34, v32
	ds_bpermute_b32 v32, v125, v34
	s_waitcnt lgkmcnt(0)
	v_add_f32_e32 v34, v34, v32
	ds_bpermute_b32 v32, v126, v34
	s_waitcnt lgkmcnt(0)
	v_add_f32_e32 v34, v34, v32
	ds_bpermute_b32 v32, v127, v34
	s_waitcnt lgkmcnt(0)
	v_add_f32_e32 v34, v34, v32
	v_fmamk_f32 v34, v34, 0x3a800000, v201
	v_cmp_gt_f32_e32 vcc, 0xf800000, v34
	v_mul_f32_e32 v32, 0x4f800000, v34
	s_nop 0
	v_cndmask_b32_e32 v34, v34, v32, vcc
	v_sqrt_f32_e32 v32, v34
	s_nop 0
	v_add_u32_e32 v35, -1, v32
	v_fma_f32 v36, -v35, v32, v34
	v_cmp_ge_f32_e64 s[42:43], 0, v36
	v_add_u32_e32 v36, 1, v32
	s_nop 0
	v_cndmask_b32_e64 v35, v32, v35, s[42:43]
	v_fma_f32 v32, -v36, v32, v34
	v_cmp_lt_f32_e64 s[42:43], 0, v32
	s_nop 1
	v_cndmask_b32_e64 v32, v35, v36, s[42:43]
	v_mul_f32_e32 v35, 0x37800000, v32
	v_cndmask_b32_e32 v32, v32, v35, vcc
	v_cmp_class_f32_e32 vcc, v34, v202
	s_nop 1
	v_cndmask_b32_e32 v34, v32, v34, vcc
	v_div_scale_f32 v32, s[42:43], v34, v34, 1.0
	v_rcp_f32_e32 v35, v32
	s_nop 0
	v_fma_f32 v36, -v32, v35, 1.0
	v_fmac_f32_e32 v35, v36, v35
	v_div_scale_f32 v36, vcc, 1.0, v34, 1.0
	v_mul_f32_e32 v37, v36, v35
	v_fma_f32 v178, -v32, v37, v36
	v_fmac_f32_e32 v37, v178, v35
	v_fma_f32 v32, -v32, v37, v36
	v_div_fmas_f32 v32, v32, v35, v37
	v_div_fixup_f32 v179, v32, v34, 1.0
	s_lshr_b32 s42, s101, 8
	s_mov_b32 vcc_lo, s42
	s_cmp_ge_u32 s42, 16
	s_cselect_b32 vcc_hi, 4, 0
	s_add_u32 vcc_lo, vcc_lo, vcc_hi
	s_cmp_ge_u32 s42, 28
	s_cselect_b32 vcc_hi, 4, 0
	s_add_u32 vcc_lo, vcc_lo, vcc_hi
	s_cmp_ge_u32 s42, 44
	s_cselect_b32 vcc_hi, 4, 0
	s_add_u32 vcc_lo, vcc_lo, vcc_hi
	s_cmp_ge_u32 s42, 56
	s_cselect_b32 vcc_hi, 4, 0
	s_add_u32 vcc_lo, vcc_lo, vcc_hi
	s_cmp_ge_u32 s42, 72
	s_cselect_b32 vcc_hi, 4, 0
	s_add_u32 vcc_lo, vcc_lo, vcc_hi
	s_cmp_ge_u32 s42, 84
	s_cselect_b32 vcc_hi, 4, 0
	s_add_u32 vcc_lo, vcc_lo, vcc_hi
	s_cmp_ge_u32 s42, 100
	s_cselect_b32 vcc_hi, 4, 0
	s_add_u32 vcc_lo, vcc_lo, vcc_hi
	s_cmp_ge_u32 s42, 112
	s_cselect_b32 vcc_hi, 4, 0
	s_add_u32 vcc_lo, vcc_lo, vcc_hi
	s_and_b32 s43, s101, 0xff
	s_lshl_b32 vcc_lo, vcc_lo, 8
	s_or_b32 s43, s43, vcc_lo
	s_lshl_b32 s8, s43, 11
	s_add_u32 s0, s46, s8
	s_addc_u32 s1, s47, 0
	s_add_u32 s0, s0, 0x5500000
	s_addc_u32 s1, s1, 0
	s_waitcnt vmcnt(16)
	v_mul_f32_e32 v193, v16, v179
	v_add_f32_e32 v192, 1.0, v104
	v_mul_f32_e32 v193, v162, v193
	v_fma_f32 v180, v192, v193, v88
	v_mul_f32_e32 v193, v17, v179
	v_add_f32_e32 v192, 1.0, v105
	v_mul_f32_e32 v193, v163, v193
	v_fma_f32 v181, v192, v193, v89
	v_mul_f32_e32 v193, v18, v179
	v_add_f32_e32 v192, 1.0, v106
	v_mul_f32_e32 v193, v164, v193
	v_fma_f32 v182, v192, v193, v90
	v_mul_f32_e32 v193, v19, v179
	v_add_f32_e32 v192, 1.0, v107
	v_mul_f32_e32 v193, v165, v193
	v_fma_f32 v183, v192, v193, v91
	v_cvt_pk_bf16_f32 v184, v180, v181
	v_cvt_pk_bf16_f32 v185, v182, v183
	global_store_dwordx2 v121, v[184:185], s[0:1]
	v_mul_f32_e32 v193, v20, v179
	v_add_f32_e32 v192, 1.0, v108
	v_mul_f32_e32 v193, v166, v193
	v_fma_f32 v180, v192, v193, v92
	v_mul_f32_e32 v193, v21, v179
	v_add_f32_e32 v192, 1.0, v109
	v_mul_f32_e32 v193, v167, v193
	v_fma_f32 v181, v192, v193, v93
	v_mul_f32_e32 v193, v22, v179
	v_add_f32_e32 v192, 1.0, v110
	v_mul_f32_e32 v193, v168, v193
	v_fma_f32 v182, v192, v193, v94
	v_mul_f32_e32 v193, v23, v179
	v_add_f32_e32 v192, 1.0, v111
	v_mul_f32_e32 v193, v169, v193
	v_fma_f32 v183, v192, v193, v95
	v_cvt_pk_bf16_f32 v186, v180, v181
	v_cvt_pk_bf16_f32 v187, v182, v183
	global_store_dwordx2 v121, v[186:187], s[0:1] offset:512
	v_mul_f32_e32 v193, v24, v179
	v_add_f32_e32 v192, 1.0, v112
	v_mul_f32_e32 v193, v170, v193
	v_fma_f32 v180, v192, v193, v96
	v_mul_f32_e32 v193, v25, v179
	v_add_f32_e32 v192, 1.0, v113
	v_mul_f32_e32 v193, v171, v193
	v_fma_f32 v181, v192, v193, v97
	v_mul_f32_e32 v193, v26, v179
	v_add_f32_e32 v192, 1.0, v114
	v_mul_f32_e32 v193, v172, v193
	v_fma_f32 v182, v192, v193, v98
	v_mul_f32_e32 v193, v27, v179
	v_add_f32_e32 v192, 1.0, v115
	v_mul_f32_e32 v193, v173, v193
	v_fma_f32 v183, v192, v193, v99
	v_cvt_pk_bf16_f32 v188, v180, v181
	v_cvt_pk_bf16_f32 v189, v182, v183
	global_store_dwordx2 v121, v[188:189], s[0:1] offset:1024
	v_mul_f32_e32 v193, v28, v179
	v_add_f32_e32 v192, 1.0, v116
	v_mul_f32_e32 v193, v174, v193
	v_fma_f32 v180, v192, v193, v100
	v_mul_f32_e32 v193, v29, v179
	v_add_f32_e32 v192, 1.0, v117
	v_mul_f32_e32 v193, v175, v193
	v_fma_f32 v181, v192, v193, v101
	v_mul_f32_e32 v193, v30, v179
	v_add_f32_e32 v192, 1.0, v118
	v_mul_f32_e32 v193, v176, v193
	v_fma_f32 v182, v192, v193, v102
	v_mul_f32_e32 v193, v31, v179
	v_add_f32_e32 v192, 1.0, v119
	v_mul_f32_e32 v193, v177, v193
	v_fma_f32 v183, v192, v193, v103
	v_cvt_pk_bf16_f32 v190, v180, v181
	v_cvt_pk_bf16_f32 v191, v182, v183
	global_store_dwordx2 v121, v[190:191], s[0:1] offset:1536
	s_add_u32 s100, s101, 4608
	s_cmp_le_u32 s100, 28671
	s_cselect_b32 s100, s100, s101
	s_lshr_b32 s42, s100, 8
	s_mov_b32 vcc_lo, s42
	s_cmp_ge_u32 s42, 16
	s_cselect_b32 vcc_hi, 4, 0
	s_add_u32 vcc_lo, vcc_lo, vcc_hi
	s_cmp_ge_u32 s42, 28
	s_cselect_b32 vcc_hi, 4, 0
	s_add_u32 vcc_lo, vcc_lo, vcc_hi
	s_cmp_ge_u32 s42, 44
	s_cselect_b32 vcc_hi, 4, 0
	s_add_u32 vcc_lo, vcc_lo, vcc_hi
	s_cmp_ge_u32 s42, 56
	s_cselect_b32 vcc_hi, 4, 0
	s_add_u32 vcc_lo, vcc_lo, vcc_hi
	s_cmp_ge_u32 s42, 72
	s_cselect_b32 vcc_hi, 4, 0
	s_add_u32 vcc_lo, vcc_lo, vcc_hi
	s_cmp_ge_u32 s42, 84
	s_cselect_b32 vcc_hi, 4, 0
	s_add_u32 vcc_lo, vcc_lo, vcc_hi
	s_cmp_ge_u32 s42, 100
	s_cselect_b32 vcc_hi, 4, 0
	s_add_u32 vcc_lo, vcc_lo, vcc_hi
	s_cmp_ge_u32 s42, 112
	s_cselect_b32 vcc_hi, 4, 0
	s_add_u32 vcc_lo, vcc_lo, vcc_hi
	s_and_b32 s43, s100, 0xff
	s_lshl_b32 vcc_lo, vcc_lo, 8
	s_or_b32 s43, s43, vcc_lo
	s_lshr_b32 s8, s43, 8
	s_mul_i32 s8, s8, 57
	s_lshr_b32 s8, s8, 9
	s_mul_i32 s9, s8, 0x900
	s_sub_u32 s9, s43, s9
	s_lshl_b32 s0, s8, 11
	s_add_u32 s0, s0, s9
	s_sub_u32 s0, s0, 0x100
	s_lshl_b32 s8, s8, 8
	s_add_u32 s8, s8, s9
	s_cmp_lt_u32 s9, 0x100
	s_cselect_b32 s8, s8, s0
	s_cselect_b32 s0, s36, s44
	s_cselect_b32 s1, s37, s45
	s_lshl_b32 s8, s8, 12
	s_add_u32 s0, s0, s8
	s_addc_u32 s1, s1, 0
	global_load_dwordx4 v[16:19], v120, s[0:1]
	global_load_dwordx4 v[20:23], v120, s[0:1] offset:1024
	global_load_dwordx4 v[24:27], v120, s[0:1] offset:2048
	global_load_dwordx4 v[28:31], v120, s[0:1] offset:3072
	s_add_u32 s101, s101, 1536
	s_cmp_gt_u32 s101, 28671
	s_cbranch_scc1 .Lnf_g2t_exit
; __device__ __forceinline__ unsigned pk2(float lo, float hi) { f32x2_t v = {lo, hi}; bf16x2_t b = __builtin_convertvector(v, bf16x2_t); return __builtin_bit_cast(unsigned, b); }
; __device__ __forceinline__ void phase_norm(const Params& P, int l, int which, bool first) {
;     ...
;     for (int r = gw; r < ROWS; r += NGW) {
;         const int b = r / TT, t = r - b * TT; const int bb = (t < CTX) ? 16 : b;
;         float* xr = xrow_ptr(P, r);
;         const float* src = first ? ((t < CTX) ? P.ctx + ((size_t)b * CTX + t) * DM : P.x + ((size_t)b * SEQ + (t - CTX)) * DM) : xr;
;         f32x4 v[4]; float s2 = 0.f;
; #pragma unroll
;         for (int j = 0; j < 4; ++j) { v[j] = *((const f32x4*)src + lane + 64 * j); s2 += (v[j].x * v[j].x + v[j].y * v[j].y) + (v[j].z * v[j].z + v[j].w * v[j].w); }
;         if (first) {
; #pragma unroll
;             for (int j = 0; j < 4; ++j) *((f32x4*)xr + lane + 64 * j) = v[j];
;         }
;         const float rstd = 1.0f / sqrtf(wave_sum(s2, lane) * (1.0f / DM) + RMS_EPS);
;         const float* mrow = mod + (size_t)bb * MODW;
; #pragma unroll
;         for (int j = 0; j < 4; ++j) {
;             const int c0 = 4 * (lane + 64 * j);
;             const f32x4 g = *(const f32x4*)(gain + c0), sh = *(const f32x4*)(mrow + c0), scl = *(const f32x4*)(mrow + DM + c0);
;             const f32x4 y = v[j] * rstd * g * (scl + 1.0f) + sh;
;             u32x2 w; w.x = pk2(y.x, y.y); w.y = pk2(y.z, y.w);
;             *(u32x2*)(H + (size_t)r * DM + c0) = w;
;         }
	s_waitcnt vmcnt(32)
	s_add_u32 s100, s101, 1536
	s_cmp_le_u32 s100, 28671
	s_cselect_b32 s100, s100, s101
	s_lshr_b32 s42, s100, 8
	s_mov_b32 vcc_lo, s42
	s_cmp_ge_u32 s42, 16
	s_cselect_b32 vcc_hi, 4, 0
	s_add_u32 vcc_lo, vcc_lo, vcc_hi
	s_cmp_ge_u32 s42, 28
	s_cselect_b32 vcc_hi, 4, 0
	s_add_u32 vcc_lo, vcc_lo, vcc_hi
	s_cmp_ge_u32 s42, 44
	s_cselect_b32 vcc_hi, 4, 0
	s_add_u32 vcc_lo, vcc_lo, vcc_hi
	s_cmp_ge_u32 s42, 56
	s_cselect_b32 vcc_hi, 4, 0
	s_add_u32 vcc_lo, vcc_lo, vcc_hi
	s_cmp_ge_u32 s42, 72
	s_cselect_b32 vcc_hi, 4, 0
	s_add_u32 vcc_lo, vcc_lo, vcc_hi
	s_cmp_ge_u32 s42, 84
	s_cselect_b32 vcc_hi, 4, 0
	s_add_u32 vcc_lo, vcc_lo, vcc_hi
	s_cmp_ge_u32 s42, 100
	s_cselect_b32 vcc_hi, 4, 0
	s_add_u32 vcc_lo, vcc_lo, vcc_hi
	s_cmp_ge_u32 s42, 112
	s_cselect_b32 vcc_hi, 4, 0
	s_add_u32 vcc_lo, vcc_lo, vcc_hi
	s_and_b32 s43, s100, 0xff
	s_lshl_b32 vcc_lo, vcc_lo, 8
	s_or_b32 s43, s43, vcc_lo
	s_lshr_b32 s8, s43, 8
	s_mul_i32 s8, s8, 57
	s_lshr_b32 s8, s8, 9
	s_mul_i32 s9, s8, 0x900
	s_sub_u32 s9, s43, s9
	s_cmp_lt_u32 s9, 0x100
	s_cselect_b32 s8, 16, s8
	s_mul_i32 s8, s8, 0x6000
	s_add_u32 s0, s24, s8
	s_addc_u32 s1, s25, 0
	global_load_dwordx4 v[56:59], v120, s[0:1] offset:-4096
	global_load_dwordx4 v[60:63], v120, s[0:1] offset:-3072
	global_load_dwordx4 v[64:67], v120, s[0:1] offset:-2048
	global_load_dwordx4 v[68:71], v120, s[0:1] offset:-1024
	global_load_dwordx4 v[72:75], v120, s[0:1]
	global_load_dwordx4 v[76:79], v120, s[0:1] offset:1024
	global_load_dwordx4 v[80:83], v120, s[0:1] offset:2048
	global_load_dwordx4 v[84:87], v120, s[0:1] offset:3072
	v_mul_f32_e32 v32, v41, v41
	v_mul_f32_e32 v33, v43, v43
	v_fmac_f32_e32 v32, v40, v40
	v_fmac_f32_e32 v33, v42, v42
	v_add_f32_e32 v34, v32, v33
	v_mul_f32_e32 v32, v45, v45
	v_mul_f32_e32 v33, v47, v47
	v_fmac_f32_e32 v32, v44, v44
	v_fmac_f32_e32 v33, v46, v46
	v_add_f32_e32 v32, v32, v33
	v_add_f32_e32 v34, v34, v32
	v_mul_f32_e32 v32, v49, v49
	v_mul_f32_e32 v33, v51, v51
	v_fmac_f32_e32 v32, v48, v48
	v_fmac_f32_e32 v33, v50, v50
	v_add_f32_e32 v32, v32, v33
	v_add_f32_e32 v34, v34, v32
	v_mul_f32_e32 v32, v53, v53
	v_mul_f32_e32 v33, v55, v55
	v_fmac_f32_e32 v32, v52, v52
	v_fmac_f32_e32 v33, v54, v54
	v_add_f32_e32 v32, v32, v33
	v_add_f32_e32 v34, v34, v32
	ds_bpermute_b32 v32, v122, v34
	s_waitcnt lgkmcnt(0)
	v_add_f32_e32 v34, v34, v32
	ds_bpermute_b32 v32, v123, v34
	s_waitcnt lgkmcnt(0)
	v_add_f32_e32 v34, v34, v32
	ds_bpermute_b32 v32, v124, v34
	s_waitcnt lgkmcnt(0)
	v_add_f32_e32 v34, v34, v32
	ds_bpermute_b32 v32, v125, v34
	s_waitcnt lgkmcnt(0)
	v_add_f32_e32 v34, v34, v32
	ds_bpermute_b32 v32, v126, v34
	s_waitcnt lgkmcnt(0)
	v_add_f32_e32 v34, v34, v32
	ds_bpermute_b32 v32, v127, v34
	s_waitcnt lgkmcnt(0)
	v_add_f32_e32 v34, v34, v32
	v_fmamk_f32 v34, v34, 0x3a800000, v201
	v_cmp_gt_f32_e32 vcc, 0xf800000, v34
	v_mul_f32_e32 v32, 0x4f800000, v34
	s_nop 0
	v_cndmask_b32_e32 v34, v34, v32, vcc
	v_sqrt_f32_e32 v32, v34
	s_nop 0
	v_add_u32_e32 v35, -1, v32
	v_fma_f32 v36, -v35, v32, v34
	v_cmp_ge_f32_e64 s[42:43], 0, v36
	v_add_u32_e32 v36, 1, v32
	s_nop 0
	v_cndmask_b32_e64 v35, v32, v35, s[42:43]
	v_fma_f32 v32, -v36, v32, v34
	v_cmp_lt_f32_e64 s[42:43], 0, v32
	s_nop 1
	v_cndmask_b32_e64 v32, v35, v36, s[42:43]
	v_mul_f32_e32 v35, 0x37800000, v32
	v_cndmask_b32_e32 v32, v32, v35, vcc
	v_cmp_class_f32_e32 vcc, v34, v202
	s_nop 1
	v_cndmask_b32_e32 v34, v32, v34, vcc
	v_div_scale_f32 v32, s[42:43], v34, v34, 1.0
	v_rcp_f32_e32 v35, v32
	s_nop 0
	v_fma_f32 v36, -v32, v35, 1.0
	v_fmac_f32_e32 v35, v36, v35
	v_div_scale_f32 v36, vcc, 1.0, v34, 1.0
	v_mul_f32_e32 v37, v36, v35
	v_fma_f32 v178, -v32, v37, v36
	v_fmac_f32_e32 v37, v178, v35
	v_fma_f32 v32, -v32, v37, v36
	v_div_fmas_f32 v32, v32, v35, v37
	v_div_fixup_f32 v179, v32, v34, 1.0
	s_lshr_b32 s42, s101, 8
	s_mov_b32 vcc_lo, s42
	s_cmp_ge_u32 s42, 16
	s_cselect_b32 vcc_hi, 4, 0
	s_add_u32 vcc_lo, vcc_lo, vcc_hi
	s_cmp_ge_u32 s42, 28
	s_cselect_b32 vcc_hi, 4, 0
	s_add_u32 vcc_lo, vcc_lo, vcc_hi
	s_cmp_ge_u32 s42, 44
	s_cselect_b32 vcc_hi, 4, 0
	s_add_u32 vcc_lo, vcc_lo, vcc_hi
	s_cmp_ge_u32 s42, 56
	s_cselect_b32 vcc_hi, 4, 0
	s_add_u32 vcc_lo, vcc_lo, vcc_hi
	s_cmp_ge_u32 s42, 72
	s_cselect_b32 vcc_hi, 4, 0
	s_add_u32 vcc_lo, vcc_lo, vcc_hi
	s_cmp_ge_u32 s42, 84
	s_cselect_b32 vcc_hi, 4, 0
	s_add_u32 vcc_lo, vcc_lo, vcc_hi
	s_cmp_ge_u32 s42, 100
	s_cselect_b32 vcc_hi, 4, 0
	s_add_u32 vcc_lo, vcc_lo, vcc_hi
	s_cmp_ge_u32 s42, 112
	s_cselect_b32 vcc_hi, 4, 0
	s_add_u32 vcc_lo, vcc_lo, vcc_hi
	s_and_b32 s43, s101, 0xff
	s_lshl_b32 vcc_lo, vcc_lo, 8
	s_or_b32 s43, s43, vcc_lo
	s_lshl_b32 s8, s43, 11
	s_add_u32 s0, s46, s8
	s_addc_u32 s1, s47, 0
	s_add_u32 s0, s0, 0x5500000
	s_addc_u32 s1, s1, 0
	s_waitcnt vmcnt(16)
; __device__ __forceinline__ unsigned pk2(float lo, float hi) { f32x2_t v = {lo, hi}; bf16x2_t b = __builtin_convertvector(v, bf16x2_t); return __builtin_bit_cast(unsigned, b); }
; __device__ __forceinline__ void phase_norm(const Params& P, int l, int which, bool first) {
;     ...
;         const float rstd = 1.0f / sqrtf(wave_sum(s2, lane) * (1.0f / DM) + RMS_EPS);
;         const float* mrow = mod + (size_t)bb * MODW;
; #pragma unroll
;         for (int j = 0; j < 4; ++j) {
;             const int c0 = 4 * (lane + 64 * j);
;             const f32x4 g = *(const f32x4*)(gain + c0), sh = *(const f32x4*)(mrow + c0), scl = *(const f32x4*)(mrow + DM + c0);
;             const f32x4 y = v[j] * rstd * g * (scl + 1.0f) + sh;
;             u32x2 w; w.x = pk2(y.x, y.y); w.y = pk2(y.z, y.w);
;             *(u32x2*)(H + (size_t)r * DM + c0) = w;
;         }
	v_mul_f32_e32 v193, v40, v179
	v_add_f32_e32 v192, 1.0, v146
	v_mul_f32_e32 v193, v162, v193
	v_fma_f32 v180, v192, v193, v130
	v_mul_f32_e32 v193, v41, v179
	v_add_f32_e32 v192, 1.0, v147
	v_mul_f32_e32 v193, v163, v193
	v_fma_f32 v181, v192, v193, v131
	v_mul_f32_e32 v193, v42, v179
	v_add_f32_e32 v192, 1.0, v148
	v_mul_f32_e32 v193, v164, v193
	v_fma_f32 v182, v192, v193, v132
	v_mul_f32_e32 v193, v43, v179
	v_add_f32_e32 v192, 1.0, v149
	v_mul_f32_e32 v193, v165, v193
	v_fma_f32 v183, v192, v193, v133
	v_cvt_pk_bf16_f32 v184, v180, v181
	v_cvt_pk_bf16_f32 v185, v182, v183
	global_store_dwordx2 v121, v[184:185], s[0:1]
	v_mul_f32_e32 v193, v44, v179
	v_add_f32_e32 v192, 1.0, v150
	v_mul_f32_e32 v193, v166, v193
	v_fma_f32 v180, v192, v193, v134
	v_mul_f32_e32 v193, v45, v179
	v_add_f32_e32 v192, 1.0, v151
	v_mul_f32_e32 v193, v167, v193
	v_fma_f32 v181, v192, v193, v135
	v_mul_f32_e32 v193, v46, v179
	v_add_f32_e32 v192, 1.0, v152
	v_mul_f32_e32 v193, v168, v193
	v_fma_f32 v182, v192, v193, v136
	v_mul_f32_e32 v193, v47, v179
	v_add_f32_e32 v192, 1.0, v153
	v_mul_f32_e32 v193, v169, v193
	v_fma_f32 v183, v192, v193, v137
	v_cvt_pk_bf16_f32 v186, v180, v181
	v_cvt_pk_bf16_f32 v187, v182, v183
	global_store_dwordx2 v121, v[186:187], s[0:1] offset:512
	v_mul_f32_e32 v193, v48, v179
	v_add_f32_e32 v192, 1.0, v154
	v_mul_f32_e32 v193, v170, v193
	v_fma_f32 v180, v192, v193, v138
	v_mul_f32_e32 v193, v49, v179
	v_add_f32_e32 v192, 1.0, v155
	v_mul_f32_e32 v193, v171, v193
	v_fma_f32 v181, v192, v193, v139
	v_mul_f32_e32 v193, v50, v179
	v_add_f32_e32 v192, 1.0, v156
	v_mul_f32_e32 v193, v172, v193
	v_fma_f32 v182, v192, v193, v140
	v_mul_f32_e32 v193, v51, v179
	v_add_f32_e32 v192, 1.0, v157
	v_mul_f32_e32 v193, v173, v193
	v_fma_f32 v183, v192, v193, v141
	v_cvt_pk_bf16_f32 v188, v180, v181
	v_cvt_pk_bf16_f32 v189, v182, v183
	global_store_dwordx2 v121, v[188:189], s[0:1] offset:1024
	v_mul_f32_e32 v193, v52, v179
	v_add_f32_e32 v192, 1.0, v158
	v_mul_f32_e32 v193, v174, v193
	v_fma_f32 v180, v192, v193, v142
	v_mul_f32_e32 v193, v53, v179
	v_add_f32_e32 v192, 1.0, v159
	v_mul_f32_e32 v193, v175, v193
	v_fma_f32 v181, v192, v193, v143
	v_mul_f32_e32 v193, v54, v179
	v_add_f32_e32 v192, 1.0, v160
	v_mul_f32_e32 v193, v176, v193
	v_fma_f32 v182, v192, v193, v144
	v_mul_f32_e32 v193, v55, v179
	v_add_f32_e32 v192, 1.0, v161
	v_mul_f32_e32 v193, v177, v193
	v_fma_f32 v183, v192, v193, v145
	v_cvt_pk_bf16_f32 v190, v180, v181
	v_cvt_pk_bf16_f32 v191, v182, v183
	global_store_dwordx2 v121, v[190:191], s[0:1] offset:1536
	s_add_u32 s100, s101, 4608
	s_cmp_le_u32 s100, 28671
	s_cselect_b32 s100, s100, s101
	s_lshr_b32 s42, s100, 8
	s_mov_b32 vcc_lo, s42
	s_cmp_ge_u32 s42, 16
	s_cselect_b32 vcc_hi, 4, 0
	s_add_u32 vcc_lo, vcc_lo, vcc_hi
	s_cmp_ge_u32 s42, 28
	s_cselect_b32 vcc_hi, 4, 0
	s_add_u32 vcc_lo, vcc_lo, vcc_hi
	s_cmp_ge_u32 s42, 44
	s_cselect_b32 vcc_hi, 4, 0
	s_add_u32 vcc_lo, vcc_lo, vcc_hi
	s_cmp_ge_u32 s42, 56
	s_cselect_b32 vcc_hi, 4, 0
	s_add_u32 vcc_lo, vcc_lo, vcc_hi
	s_cmp_ge_u32 s42, 72
	s_cselect_b32 vcc_hi, 4, 0
	s_add_u32 vcc_lo, vcc_lo, vcc_hi
	s_cmp_ge_u32 s42, 84
	s_cselect_b32 vcc_hi, 4, 0
	s_add_u32 vcc_lo, vcc_lo, vcc_hi
	s_cmp_ge_u32 s42, 100
	s_cselect_b32 vcc_hi, 4, 0
	s_add_u32 vcc_lo, vcc_lo, vcc_hi
	s_cmp_ge_u32 s42, 112
	s_cselect_b32 vcc_hi, 4, 0
	s_add_u32 vcc_lo, vcc_lo, vcc_hi
	s_and_b32 s43, s100, 0xff
	s_lshl_b32 vcc_lo, vcc_lo, 8
	s_or_b32 s43, s43, vcc_lo
	s_lshr_b32 s8, s43, 8
	s_mul_i32 s8, s8, 57
	s_lshr_b32 s8, s8, 9
	s_mul_i32 s9, s8, 0x900
	s_sub_u32 s9, s43, s9
	s_lshl_b32 s0, s8, 11
	s_add_u32 s0, s0, s9
	s_sub_u32 s0, s0, 0x100
	s_lshl_b32 s8, s8, 8
	s_add_u32 s8, s8, s9
	s_cmp_lt_u32 s9, 0x100
	s_cselect_b32 s8, s8, s0
	s_cselect_b32 s0, s36, s44
	s_cselect_b32 s1, s37, s45
	s_lshl_b32 s8, s8, 12
	s_add_u32 s0, s0, s8
	s_addc_u32 s1, s1, 0
	global_load_dwordx4 v[40:43], v120, s[0:1]
	global_load_dwordx4 v[44:47], v120, s[0:1] offset:1024
	global_load_dwordx4 v[48:51], v120, s[0:1] offset:2048
	global_load_dwordx4 v[52:55], v120, s[0:1] offset:3072
	s_add_u32 s101, s101, 1536
	s_cmp_gt_u32 s101, 28671
	s_cbranch_scc1 .Lnf_g2t_exit
	s_branch .Lnf_g2t_loop

; #define PG8_WAIT_V(n) asm volatile("s_waitcnt vmcnt(" #n ")" ::: "memory")
; #define PG8_BAR __builtin_amdgcn_s_barrier()
; template <class Epi, class Sched, bool ALIGN_EPI = false, bool SP2 = false>
; __device__ __forceinline__ void gemm_phase(PG8_LAS unsigned char* lds, const Gemm g, const Sched& S, const Epi& E) {
;     ...
;     PG8_WAIT_V(0);
;     if constexpr (!ALIGN_EPI) { if (wr == 0) PG8_BAR; }
;     PG8_BAR;
.Lg2t_done:
.LBB0_859:
	s_mov_b64 s[10:11], 0

; __device__ __forceinline__ int opaque_tid() { int t = threadIdx.x; asm volatile("" : "+v"(t)); return t; }
; __device__ __forceinline__ void phase_norm(const Params& P, int l, int which, bool first) {
;     const int tid = opaque_tid(), lane = tid & 63, wave = tid >> 6;
;     const int gw = blockIdx.x * 8 + wave, NGW = gridDim.x * 8;
;     const float* gain = (which == 0 ? P.norm1 : P.norm2) + (size_t)l * DM;
;     const float* mod = (const float*)(P.ws + WS_MOD) + (size_t)l * 17 * MODW + (which == 0 ? 0 : 3 * DM);
;     bf16_t* H = (bf16_t*)(P.ws + WS_H);
;     for (int r = gw; r < ROWS; r += NGW) {
;         const int b = r / TT, t = r - b * TT; const int bb = (t < CTX) ? 16 : b;
;         float* xr = xrow_ptr(P, r);
;         const float* src = first ? ((t < CTX) ? P.ctx + ((size_t)b * CTX + t) * DM : P.x + ((size_t)b * SEQ + (t - CTX)) * DM) : xr;
;         f32x4 v[4]; float s2 = 0.f;
; #pragma unroll
;         for (int j = 0; j < 4; ++j) { v[j] = *((const f32x4*)src + lane + 64 * j); s2 += (v[j].x * v[j].x + v[j].y * v[j].y) + (v[j].z * v[j].z + v[j].w * v[j].w); }
.LBB0_937:
	s_or_b64 exec, exec, s[10:11]
	s_mov_b64 s[24:25], s[18:19]
	s_waitcnt lgkmcnt(0)
	v_mov_b32_e32 v0, v200
	s_barrier
	v_readlane_b32 s0, v253, 62
	v_ashrrev_i32_e32 v1, 6, v0
	s_nop 0
	v_add_u32_e32 v20, s0, v1
	s_mov_b32 s0, 0x9000
	v_cmp_gt_i32_e32 vcc, s0, v20
	s_and_saveexec_b64 s[10:11], vcc
	s_mov_b32 s7, 0xf800000
	s_mov_b64 s[12:13], 0x1000
	s_cbranch_execz .LBB0_940
	v_readlane_b32 s8, v255, 0
	s_nop 3
	s_cmp_eq_u32 s8, 3
	s_cbranch_scc1 .Lnf_n2_full
	s_cmp_lg_u32 s60, 0x100
	s_cbranch_scc1 .Lnf_n2_full
	s_load_dwordx4 s[44:47], s[24:25], 0x98
	s_load_dwordx2 s[0:1], s[24:25], 0x78
	v_readlane_b32 s8, v255, 2
	v_readlane_b32 s9, v254, 63
	v_readlane_b32 s100, v255, 0
	v_readfirstlane_b32 s101, v20
	v_and_b32_e32 v120, 63, v200
	v_lshlrev_b32_e32 v121, 3, v120
	v_lshlrev_b32_e32 v32, 2, v120
	v_xor_b32_e32 v122, 4, v32
	v_xor_b32_e32 v123, 8, v32
	v_xor_b32_e32 v124, 16, v32
	v_xor_b32_e32 v125, 32, v32
	v_xor_b32_e32 v126, 64, v32
	v_xor_b32_e32 v127, 0x80, v32
	v_lshlrev_b32_e32 v120, 4, v120
	s_waitcnt lgkmcnt(0)
	s_add_u32 s8, s46, s8
	s_addc_u32 s9, s47, s9
	s_add_u32 s24, s8, 0x104000
	s_addc_u32 s25, s9, 0
	s_lshl_b32 s100, s100, 12
	s_add_u32 s0, s0, s100
	s_addc_u32 s1, s1, 0
	s_add_u32 s36, s46, 0x4500000
	s_addc_u32 s37, s47, 0
	global_load_dwordx4 v[162:165], v120, s[0:1]
	global_load_dwordx4 v[166:169], v120, s[0:1] offset:1024
	global_load_dwordx4 v[170:173], v120, s[0:1] offset:2048
	global_load_dwordx4 v[174:177], v120, s[0:1] offset:3072
	s_lshr_b32 s42, s101, 8
	s_lshr_b32 vcc_lo, s42, 2
	s_lshr_b32 vcc_hi, vcc_lo, 1
	s_lshl_b32 vcc_hi, vcc_hi, 2
	s_lshl_b32 vcc_lo, vcc_lo, 4
	s_add_u32 vcc_lo, vcc_lo, vcc_hi
	s_and_b32 s42, s42, 3
	s_add_u32 vcc_lo, vcc_lo, s42
	s_add_u32 vcc_lo, vcc_lo, 16
	s_and_b32 s43, s101, 0xff
	s_lshl_b32 vcc_lo, vcc_lo, 8
	s_or_b32 s43, s43, vcc_lo
	s_lshr_b32 s8, s43, 8
	s_mul_i32 s8, s8, 57
	s_lshr_b32 s8, s8, 9
	s_mul_i32 s9, s8, 0x900
	s_sub_u32 s9, s43, s9
	s_lshl_b32 s0, s8, 11
	s_add_u32 s0, s0, s9
	s_sub_u32 s0, s0, 0x100
	s_lshl_b32 s8, s8, 8
	s_add_u32 s8, s8, s9
	s_cmp_lt_u32 s9, 0x100
	s_cselect_b32 s8, s8, s0
	s_cselect_b32 s0, s36, s44
	s_cselect_b32 s1, s37, s45
	s_lshl_b32 s8, s8, 12
	s_add_u32 s0, s0, s8
	s_addc_u32 s1, s1, 0
	global_load_dwordx4 v[0:3], v120, s[0:1]
	global_load_dwordx4 v[4:7], v120, s[0:1] offset:1024
	global_load_dwordx4 v[8:11], v120, s[0:1] offset:2048
	global_load_dwordx4 v[12:15], v120, s[0:1] offset:3072
	s_add_u32 s100, s101, s68
	s_cmp_le_u32 s100, 8191
	s_cselect_b32 s100, s100, s101
	s_lshr_b32 s42, s100, 8
	s_lshr_b32 vcc_lo, s42, 2
	s_lshr_b32 vcc_hi, vcc_lo, 1
	s_lshl_b32 vcc_hi, vcc_hi, 2
	s_lshl_b32 vcc_lo, vcc_lo, 4
	s_add_u32 vcc_lo, vcc_lo, vcc_hi
	s_and_b32 s42, s42, 3
	s_add_u32 vcc_lo, vcc_lo, s42
	s_add_u32 vcc_lo, vcc_lo, 16
	s_and_b32 s43, s100, 0xff
	s_lshl_b32 vcc_lo, vcc_lo, 8
	s_or_b32 s43, s43, vcc_lo
	s_lshr_b32 s8, s43, 8
	s_mul_i32 s8, s8, 57
	s_lshr_b32 s8, s8, 9
	s_mul_i32 s9, s8, 0x900
	s_sub_u32 s9, s43, s9
	s_lshl_b32 s0, s8, 11
	s_add_u32 s0, s0, s9
	s_sub_u32 s0, s0, 0x100
	s_lshl_b32 s8, s8, 8
	s_add_u32 s8, s8, s9
	s_cmp_lt_u32 s9, 0x100
	s_cselect_b32 s8, s8, s0
	s_cselect_b32 s0, s36, s44
	s_cselect_b32 s1, s37, s45
	s_lshl_b32 s8, s8, 12
	s_add_u32 s0, s0, s8
	s_addc_u32 s1, s1, 0
	global_load_dwordx4 v[16:19], v120, s[0:1]
	global_load_dwordx4 v[20:23], v120, s[0:1] offset:1024
	global_load_dwordx4 v[24:27], v120, s[0:1] offset:2048
	global_load_dwordx4 v[28:31], v120, s[0:1] offset:3072
	s_mul_i32 s100, s68, 2
	s_add_u32 s100, s100, s101
	s_cmp_le_u32 s100, 8191
	s_cselect_b32 s100, s100, s101
	s_lshr_b32 s42, s100, 8
	s_lshr_b32 vcc_lo, s42, 2
	s_lshr_b32 vcc_hi, vcc_lo, 1
	s_lshl_b32 vcc_hi, vcc_hi, 2
	s_lshl_b32 vcc_lo, vcc_lo, 4
	s_add_u32 vcc_lo, vcc_lo, vcc_hi
	s_and_b32 s42, s42, 3
	s_add_u32 vcc_lo, vcc_lo, s42
	s_add_u32 vcc_lo, vcc_lo, 16
	s_and_b32 s43, s100, 0xff
	s_lshl_b32 vcc_lo, vcc_lo, 8
	s_or_b32 s43, s43, vcc_lo
	s_lshr_b32 s8, s43, 8
	s_mul_i32 s8, s8, 57
	s_lshr_b32 s8, s8, 9
	s_mul_i32 s9, s8, 0x900
	s_sub_u32 s9, s43, s9
	s_lshl_b32 s0, s8, 11
	s_add_u32 s0, s0, s9
	s_sub_u32 s0, s0, 0x100
	s_lshl_b32 s8, s8, 8
	s_add_u32 s8, s8, s9
	s_cmp_lt_u32 s9, 0x100
	s_cselect_b32 s8, s8, s0
	s_cselect_b32 s0, s36, s44
	s_cselect_b32 s1, s37, s45
	s_lshl_b32 s8, s8, 12
	s_add_u32 s0, s0, s8
	s_addc_u32 s1, s1, 0
	global_load_dwordx4 v[40:43], v120, s[0:1]
	global_load_dwordx4 v[44:47], v120, s[0:1] offset:1024
	global_load_dwordx4 v[48:51], v120, s[0:1] offset:2048
	global_load_dwordx4 v[52:55], v120, s[0:1] offset:3072
	s_lshr_b32 s42, s101, 8
	s_lshr_b32 vcc_lo, s42, 2
	s_lshr_b32 vcc_hi, vcc_lo, 1
	s_lshl_b32 vcc_hi, vcc_hi, 2
	s_lshl_b32 vcc_lo, vcc_lo, 4
	s_add_u32 vcc_lo, vcc_lo, vcc_hi
	s_and_b32 s42, s42, 3
	s_add_u32 vcc_lo, vcc_lo, s42
	s_add_u32 vcc_lo, vcc_lo, 16
	s_and_b32 s43, s101, 0xff
	s_lshl_b32 vcc_lo, vcc_lo, 8
	s_or_b32 s43, s43, vcc_lo
	s_lshr_b32 s8, s43, 8
	s_mul_i32 s8, s8, 57
	s_lshr_b32 s8, s8, 9
	s_mul_i32 s9, s8, 0x900
	s_sub_u32 s9, s43, s9
	s_cmp_lt_u32 s9, 0x100
	s_cselect_b32 s8, 16, s8
	s_mul_i32 s8, s8, 0x6000
	s_add_u32 s0, s24, s8
	s_addc_u32 s1, s25, 0
	global_load_dwordx4 v[56:59], v120, s[0:1] offset:-4096
	global_load_dwordx4 v[60:63], v120, s[0:1] offset:-3072
	global_load_dwordx4 v[64:67], v120, s[0:1] offset:-2048
	global_load_dwordx4 v[68:71], v120, s[0:1] offset:-1024
	global_load_dwordx4 v[72:75], v120, s[0:1]
	global_load_dwordx4 v[76:79], v120, s[0:1] offset:1024
	global_load_dwordx4 v[80:83], v120, s[0:1] offset:2048
	global_load_dwordx4 v[84:87], v120, s[0:1] offset:3072
	s_waitcnt vmcnt(16)
; __device__ __forceinline__ unsigned pk2(float lo, float hi) { f32x2_t v = {lo, hi}; bf16x2_t b = __builtin_convertvector(v, bf16x2_t); return __builtin_bit_cast(unsigned, b); }
; __device__ __forceinline__ void phase_norm(const Params& P, int l, int which, bool first) {
;     ...
;     for (int r = gw; r < ROWS; r += NGW) {
;         const int b = r / TT, t = r - b * TT; const int bb = (t < CTX) ? 16 : b;
;         float* xr = xrow_ptr(P, r);
;         const float* src = first ? ((t < CTX) ? P.ctx + ((size_t)b * CTX + t) * DM : P.x + ((size_t)b * SEQ + (t - CTX)) * DM) : xr;
;         f32x4 v[4]; float s2 = 0.f;
; #pragma unroll
;         for (int j = 0; j < 4; ++j) { v[j] = *((const f32x4*)src + lane + 64 * j); s2 += (v[j].x * v[j].x + v[j].y * v[j].y) + (v[j].z * v[j].z + v[j].w * v[j].w); }
;         if (first) {
; #pragma unroll
;             for (int j = 0; j < 4; ++j) *((f32x4*)xr + lane + 64 * j) = v[j];
;         }
;         const float rstd = 1.0f / sqrtf(wave_sum(s2, lane) * (1.0f / DM) + RMS_EPS);
;         const float* mrow = mod + (size_t)bb * MODW;
; #pragma unroll
;         for (int j = 0; j < 4; ++j) {
;             const int c0 = 4 * (lane + 64 * j);
;             const f32x4 g = *(const f32x4*)(gain + c0), sh = *(const f32x4*)(mrow + c0), scl = *(const f32x4*)(mrow + DM + c0);
;             const f32x4 y = v[j] * rstd * g * (scl + 1.0f) + sh;
;             u32x2 w; w.x = pk2(y.x, y.y); w.y = pk2(y.z, y.w);
;             *(u32x2*)(H + (size_t)r * DM + c0) = w;
;         }
	s_add_u32 s100, s101, s68
	s_cmp_le_u32 s100, 8191
	s_cselect_b32 s100, s100, s101
	s_lshr_b32 s42, s100, 8
	s_lshr_b32 vcc_lo, s42, 2
	s_lshr_b32 vcc_hi, vcc_lo, 1
	s_lshl_b32 vcc_hi, vcc_hi, 2
	s_lshl_b32 vcc_lo, vcc_lo, 4
	s_add_u32 vcc_lo, vcc_lo, vcc_hi
	s_and_b32 s42, s42, 3
	s_add_u32 vcc_lo, vcc_lo, s42
	s_add_u32 vcc_lo, vcc_lo, 16
	s_and_b32 s43, s100, 0xff
	s_lshl_b32 vcc_lo, vcc_lo, 8
	s_or_b32 s43, s43, vcc_lo
	s_lshr_b32 s8, s43, 8
	s_mul_i32 s8, s8, 57
	s_lshr_b32 s8, s8, 9
	s_mul_i32 s9, s8, 0x900
	s_sub_u32 s9, s43, s9
	s_cmp_lt_u32 s9, 0x100
	s_cselect_b32 s8, 16, s8
	s_mul_i32 s8, s8, 0x6000
	s_add_u32 s0, s24, s8
	s_addc_u32 s1, s25, 0
	global_load_dwordx4 v[88:91], v120, s[0:1] offset:-4096
	global_load_dwordx4 v[92:95], v120, s[0:1] offset:-3072
	global_load_dwordx4 v[96:99], v120, s[0:1] offset:-2048
	global_load_dwordx4 v[100:103], v120, s[0:1] offset:-1024
	global_load_dwordx4 v[104:107], v120, s[0:1]
	global_load_dwordx4 v[108:111], v120, s[0:1] offset:1024
	global_load_dwordx4 v[112:115], v120, s[0:1] offset:2048
	global_load_dwordx4 v[116:119], v120, s[0:1] offset:3072
	v_mul_f32_e32 v32, v1, v1
	v_mul_f32_e32 v33, v3, v3
	v_fmac_f32_e32 v32, v0, v0
	v_fmac_f32_e32 v33, v2, v2
	v_add_f32_e32 v34, v32, v33
	v_mul_f32_e32 v32, v5, v5
	v_mul_f32_e32 v33, v7, v7
	v_fmac_f32_e32 v32, v4, v4
	v_fmac_f32_e32 v33, v6, v6
	v_add_f32_e32 v32, v32, v33
	v_add_f32_e32 v34, v34, v32
	v_mul_f32_e32 v32, v9, v9
	v_mul_f32_e32 v33, v11, v11
	v_fmac_f32_e32 v32, v8, v8
	v_fmac_f32_e32 v33, v10, v10
	v_add_f32_e32 v32, v32, v33
	v_add_f32_e32 v34, v34, v32
	v_mul_f32_e32 v32, v13, v13
	v_mul_f32_e32 v33, v15, v15
	v_fmac_f32_e32 v32, v12, v12
	v_fmac_f32_e32 v33, v14, v14
	v_add_f32_e32 v32, v32, v33
	v_add_f32_e32 v34, v34, v32
	ds_bpermute_b32 v32, v122, v34
	s_waitcnt lgkmcnt(0)
	v_add_f32_e32 v34, v34, v32
	ds_bpermute_b32 v32, v123, v34
	s_waitcnt lgkmcnt(0)
	v_add_f32_e32 v34, v34, v32
	ds_bpermute_b32 v32, v124, v34
	s_waitcnt lgkmcnt(0)
	v_add_f32_e32 v34, v34, v32
	ds_bpermute_b32 v32, v125, v34
	s_waitcnt lgkmcnt(0)
	v_add_f32_e32 v34, v34, v32
	ds_bpermute_b32 v32, v126, v34
	s_waitcnt lgkmcnt(0)
	v_add_f32_e32 v34, v34, v32
	ds_bpermute_b32 v32, v127, v34
	s_waitcnt lgkmcnt(0)
	v_add_f32_e32 v34, v34, v32
	v_fmamk_f32 v34, v34, 0x3a800000, v201
	v_cmp_gt_f32_e32 vcc, 0xf800000, v34
	v_mul_f32_e32 v32, 0x4f800000, v34
	s_nop 0
	v_cndmask_b32_e32 v34, v34, v32, vcc
	v_sqrt_f32_e32 v32, v34
	s_nop 0
	v_add_u32_e32 v35, -1, v32
	v_fma_f32 v36, -v35, v32, v34
	v_cmp_ge_f32_e64 s[42:43], 0, v36
	v_add_u32_e32 v36, 1, v32
	s_nop 0
	v_cndmask_b32_e64 v35, v32, v35, s[42:43]
	v_fma_f32 v32, -v36, v32, v34
	v_cmp_lt_f32_e64 s[42:43], 0, v32
	s_nop 1
	v_cndmask_b32_e64 v32, v35, v36, s[42:43]
	v_mul_f32_e32 v35, 0x37800000, v32
	v_cndmask_b32_e32 v32, v32, v35, vcc
	v_cmp_class_f32_e32 vcc, v34, v202
	s_nop 1
	v_cndmask_b32_e32 v34, v32, v34, vcc
	v_div_scale_f32 v32, s[42:43], v34, v34, 1.0
	v_rcp_f32_e32 v35, v32
	s_nop 0
	v_fma_f32 v36, -v32, v35, 1.0
	v_fmac_f32_e32 v35, v36, v35
	v_div_scale_f32 v36, vcc, 1.0, v34, 1.0
	v_mul_f32_e32 v37, v36, v35
	v_fma_f32 v178, -v32, v37, v36
	v_fmac_f32_e32 v37, v178, v35
	v_fma_f32 v32, -v32, v37, v36
	v_div_fmas_f32 v32, v32, v35, v37
	v_div_fixup_f32 v179, v32, v34, 1.0
	s_lshr_b32 s42, s101, 8
	s_lshr_b32 vcc_lo, s42, 2
	s_lshr_b32 vcc_hi, vcc_lo, 1
	s_lshl_b32 vcc_hi, vcc_hi, 2
	s_lshl_b32 vcc_lo, vcc_lo, 4
	s_add_u32 vcc_lo, vcc_lo, vcc_hi
	s_and_b32 s42, s42, 3
	s_add_u32 vcc_lo, vcc_lo, s42
	s_add_u32 vcc_lo, vcc_lo, 16
	s_and_b32 s43, s101, 0xff
	s_lshl_b32 vcc_lo, vcc_lo, 8
	s_or_b32 s43, s43, vcc_lo
	s_lshl_b32 s8, s43, 11
	s_add_u32 s0, s46, s8
	s_addc_u32 s1, s47, 0
	s_add_u32 s0, s0, 0x5500000
	s_addc_u32 s1, s1, 0
	s_waitcnt vmcnt(8)
	v_mul_f32_e32 v193, v0, v179
	v_add_f32_e32 v192, 1.0, v72
	v_mul_f32_e32 v193, v162, v193
	v_fma_f32 v180, v192, v193, v56
	v_mul_f32_e32 v193, v1, v179
	v_add_f32_e32 v192, 1.0, v73
	v_mul_f32_e32 v193, v163, v193
	v_fma_f32 v181, v192, v193, v57
	v_mul_f32_e32 v193, v2, v179
	v_add_f32_e32 v192, 1.0, v74
	v_mul_f32_e32 v193, v164, v193
	v_fma_f32 v182, v192, v193, v58
	v_mul_f32_e32 v193, v3, v179
	v_add_f32_e32 v192, 1.0, v75
	v_mul_f32_e32 v193, v165, v193
	v_fma_f32 v183, v192, v193, v59
	v_cvt_pk_bf16_f32 v184, v180, v181
	v_cvt_pk_bf16_f32 v185, v182, v183
	global_store_dwordx2 v121, v[184:185], s[0:1]
	v_mul_f32_e32 v193, v4, v179
	v_add_f32_e32 v192, 1.0, v76
	v_mul_f32_e32 v193, v166, v193
	v_fma_f32 v180, v192, v193, v60
	v_mul_f32_e32 v193, v5, v179
	v_add_f32_e32 v192, 1.0, v77
	v_mul_f32_e32 v193, v167, v193
	v_fma_f32 v181, v192, v193, v61
	v_mul_f32_e32 v193, v6, v179
	v_add_f32_e32 v192, 1.0, v78
	v_mul_f32_e32 v193, v168, v193
	v_fma_f32 v182, v192, v193, v62
	v_mul_f32_e32 v193, v7, v179
	v_add_f32_e32 v192, 1.0, v79
	v_mul_f32_e32 v193, v169, v193
	v_fma_f32 v183, v192, v193, v63
	v_cvt_pk_bf16_f32 v186, v180, v181
	v_cvt_pk_bf16_f32 v187, v182, v183
	global_store_dwordx2 v121, v[186:187], s[0:1] offset:512
	v_mul_f32_e32 v193, v8, v179
	v_add_f32_e32 v192, 1.0, v80
	v_mul_f32_e32 v193, v170, v193
	v_fma_f32 v180, v192, v193, v64
	v_mul_f32_e32 v193, v9, v179
	v_add_f32_e32 v192, 1.0, v81
	v_mul_f32_e32 v193, v171, v193
	v_fma_f32 v181, v192, v193, v65
	v_mul_f32_e32 v193, v10, v179
	v_add_f32_e32 v192, 1.0, v82
	v_mul_f32_e32 v193, v172, v193
	v_fma_f32 v182, v192, v193, v66
	v_mul_f32_e32 v193, v11, v179
	v_add_f32_e32 v192, 1.0, v83
	v_mul_f32_e32 v193, v173, v193
	v_fma_f32 v183, v192, v193, v67
	v_cvt_pk_bf16_f32 v188, v180, v181
	v_cvt_pk_bf16_f32 v189, v182, v183
	global_store_dwordx2 v121, v[188:189], s[0:1] offset:1024
; __device__ __forceinline__ unsigned pk2(float lo, float hi) { f32x2_t v = {lo, hi}; bf16x2_t b = __builtin_convertvector(v, bf16x2_t); return __builtin_bit_cast(unsigned, b); }
; __device__ __forceinline__ void phase_norm(const Params& P, int l, int which, bool first) {
;     ...
;         const float rstd = 1.0f / sqrtf(wave_sum(s2, lane) * (1.0f / DM) + RMS_EPS);
;         const float* mrow = mod + (size_t)bb * MODW;
; #pragma unroll
;         for (int j = 0; j < 4; ++j) {
;             const int c0 = 4 * (lane + 64 * j);
;             const f32x4 g = *(const f32x4*)(gain + c0), sh = *(const f32x4*)(mrow + c0), scl = *(const f32x4*)(mrow + DM + c0);
;             const f32x4 y = v[j] * rstd * g * (scl + 1.0f) + sh;
;             u32x2 w; w.x = pk2(y.x, y.y); w.y = pk2(y.z, y.w);
;             *(u32x2*)(H + (size_t)r * DM + c0) = w;
;         }
	v_mul_f32_e32 v193, v12, v179
	v_add_f32_e32 v192, 1.0, v84
	v_mul_f32_e32 v193, v174, v193
	v_fma_f32 v180, v192, v193, v68
	v_mul_f32_e32 v193, v13, v179
	v_add_f32_e32 v192, 1.0, v85
	v_mul_f32_e32 v193, v175, v193
	v_fma_f32 v181, v192, v193, v69
	v_mul_f32_e32 v193, v14, v179
	v_add_f32_e32 v192, 1.0, v86
	v_mul_f32_e32 v193, v176, v193
	v_fma_f32 v182, v192, v193, v70
	v_mul_f32_e32 v193, v15, v179
	v_add_f32_e32 v192, 1.0, v87
	v_mul_f32_e32 v193, v177, v193
	v_fma_f32 v183, v192, v193, v71
	v_cvt_pk_bf16_f32 v190, v180, v181
	v_cvt_pk_bf16_f32 v191, v182, v183
	global_store_dwordx2 v121, v[190:191], s[0:1] offset:1536
	s_mul_i32 s100, s68, 3
	s_add_u32 s100, s100, s101
	s_cmp_le_u32 s100, 8191
	s_cselect_b32 s100, s100, s101
	s_lshr_b32 s42, s100, 8
	s_lshr_b32 vcc_lo, s42, 2
	s_lshr_b32 vcc_hi, vcc_lo, 1
	s_lshl_b32 vcc_hi, vcc_hi, 2
	s_lshl_b32 vcc_lo, vcc_lo, 4
	s_add_u32 vcc_lo, vcc_lo, vcc_hi
	s_and_b32 s42, s42, 3
	s_add_u32 vcc_lo, vcc_lo, s42
	s_add_u32 vcc_lo, vcc_lo, 16
	s_and_b32 s43, s100, 0xff
	s_lshl_b32 vcc_lo, vcc_lo, 8
	s_or_b32 s43, s43, vcc_lo
	s_lshr_b32 s8, s43, 8
	s_mul_i32 s8, s8, 57
	s_lshr_b32 s8, s8, 9
	s_mul_i32 s9, s8, 0x900
	s_sub_u32 s9, s43, s9
	s_lshl_b32 s0, s8, 11
	s_add_u32 s0, s0, s9
	s_sub_u32 s0, s0, 0x100
	s_lshl_b32 s8, s8, 8
	s_add_u32 s8, s8, s9
	s_cmp_lt_u32 s9, 0x100
	s_cselect_b32 s8, s8, s0
	s_cselect_b32 s0, s36, s44
	s_cselect_b32 s1, s37, s45
	s_lshl_b32 s8, s8, 12
	s_add_u32 s0, s0, s8
	s_addc_u32 s1, s1, 0
	global_load_dwordx4 v[0:3], v120, s[0:1]
	global_load_dwordx4 v[4:7], v120, s[0:1] offset:1024
	global_load_dwordx4 v[8:11], v120, s[0:1] offset:2048
	global_load_dwordx4 v[12:15], v120, s[0:1] offset:3072
	s_add_u32 s101, s101, s68
	s_cmp_gt_u32 s101, 8191
	s_cbranch_scc1 .Lnf_n2i_exit
	s_waitcnt vmcnt(28)
	s_add_u32 s100, s101, s68
	s_cmp_le_u32 s100, 8191
	s_cselect_b32 s100, s100, s101
	s_lshr_b32 s42, s100, 8
	s_lshr_b32 vcc_lo, s42, 2
	s_lshr_b32 vcc_hi, vcc_lo, 1
	s_lshl_b32 vcc_hi, vcc_hi, 2
	s_lshl_b32 vcc_lo, vcc_lo, 4
	s_add_u32 vcc_lo, vcc_lo, vcc_hi
	s_and_b32 s42, s42, 3
	s_add_u32 vcc_lo, vcc_lo, s42
	s_add_u32 vcc_lo, vcc_lo, 16
	s_and_b32 s43, s100, 0xff
	s_lshl_b32 vcc_lo, vcc_lo, 8
	s_or_b32 s43, s43, vcc_lo
	s_lshr_b32 s8, s43, 8
	s_mul_i32 s8, s8, 57
	s_lshr_b32 s8, s8, 9
	s_mul_i32 s9, s8, 0x900
	s_sub_u32 s9, s43, s9
	s_cmp_lt_u32 s9, 0x100
	s_cselect_b32 s8, 16, s8
	s_mul_i32 s8, s8, 0x6000
	s_add_u32 s0, s24, s8
	s_addc_u32 s1, s25, 0
	global_load_dwordx4 v[130:133], v120, s[0:1] offset:-4096
	global_load_dwordx4 v[134:137], v120, s[0:1] offset:-3072
	global_load_dwordx4 v[138:141], v120, s[0:1] offset:-2048
	global_load_dwordx4 v[142:145], v120, s[0:1] offset:-1024
	global_load_dwordx4 v[146:149], v120, s[0:1]
	global_load_dwordx4 v[150:153], v120, s[0:1] offset:1024
	global_load_dwordx4 v[154:157], v120, s[0:1] offset:2048
	global_load_dwordx4 v[158:161], v120, s[0:1] offset:3072
	v_mul_f32_e32 v32, v17, v17
	v_mul_f32_e32 v33, v19, v19
	v_fmac_f32_e32 v32, v16, v16
	v_fmac_f32_e32 v33, v18, v18
	v_add_f32_e32 v34, v32, v33
	v_mul_f32_e32 v32, v21, v21
	v_mul_f32_e32 v33, v23, v23
	v_fmac_f32_e32 v32, v20, v20
	v_fmac_f32_e32 v33, v22, v22
	v_add_f32_e32 v32, v32, v33
	v_add_f32_e32 v34, v34, v32
	v_mul_f32_e32 v32, v25, v25
	v_mul_f32_e32 v33, v27, v27
	v_fmac_f32_e32 v32, v24, v24
	v_fmac_f32_e32 v33, v26, v26
	v_add_f32_e32 v32, v32, v33
	v_add_f32_e32 v34, v34, v32
	v_mul_f32_e32 v32, v29, v29
	v_mul_f32_e32 v33, v31, v31
	v_fmac_f32_e32 v32, v28, v28
	v_fmac_f32_e32 v33, v30, v30
	v_add_f32_e32 v32, v32, v33
	v_add_f32_e32 v34, v34, v32
	ds_bpermute_b32 v32, v122, v34
	s_waitcnt lgkmcnt(0)
	v_add_f32_e32 v34, v34, v32
	ds_bpermute_b32 v32, v123, v34
	s_waitcnt lgkmcnt(0)
	v_add_f32_e32 v34, v34, v32
	ds_bpermute_b32 v32, v124, v34
	s_waitcnt lgkmcnt(0)
	v_add_f32_e32 v34, v34, v32
	ds_bpermute_b32 v32, v125, v34
	s_waitcnt lgkmcnt(0)
	v_add_f32_e32 v34, v34, v32
	ds_bpermute_b32 v32, v126, v34
	s_waitcnt lgkmcnt(0)
	v_add_f32_e32 v34, v34, v32
	ds_bpermute_b32 v32, v127, v34
	s_waitcnt lgkmcnt(0)
	v_add_f32_e32 v34, v34, v32
	v_fmamk_f32 v34, v34, 0x3a800000, v201
	v_cmp_gt_f32_e32 vcc, 0xf800000, v34
	v_mul_f32_e32 v32, 0x4f800000, v34
	s_nop 0
	v_cndmask_b32_e32 v34, v34, v32, vcc
	v_sqrt_f32_e32 v32, v34
	s_nop 0
	v_add_u32_e32 v35, -1, v32
	v_fma_f32 v36, -v35, v32, v34
	v_cmp_ge_f32_e64 s[42:43], 0, v36
	v_add_u32_e32 v36, 1, v32
	s_nop 0
	v_cndmask_b32_e64 v35, v32, v35, s[42:43]
	v_fma_f32 v32, -v36, v32, v34
	v_cmp_lt_f32_e64 s[42:43], 0, v32
	s_nop 1
	v_cndmask_b32_e64 v32, v35, v36, s[42:43]
	v_mul_f32_e32 v35, 0x37800000, v32
	v_cndmask_b32_e32 v32, v32, v35, vcc
	v_cmp_class_f32_e32 vcc, v34, v202
	s_nop 1
	v_cndmask_b32_e32 v34, v32, v34, vcc
	v_div_scale_f32 v32, s[42:43], v34, v34, 1.0
	v_rcp_f32_e32 v35, v32
	s_nop 0
	v_fma_f32 v36, -v32, v35, 1.0
	v_fmac_f32_e32 v35, v36, v35
	v_div_scale_f32 v36, vcc, 1.0, v34, 1.0
	v_mul_f32_e32 v37, v36, v35
	v_fma_f32 v178, -v32, v37, v36
	v_fmac_f32_e32 v37, v178, v35
	v_fma_f32 v32, -v32, v37, v36
	v_div_fmas_f32 v32, v32, v35, v37
	v_div_fixup_f32 v179, v32, v34, 1.0
	s_lshr_b32 s42, s101, 8
	s_lshr_b32 vcc_lo, s42, 2
	s_lshr_b32 vcc_hi, vcc_lo, 1
	s_lshl_b32 vcc_hi, vcc_hi, 2
	s_lshl_b32 vcc_lo, vcc_lo, 4
	s_add_u32 vcc_lo, vcc_lo, vcc_hi
	s_and_b32 s42, s42, 3
	s_add_u32 vcc_lo, vcc_lo, s42
	s_add_u32 vcc_lo, vcc_lo, 16
	s_and_b32 s43, s101, 0xff
	s_lshl_b32 vcc_lo, vcc_lo, 8
	s_or_b32 s43, s43, vcc_lo
	s_lshl_b32 s8, s43, 11
	s_add_u32 s0, s46, s8
	s_addc_u32 s1, s47, 0
	s_add_u32 s0, s0, 0x5500000
	s_addc_u32 s1, s1, 0
	s_waitcnt vmcnt(16)
; __device__ __forceinline__ unsigned pk2(float lo, float hi) { f32x2_t v = {lo, hi}; bf16x2_t b = __builtin_convertvector(v, bf16x2_t); return __builtin_bit_cast(unsigned, b); }
; __device__ __forceinline__ void phase_norm(const Params& P, int l, int which, bool first) {
;     ...
;     for (int r = gw; r < ROWS; r += NGW) {
;         const int b = r / TT, t = r - b * TT; const int bb = (t < CTX) ? 16 : b;
;         float* xr = xrow_ptr(P, r);
;         const float* src = first ? ((t < CTX) ? P.ctx + ((size_t)b * CTX + t) * DM : P.x + ((size_t)b * SEQ + (t - CTX)) * DM) : xr;
;         f32x4 v[4]; float s2 = 0.f;
; #pragma unroll
;         for (int j = 0; j < 4; ++j) { v[j] = *((const f32x4*)src + lane + 64 * j); s2 += (v[j].x * v[j].x + v[j].y * v[j].y) + (v[j].z * v[j].z + v[j].w * v[j].w); }
;         if (first) {
; #pragma unroll
;             for (int j = 0; j < 4; ++j) *((f32x4*)xr + lane + 64 * j) = v[j];
;         }
;         const float rstd = 1.0f / sqrtf(wave_sum(s2, lane) * (1.0f / DM) + RMS_EPS);
;         const float* mrow = mod + (size_t)bb * MODW;
; #pragma unroll
;         for (int j = 0; j < 4; ++j) {
;             const int c0 = 4 * (lane + 64 * j);
;             const f32x4 g = *(const f32x4*)(gain + c0), sh = *(const f32x4*)(mrow + c0), scl = *(const f32x4*)(mrow + DM + c0);
;             const f32x4 y = v[j] * rstd * g * (scl + 1.0f) + sh;
;             u32x2 w; w.x = pk2(y.x, y.y); w.y = pk2(y.z, y.w);
;             *(u32x2*)(H + (size_t)r * DM + c0) = w;
;         }
	v_mul_f32_e32 v193, v16, v179
	v_add_f32_e32 v192, 1.0, v104
	v_mul_f32_e32 v193, v162, v193
	v_fma_f32 v180, v192, v193, v88
	v_mul_f32_e32 v193, v17, v179
	v_add_f32_e32 v192, 1.0, v105
	v_mul_f32_e32 v193, v163, v193
	v_fma_f32 v181, v192, v193, v89
	v_mul_f32_e32 v193, v18, v179
	v_add_f32_e32 v192, 1.0, v106
	v_mul_f32_e32 v193, v164, v193
	v_fma_f32 v182, v192, v193, v90
	v_mul_f32_e32 v193, v19, v179
	v_add_f32_e32 v192, 1.0, v107
	v_mul_f32_e32 v193, v165, v193
	v_fma_f32 v183, v192, v193, v91
	v_cvt_pk_bf16_f32 v184, v180, v181
	v_cvt_pk_bf16_f32 v185, v182, v183
	global_store_dwordx2 v121, v[184:185], s[0:1]
	v_mul_f32_e32 v193, v20, v179
	v_add_f32_e32 v192, 1.0, v108
	v_mul_f32_e32 v193, v166, v193
	v_fma_f32 v180, v192, v193, v92
	v_mul_f32_e32 v193, v21, v179
	v_add_f32_e32 v192, 1.0, v109
	v_mul_f32_e32 v193, v167, v193
	v_fma_f32 v181, v192, v193, v93
	v_mul_f32_e32 v193, v22, v179
	v_add_f32_e32 v192, 1.0, v110
	v_mul_f32_e32 v193, v168, v193
	v_fma_f32 v182, v192, v193, v94
	v_mul_f32_e32 v193, v23, v179
	v_add_f32_e32 v192, 1.0, v111
	v_mul_f32_e32 v193, v169, v193
	v_fma_f32 v183, v192, v193, v95
	v_cvt_pk_bf16_f32 v186, v180, v181
	v_cvt_pk_bf16_f32 v187, v182, v183
	global_store_dwordx2 v121, v[186:187], s[0:1] offset:512
	v_mul_f32_e32 v193, v24, v179
	v_add_f32_e32 v192, 1.0, v112
	v_mul_f32_e32 v193, v170, v193
	v_fma_f32 v180, v192, v193, v96
	v_mul_f32_e32 v193, v25, v179
	v_add_f32_e32 v192, 1.0, v113
	v_mul_f32_e32 v193, v171, v193
	v_fma_f32 v181, v192, v193, v97
	v_mul_f32_e32 v193, v26, v179
	v_add_f32_e32 v192, 1.0, v114
	v_mul_f32_e32 v193, v172, v193
	v_fma_f32 v182, v192, v193, v98
	v_mul_f32_e32 v193, v27, v179
	v_add_f32_e32 v192, 1.0, v115
	v_mul_f32_e32 v193, v173, v193
	v_fma_f32 v183, v192, v193, v99
	v_cvt_pk_bf16_f32 v188, v180, v181
	v_cvt_pk_bf16_f32 v189, v182, v183
	global_store_dwordx2 v121, v[188:189], s[0:1] offset:1024
	v_mul_f32_e32 v193, v28, v179
	v_add_f32_e32 v192, 1.0, v116
	v_mul_f32_e32 v193, v174, v193
	v_fma_f32 v180, v192, v193, v100
	v_mul_f32_e32 v193, v29, v179
	v_add_f32_e32 v192, 1.0, v117
	v_mul_f32_e32 v193, v175, v193
	v_fma_f32 v181, v192, v193, v101
	v_mul_f32_e32 v193, v30, v179
	v_add_f32_e32 v192, 1.0, v118
	v_mul_f32_e32 v193, v176, v193
	v_fma_f32 v182, v192, v193, v102
	v_mul_f32_e32 v193, v31, v179
	v_add_f32_e32 v192, 1.0, v119
	v_mul_f32_e32 v193, v177, v193
	v_fma_f32 v183, v192, v193, v103
	v_cvt_pk_bf16_f32 v190, v180, v181
	v_cvt_pk_bf16_f32 v191, v182, v183
	global_store_dwordx2 v121, v[190:191], s[0:1] offset:1536
	s_mul_i32 s100, s68, 3
	s_add_u32 s100, s100, s101
	s_cmp_le_u32 s100, 8191
	s_cselect_b32 s100, s100, s101
	s_lshr_b32 s42, s100, 8
	s_lshr_b32 vcc_lo, s42, 2
	s_lshr_b32 vcc_hi, vcc_lo, 1
	s_lshl_b32 vcc_hi, vcc_hi, 2
	s_lshl_b32 vcc_lo, vcc_lo, 4
	s_add_u32 vcc_lo, vcc_lo, vcc_hi
	s_and_b32 s42, s42, 3
	s_add_u32 vcc_lo, vcc_lo, s42
	s_add_u32 vcc_lo, vcc_lo, 16
	s_and_b32 s43, s100, 0xff
	s_lshl_b32 vcc_lo, vcc_lo, 8
	s_or_b32 s43, s43, vcc_lo
	s_lshr_b32 s8, s43, 8
	s_mul_i32 s8, s8, 57
	s_lshr_b32 s8, s8, 9
	s_mul_i32 s9, s8, 0x900
	s_sub_u32 s9, s43, s9
	s_lshl_b32 s0, s8, 11
	s_add_u32 s0, s0, s9
	s_sub_u32 s0, s0, 0x100
	s_lshl_b32 s8, s8, 8
	s_add_u32 s8, s8, s9
	s_cmp_lt_u32 s9, 0x100
	s_cselect_b32 s8, s8, s0
	s_cselect_b32 s0, s36, s44
	s_cselect_b32 s1, s37, s45
	s_lshl_b32 s8, s8, 12
	s_add_u32 s0, s0, s8
	s_addc_u32 s1, s1, 0
	global_load_dwordx4 v[16:19], v120, s[0:1]
	global_load_dwordx4 v[20:23], v120, s[0:1] offset:1024
	global_load_dwordx4 v[24:27], v120, s[0:1] offset:2048
	global_load_dwordx4 v[28:31], v120, s[0:1] offset:3072
	s_add_u32 s101, s101, s68
	s_cmp_gt_u32 s101, 8191
	s_cbranch_scc1 .Lnf_n2i_exit
	s_waitcnt vmcnt(32)
	s_add_u32 s100, s101, s68
	s_cmp_le_u32 s100, 8191
	s_cselect_b32 s100, s100, s101
	s_lshr_b32 s42, s100, 8
	s_lshr_b32 vcc_lo, s42, 2
	s_lshr_b32 vcc_hi, vcc_lo, 1
	s_lshl_b32 vcc_hi, vcc_hi, 2
	s_lshl_b32 vcc_lo, vcc_lo, 4
	s_add_u32 vcc_lo, vcc_lo, vcc_hi
	s_and_b32 s42, s42, 3
	s_add_u32 vcc_lo, vcc_lo, s42
	s_add_u32 vcc_lo, vcc_lo, 16
	s_and_b32 s43, s100, 0xff
	s_lshl_b32 vcc_lo, vcc_lo, 8
	s_or_b32 s43, s43, vcc_lo
	s_lshr_b32 s8, s43, 8
	s_mul_i32 s8, s8, 57
	s_lshr_b32 s8, s8, 9
	s_mul_i32 s9, s8, 0x900
	s_sub_u32 s9, s43, s9
	s_cmp_lt_u32 s9, 0x100
	s_cselect_b32 s8, 16, s8
	s_mul_i32 s8, s8, 0x6000
	s_add_u32 s0, s24, s8
	s_addc_u32 s1, s25, 0
	global_load_dwordx4 v[56:59], v120, s[0:1] offset:-4096
	global_load_dwordx4 v[60:63], v120, s[0:1] offset:-3072
	global_load_dwordx4 v[64:67], v120, s[0:1] offset:-2048
	global_load_dwordx4 v[68:71], v120, s[0:1] offset:-1024
	global_load_dwordx4 v[72:75], v120, s[0:1]
	global_load_dwordx4 v[76:79], v120, s[0:1] offset:1024
	global_load_dwordx4 v[80:83], v120, s[0:1] offset:2048
	global_load_dwordx4 v[84:87], v120, s[0:1] offset:3072
	v_mul_f32_e32 v32, v41, v41
	v_mul_f32_e32 v33, v43, v43
	v_fmac_f32_e32 v32, v40, v40
	v_fmac_f32_e32 v33, v42, v42
	v_add_f32_e32 v34, v32, v33
	v_mul_f32_e32 v32, v45, v45
	v_mul_f32_e32 v33, v47, v47
	v_fmac_f32_e32 v32, v44, v44
	v_fmac_f32_e32 v33, v46, v46
	v_add_f32_e32 v32, v32, v33
	v_add_f32_e32 v34, v34, v32
	v_mul_f32_e32 v32, v49, v49
	v_mul_f32_e32 v33, v51, v51
	v_fmac_f32_e32 v32, v48, v48
	v_fmac_f32_e32 v33, v50, v50
	v_add_f32_e32 v32, v32, v33
	v_add_f32_e32 v34, v34, v32
	v_mul_f32_e32 v32, v53, v53
	v_mul_f32_e32 v33, v55, v55
	v_fmac_f32_e32 v32, v52, v52
	v_fmac_f32_e32 v33, v54, v54
	v_add_f32_e32 v32, v32, v33
	v_add_f32_e32 v34, v34, v32
	ds_bpermute_b32 v32, v122, v34
	s_waitcnt lgkmcnt(0)
	v_add_f32_e32 v34, v34, v32
	ds_bpermute_b32 v32, v123, v34
	s_waitcnt lgkmcnt(0)
; __device__ __forceinline__ unsigned pk2(float lo, float hi) { f32x2_t v = {lo, hi}; bf16x2_t b = __builtin_convertvector(v, bf16x2_t); return __builtin_bit_cast(unsigned, b); }
; __device__ __forceinline__ void phase_norm(const Params& P, int l, int which, bool first) {
;     ...
;         for (int j = 0; j < 4; ++j) { v[j] = *((const f32x4*)src + lane + 64 * j); s2 += (v[j].x * v[j].x + v[j].y * v[j].y) + (v[j].z * v[j].z + v[j].w * v[j].w); }
;         if (first) {
; #pragma unroll
;             for (int j = 0; j < 4; ++j) *((f32x4*)xr + lane + 64 * j) = v[j];
;         }
;         const float rstd = 1.0f / sqrtf(wave_sum(s2, lane) * (1.0f / DM) + RMS_EPS);
;         const float* mrow = mod + (size_t)bb * MODW;
; #pragma unroll
;         for (int j = 0; j < 4; ++j) {
;             const int c0 = 4 * (lane + 64 * j);
;             const f32x4 g = *(const f32x4*)(gain + c0), sh = *(const f32x4*)(mrow + c0), scl = *(const f32x4*)(mrow + DM + c0);
;             const f32x4 y = v[j] * rstd * g * (scl + 1.0f) + sh;
;             u32x2 w; w.x = pk2(y.x, y.y); w.y = pk2(y.z, y.w);
;             *(u32x2*)(H + (size_t)r * DM + c0) = w;
;         }
	v_add_f32_e32 v34, v34, v32
	ds_bpermute_b32 v32, v124, v34
	s_waitcnt lgkmcnt(0)
	v_add_f32_e32 v34, v34, v32
	ds_bpermute_b32 v32, v125, v34
	s_waitcnt lgkmcnt(0)
	v_add_f32_e32 v34, v34, v32
	ds_bpermute_b32 v32, v126, v34
	s_waitcnt lgkmcnt(0)
	v_add_f32_e32 v34, v34, v32
	ds_bpermute_b32 v32, v127, v34
	s_waitcnt lgkmcnt(0)
	v_add_f32_e32 v34, v34, v32
	v_fmamk_f32 v34, v34, 0x3a800000, v201
	v_cmp_gt_f32_e32 vcc, 0xf800000, v34
	v_mul_f32_e32 v32, 0x4f800000, v34
	s_nop 0
	v_cndmask_b32_e32 v34, v34, v32, vcc
	v_sqrt_f32_e32 v32, v34
	s_nop 0
	v_add_u32_e32 v35, -1, v32
	v_fma_f32 v36, -v35, v32, v34
	v_cmp_ge_f32_e64 s[42:43], 0, v36
	v_add_u32_e32 v36, 1, v32
	s_nop 0
	v_cndmask_b32_e64 v35, v32, v35, s[42:43]
	v_fma_f32 v32, -v36, v32, v34
	v_cmp_lt_f32_e64 s[42:43], 0, v32
	s_nop 1
	v_cndmask_b32_e64 v32, v35, v36, s[42:43]
	v_mul_f32_e32 v35, 0x37800000, v32
	v_cndmask_b32_e32 v32, v32, v35, vcc
	v_cmp_class_f32_e32 vcc, v34, v202
	s_nop 1
	v_cndmask_b32_e32 v34, v32, v34, vcc
	v_div_scale_f32 v32, s[42:43], v34, v34, 1.0
	v_rcp_f32_e32 v35, v32
	s_nop 0
	v_fma_f32 v36, -v32, v35, 1.0
	v_fmac_f32_e32 v35, v36, v35
	v_div_scale_f32 v36, vcc, 1.0, v34, 1.0
	v_mul_f32_e32 v37, v36, v35
	v_fma_f32 v178, -v32, v37, v36
	v_fmac_f32_e32 v37, v178, v35
	v_fma_f32 v32, -v32, v37, v36
	v_div_fmas_f32 v32, v32, v35, v37
	v_div_fixup_f32 v179, v32, v34, 1.0
	s_lshr_b32 s42, s101, 8
	s_lshr_b32 vcc_lo, s42, 2
	s_lshr_b32 vcc_hi, vcc_lo, 1
	s_lshl_b32 vcc_hi, vcc_hi, 2
	s_lshl_b32 vcc_lo, vcc_lo, 4
	s_add_u32 vcc_lo, vcc_lo, vcc_hi
	s_and_b32 s42, s42, 3
	s_add_u32 vcc_lo, vcc_lo, s42
	s_add_u32 vcc_lo, vcc_lo, 16
	s_and_b32 s43, s101, 0xff
	s_lshl_b32 vcc_lo, vcc_lo, 8
	s_or_b32 s43, s43, vcc_lo
	s_lshl_b32 s8, s43, 11
	s_add_u32 s0, s46, s8
	s_addc_u32 s1, s47, 0
	s_add_u32 s0, s0, 0x5500000
	s_addc_u32 s1, s1, 0
	s_waitcnt vmcnt(16)
	v_mul_f32_e32 v193, v40, v179
	v_add_f32_e32 v192, 1.0, v146
	v_mul_f32_e32 v193, v162, v193
	v_fma_f32 v180, v192, v193, v130
	v_mul_f32_e32 v193, v41, v179
	v_add_f32_e32 v192, 1.0, v147
	v_mul_f32_e32 v193, v163, v193
	v_fma_f32 v181, v192, v193, v131
	v_mul_f32_e32 v193, v42, v179
	v_add_f32_e32 v192, 1.0, v148
	v_mul_f32_e32 v193, v164, v193
	v_fma_f32 v182, v192, v193, v132
	v_mul_f32_e32 v193, v43, v179
	v_add_f32_e32 v192, 1.0, v149
	v_mul_f32_e32 v193, v165, v193
	v_fma_f32 v183, v192, v193, v133
	v_cvt_pk_bf16_f32 v184, v180, v181
	v_cvt_pk_bf16_f32 v185, v182, v183
	global_store_dwordx2 v121, v[184:185], s[0:1]
	v_mul_f32_e32 v193, v44, v179
	v_add_f32_e32 v192, 1.0, v150
	v_mul_f32_e32 v193, v166, v193
	v_fma_f32 v180, v192, v193, v134
	v_mul_f32_e32 v193, v45, v179
	v_add_f32_e32 v192, 1.0, v151
	v_mul_f32_e32 v193, v167, v193
	v_fma_f32 v181, v192, v193, v135
	v_mul_f32_e32 v193, v46, v179
	v_add_f32_e32 v192, 1.0, v152
	v_mul_f32_e32 v193, v168, v193
	v_fma_f32 v182, v192, v193, v136
	v_mul_f32_e32 v193, v47, v179
	v_add_f32_e32 v192, 1.0, v153
	v_mul_f32_e32 v193, v169, v193
	v_fma_f32 v183, v192, v193, v137
	v_cvt_pk_bf16_f32 v186, v180, v181
	v_cvt_pk_bf16_f32 v187, v182, v183
	global_store_dwordx2 v121, v[186:187], s[0:1] offset:512
	v_mul_f32_e32 v193, v48, v179
	v_add_f32_e32 v192, 1.0, v154
	v_mul_f32_e32 v193, v170, v193
	v_fma_f32 v180, v192, v193, v138
	v_mul_f32_e32 v193, v49, v179
	v_add_f32_e32 v192, 1.0, v155
	v_mul_f32_e32 v193, v171, v193
	v_fma_f32 v181, v192, v193, v139
	v_mul_f32_e32 v193, v50, v179
	v_add_f32_e32 v192, 1.0, v156
	v_mul_f32_e32 v193, v172, v193
	v_fma_f32 v182, v192, v193, v140
	v_mul_f32_e32 v193, v51, v179
	v_add_f32_e32 v192, 1.0, v157
	v_mul_f32_e32 v193, v173, v193
	v_fma_f32 v183, v192, v193, v141
	v_cvt_pk_bf16_f32 v188, v180, v181
	v_cvt_pk_bf16_f32 v189, v182, v183
	global_store_dwordx2 v121, v[188:189], s[0:1] offset:1024
	v_mul_f32_e32 v193, v52, v179
	v_add_f32_e32 v192, 1.0, v158
	v_mul_f32_e32 v193, v174, v193
	v_fma_f32 v180, v192, v193, v142
	v_mul_f32_e32 v193, v53, v179
	v_add_f32_e32 v192, 1.0, v159
	v_mul_f32_e32 v193, v175, v193
	v_fma_f32 v181, v192, v193, v143
	v_mul_f32_e32 v193, v54, v179
	v_add_f32_e32 v192, 1.0, v160
	v_mul_f32_e32 v193, v176, v193
	v_fma_f32 v182, v192, v193, v144
	v_mul_f32_e32 v193, v55, v179
	v_add_f32_e32 v192, 1.0, v161
	v_mul_f32_e32 v193, v177, v193
	v_fma_f32 v183, v192, v193, v145
	v_cvt_pk_bf16_f32 v190, v180, v181
	v_cvt_pk_bf16_f32 v191, v182, v183
	global_store_dwordx2 v121, v[190:191], s[0:1] offset:1536
	s_mul_i32 s100, s68, 3
	s_add_u32 s100, s100, s101
	s_cmp_le_u32 s100, 8191
	s_cselect_b32 s100, s100, s101
	s_lshr_b32 s42, s100, 8
	s_lshr_b32 vcc_lo, s42, 2
	s_lshr_b32 vcc_hi, vcc_lo, 1
	s_lshl_b32 vcc_hi, vcc_hi, 2
	s_lshl_b32 vcc_lo, vcc_lo, 4
	s_add_u32 vcc_lo, vcc_lo, vcc_hi
	s_and_b32 s42, s42, 3
	s_add_u32 vcc_lo, vcc_lo, s42
	s_add_u32 vcc_lo, vcc_lo, 16
	s_and_b32 s43, s100, 0xff
	s_lshl_b32 vcc_lo, vcc_lo, 8
	s_or_b32 s43, s43, vcc_lo
	s_lshr_b32 s8, s43, 8
	s_mul_i32 s8, s8, 57
	s_lshr_b32 s8, s8, 9
	s_mul_i32 s9, s8, 0x900
	s_sub_u32 s9, s43, s9
	s_lshl_b32 s0, s8, 11
	s_add_u32 s0, s0, s9
	s_sub_u32 s0, s0, 0x100
	s_lshl_b32 s8, s8, 8
	s_add_u32 s8, s8, s9
	s_cmp_lt_u32 s9, 0x100
	s_cselect_b32 s8, s8, s0
	s_cselect_b32 s0, s36, s44
	s_cselect_b32 s1, s37, s45
	s_lshl_b32 s8, s8, 12
	s_add_u32 s0, s0, s8
	s_addc_u32 s1, s1, 0
	global_load_dwordx4 v[40:43], v120, s[0:1]
	global_load_dwordx4 v[44:47], v120, s[0:1] offset:1024
	global_load_dwordx4 v[48:51], v120, s[0:1] offset:2048
	global_load_dwordx4 v[52:55], v120, s[0:1] offset:3072
	s_add_u32 s101, s101, s68
	s_cmp_gt_u32 s101, 8191
	s_cbranch_scc1 .Lnf_n2i_exit
; __device__ __forceinline__ unsigned pk2(float lo, float hi) { f32x2_t v = {lo, hi}; bf16x2_t b = __builtin_convertvector(v, bf16x2_t); return __builtin_bit_cast(unsigned, b); }
; __device__ __forceinline__ void phase_norm(const Params& P, int l, int which, bool first) {
;     ...
;     for (int r = gw; r < ROWS; r += NGW) {
;         const int b = r / TT, t = r - b * TT; const int bb = (t < CTX) ? 16 : b;
;         float* xr = xrow_ptr(P, r);
;         const float* src = first ? ((t < CTX) ? P.ctx + ((size_t)b * CTX + t) * DM : P.x + ((size_t)b * SEQ + (t - CTX)) * DM) : xr;
;         f32x4 v[4]; float s2 = 0.f;
; #pragma unroll
;         for (int j = 0; j < 4; ++j) { v[j] = *((const f32x4*)src + lane + 64 * j); s2 += (v[j].x * v[j].x + v[j].y * v[j].y) + (v[j].z * v[j].z + v[j].w * v[j].w); }
;         if (first) {
; #pragma unroll
;             for (int j = 0; j < 4; ++j) *((f32x4*)xr + lane + 64 * j) = v[j];
;         }
;         const float rstd = 1.0f / sqrtf(wave_sum(s2, lane) * (1.0f / DM) + RMS_EPS);
;         const float* mrow = mod + (size_t)bb * MODW;
; #pragma unroll
;         for (int j = 0; j < 4; ++j) {
;             const int c0 = 4 * (lane + 64 * j);
;             const f32x4 g = *(const f32x4*)(gain + c0), sh = *(const f32x4*)(mrow + c0), scl = *(const f32x4*)(mrow + DM + c0);
;             const f32x4 y = v[j] * rstd * g * (scl + 1.0f) + sh;
;             u32x2 w; w.x = pk2(y.x, y.y); w.y = pk2(y.z, y.w);
;             *(u32x2*)(H + (size_t)r * DM + c0) = w;
;         }
.Lnf_n2i_loop:
	s_waitcnt vmcnt(32)
	s_add_u32 s100, s101, s68
	s_cmp_le_u32 s100, 8191
	s_cselect_b32 s100, s100, s101
	s_lshr_b32 s42, s100, 8
	s_lshr_b32 vcc_lo, s42, 2
	s_lshr_b32 vcc_hi, vcc_lo, 1
	s_lshl_b32 vcc_hi, vcc_hi, 2
	s_lshl_b32 vcc_lo, vcc_lo, 4
	s_add_u32 vcc_lo, vcc_lo, vcc_hi
	s_and_b32 s42, s42, 3
	s_add_u32 vcc_lo, vcc_lo, s42
	s_add_u32 vcc_lo, vcc_lo, 16
	s_and_b32 s43, s100, 0xff
	s_lshl_b32 vcc_lo, vcc_lo, 8
	s_or_b32 s43, s43, vcc_lo
	s_lshr_b32 s8, s43, 8
	s_mul_i32 s8, s8, 57
	s_lshr_b32 s8, s8, 9
	s_mul_i32 s9, s8, 0x900
	s_sub_u32 s9, s43, s9
	s_cmp_lt_u32 s9, 0x100
	s_cselect_b32 s8, 16, s8
	s_mul_i32 s8, s8, 0x6000
	s_add_u32 s0, s24, s8
	s_addc_u32 s1, s25, 0
	global_load_dwordx4 v[88:91], v120, s[0:1] offset:-4096
	global_load_dwordx4 v[92:95], v120, s[0:1] offset:-3072
	global_load_dwordx4 v[96:99], v120, s[0:1] offset:-2048
	global_load_dwordx4 v[100:103], v120, s[0:1] offset:-1024
	global_load_dwordx4 v[104:107], v120, s[0:1]
	global_load_dwordx4 v[108:111], v120, s[0:1] offset:1024
	global_load_dwordx4 v[112:115], v120, s[0:1] offset:2048
	global_load_dwordx4 v[116:119], v120, s[0:1] offset:3072
	v_mul_f32_e32 v32, v1, v1
	v_mul_f32_e32 v33, v3, v3
	v_fmac_f32_e32 v32, v0, v0
	v_fmac_f32_e32 v33, v2, v2
	v_add_f32_e32 v34, v32, v33
	v_mul_f32_e32 v32, v5, v5
	v_mul_f32_e32 v33, v7, v7
	v_fmac_f32_e32 v32, v4, v4
	v_fmac_f32_e32 v33, v6, v6
	v_add_f32_e32 v32, v32, v33
	v_add_f32_e32 v34, v34, v32
	v_mul_f32_e32 v32, v9, v9
	v_mul_f32_e32 v33, v11, v11
	v_fmac_f32_e32 v32, v8, v8
	v_fmac_f32_e32 v33, v10, v10
	v_add_f32_e32 v32, v32, v33
	v_add_f32_e32 v34, v34, v32
	v_mul_f32_e32 v32, v13, v13
	v_mul_f32_e32 v33, v15, v15
	v_fmac_f32_e32 v32, v12, v12
	v_fmac_f32_e32 v33, v14, v14
	v_add_f32_e32 v32, v32, v33
	v_add_f32_e32 v34, v34, v32
	ds_bpermute_b32 v32, v122, v34
	s_waitcnt lgkmcnt(0)
	v_add_f32_e32 v34, v34, v32
	ds_bpermute_b32 v32, v123, v34
	s_waitcnt lgkmcnt(0)
	v_add_f32_e32 v34, v34, v32
	ds_bpermute_b32 v32, v124, v34
	s_waitcnt lgkmcnt(0)
	v_add_f32_e32 v34, v34, v32
	ds_bpermute_b32 v32, v125, v34
	s_waitcnt lgkmcnt(0)
	v_add_f32_e32 v34, v34, v32
	ds_bpermute_b32 v32, v126, v34
	s_waitcnt lgkmcnt(0)
	v_add_f32_e32 v34, v34, v32
	ds_bpermute_b32 v32, v127, v34
	s_waitcnt lgkmcnt(0)
	v_add_f32_e32 v34, v34, v32
	v_fmamk_f32 v34, v34, 0x3a800000, v201
	v_cmp_gt_f32_e32 vcc, 0xf800000, v34
	v_mul_f32_e32 v32, 0x4f800000, v34
	s_nop 0
	v_cndmask_b32_e32 v34, v34, v32, vcc
	v_sqrt_f32_e32 v32, v34
	s_nop 0
	v_add_u32_e32 v35, -1, v32
	v_fma_f32 v36, -v35, v32, v34
	v_cmp_ge_f32_e64 s[42:43], 0, v36
	v_add_u32_e32 v36, 1, v32
	s_nop 0
	v_cndmask_b32_e64 v35, v32, v35, s[42:43]
	v_fma_f32 v32, -v36, v32, v34
	v_cmp_lt_f32_e64 s[42:43], 0, v32
	s_nop 1
	v_cndmask_b32_e64 v32, v35, v36, s[42:43]
	v_mul_f32_e32 v35, 0x37800000, v32
	v_cndmask_b32_e32 v32, v32, v35, vcc
	v_cmp_class_f32_e32 vcc, v34, v202
	s_nop 1
	v_cndmask_b32_e32 v34, v32, v34, vcc
	v_div_scale_f32 v32, s[42:43], v34, v34, 1.0
	v_rcp_f32_e32 v35, v32
	s_nop 0
	v_fma_f32 v36, -v32, v35, 1.0
	v_fmac_f32_e32 v35, v36, v35
	v_div_scale_f32 v36, vcc, 1.0, v34, 1.0
	v_mul_f32_e32 v37, v36, v35
	v_fma_f32 v178, -v32, v37, v36
	v_fmac_f32_e32 v37, v178, v35
	v_fma_f32 v32, -v32, v37, v36
	v_div_fmas_f32 v32, v32, v35, v37
	v_div_fixup_f32 v179, v32, v34, 1.0
	s_lshr_b32 s42, s101, 8
	s_lshr_b32 vcc_lo, s42, 2
	s_lshr_b32 vcc_hi, vcc_lo, 1
	s_lshl_b32 vcc_hi, vcc_hi, 2
	s_lshl_b32 vcc_lo, vcc_lo, 4
	s_add_u32 vcc_lo, vcc_lo, vcc_hi
	s_and_b32 s42, s42, 3
	s_add_u32 vcc_lo, vcc_lo, s42
	s_add_u32 vcc_lo, vcc_lo, 16
	s_and_b32 s43, s101, 0xff
	s_lshl_b32 vcc_lo, vcc_lo, 8
	s_or_b32 s43, s43, vcc_lo
	s_lshl_b32 s8, s43, 11
	s_add_u32 s0, s46, s8
	s_addc_u32 s1, s47, 0
	s_add_u32 s0, s0, 0x5500000
	s_addc_u32 s1, s1, 0
	s_waitcnt vmcnt(16)
	v_mul_f32_e32 v193, v0, v179
	v_add_f32_e32 v192, 1.0, v72
	v_mul_f32_e32 v193, v162, v193
	v_fma_f32 v180, v192, v193, v56
	v_mul_f32_e32 v193, v1, v179
	v_add_f32_e32 v192, 1.0, v73
	v_mul_f32_e32 v193, v163, v193
	v_fma_f32 v181, v192, v193, v57
	v_mul_f32_e32 v193, v2, v179
	v_add_f32_e32 v192, 1.0, v74
	v_mul_f32_e32 v193, v164, v193
	v_fma_f32 v182, v192, v193, v58
	v_mul_f32_e32 v193, v3, v179
	v_add_f32_e32 v192, 1.0, v75
	v_mul_f32_e32 v193, v165, v193
	v_fma_f32 v183, v192, v193, v59
	v_cvt_pk_bf16_f32 v184, v180, v181
	v_cvt_pk_bf16_f32 v185, v182, v183
	global_store_dwordx2 v121, v[184:185], s[0:1]
	v_mul_f32_e32 v193, v4, v179
	v_add_f32_e32 v192, 1.0, v76
	v_mul_f32_e32 v193, v166, v193
	v_fma_f32 v180, v192, v193, v60
	v_mul_f32_e32 v193, v5, v179
	v_add_f32_e32 v192, 1.0, v77
	v_mul_f32_e32 v193, v167, v193
	v_fma_f32 v181, v192, v193, v61
	v_mul_f32_e32 v193, v6, v179
	v_add_f32_e32 v192, 1.0, v78
	v_mul_f32_e32 v193, v168, v193
	v_fma_f32 v182, v192, v193, v62
	v_mul_f32_e32 v193, v7, v179
	v_add_f32_e32 v192, 1.0, v79
	v_mul_f32_e32 v193, v169, v193
	v_fma_f32 v183, v192, v193, v63
	v_cvt_pk_bf16_f32 v186, v180, v181
	v_cvt_pk_bf16_f32 v187, v182, v183
	global_store_dwordx2 v121, v[186:187], s[0:1] offset:512
	v_mul_f32_e32 v193, v8, v179
	v_add_f32_e32 v192, 1.0, v80
	v_mul_f32_e32 v193, v170, v193
	v_fma_f32 v180, v192, v193, v64
	v_mul_f32_e32 v193, v9, v179
	v_add_f32_e32 v192, 1.0, v81
	v_mul_f32_e32 v193, v171, v193
	v_fma_f32 v181, v192, v193, v65
	v_mul_f32_e32 v193, v10, v179
	v_add_f32_e32 v192, 1.0, v82
	v_mul_f32_e32 v193, v172, v193
	v_fma_f32 v182, v192, v193, v66
	v_mul_f32_e32 v193, v11, v179
	v_add_f32_e32 v192, 1.0, v83
	v_mul_f32_e32 v193, v173, v193
	v_fma_f32 v183, v192, v193, v67
	v_cvt_pk_bf16_f32 v188, v180, v181
	v_cvt_pk_bf16_f32 v189, v182, v183
; __device__ __forceinline__ unsigned pk2(float lo, float hi) { f32x2_t v = {lo, hi}; bf16x2_t b = __builtin_convertvector(v, bf16x2_t); return __builtin_bit_cast(unsigned, b); }
; __device__ __forceinline__ void phase_norm(const Params& P, int l, int which, bool first) {
;     ...
;     for (int r = gw; r < ROWS; r += NGW) {
;         const int b = r / TT, t = r - b * TT; const int bb = (t < CTX) ? 16 : b;
;         float* xr = xrow_ptr(P, r);
;         const float* src = first ? ((t < CTX) ? P.ctx + ((size_t)b * CTX + t) * DM : P.x + ((size_t)b * SEQ + (t - CTX)) * DM) : xr;
;         f32x4 v[4]; float s2 = 0.f;
; #pragma unroll
;         for (int j = 0; j < 4; ++j) { v[j] = *((const f32x4*)src + lane + 64 * j); s2 += (v[j].x * v[j].x + v[j].y * v[j].y) + (v[j].z * v[j].z + v[j].w * v[j].w); }
;         if (first) {
; #pragma unroll
;             for (int j = 0; j < 4; ++j) *((f32x4*)xr + lane + 64 * j) = v[j];
;         }
;         const float rstd = 1.0f / sqrtf(wave_sum(s2, lane) * (1.0f / DM) + RMS_EPS);
;         const float* mrow = mod + (size_t)bb * MODW;
; #pragma unroll
;         for (int j = 0; j < 4; ++j) {
;             const int c0 = 4 * (lane + 64 * j);
;             const f32x4 g = *(const f32x4*)(gain + c0), sh = *(const f32x4*)(mrow + c0), scl = *(const f32x4*)(mrow + DM + c0);
;             const f32x4 y = v[j] * rstd * g * (scl + 1.0f) + sh;
;             u32x2 w; w.x = pk2(y.x, y.y); w.y = pk2(y.z, y.w);
;             *(u32x2*)(H + (size_t)r * DM + c0) = w;
;         }
;     }
	global_store_dwordx2 v121, v[188:189], s[0:1] offset:1024
	v_mul_f32_e32 v193, v12, v179
	v_add_f32_e32 v192, 1.0, v84
	v_mul_f32_e32 v193, v174, v193
	v_fma_f32 v180, v192, v193, v68
	v_mul_f32_e32 v193, v13, v179
	v_add_f32_e32 v192, 1.0, v85
	v_mul_f32_e32 v193, v175, v193
	v_fma_f32 v181, v192, v193, v69
	v_mul_f32_e32 v193, v14, v179
	v_add_f32_e32 v192, 1.0, v86
	v_mul_f32_e32 v193, v176, v193
	v_fma_f32 v182, v192, v193, v70
	v_mul_f32_e32 v193, v15, v179
	v_add_f32_e32 v192, 1.0, v87
	v_mul_f32_e32 v193, v177, v193
	v_fma_f32 v183, v192, v193, v71
	v_cvt_pk_bf16_f32 v190, v180, v181
	v_cvt_pk_bf16_f32 v191, v182, v183
	global_store_dwordx2 v121, v[190:191], s[0:1] offset:1536
	s_mul_i32 s100, s68, 3
	s_add_u32 s100, s100, s101
	s_cmp_le_u32 s100, 8191
	s_cselect_b32 s100, s100, s101
	s_lshr_b32 s42, s100, 8
	s_lshr_b32 vcc_lo, s42, 2
	s_lshr_b32 vcc_hi, vcc_lo, 1
	s_lshl_b32 vcc_hi, vcc_hi, 2
	s_lshl_b32 vcc_lo, vcc_lo, 4
	s_add_u32 vcc_lo, vcc_lo, vcc_hi
	s_and_b32 s42, s42, 3
	s_add_u32 vcc_lo, vcc_lo, s42
	s_add_u32 vcc_lo, vcc_lo, 16
	s_and_b32 s43, s100, 0xff
	s_lshl_b32 vcc_lo, vcc_lo, 8
	s_or_b32 s43, s43, vcc_lo
	s_lshr_b32 s8, s43, 8
	s_mul_i32 s8, s8, 57
	s_lshr_b32 s8, s8, 9
	s_mul_i32 s9, s8, 0x900
	s_sub_u32 s9, s43, s9
	s_lshl_b32 s0, s8, 11
	s_add_u32 s0, s0, s9
	s_sub_u32 s0, s0, 0x100
	s_lshl_b32 s8, s8, 8
	s_add_u32 s8, s8, s9
	s_cmp_lt_u32 s9, 0x100
	s_cselect_b32 s8, s8, s0
	s_cselect_b32 s0, s36, s44
	s_cselect_b32 s1, s37, s45
	s_lshl_b32 s8, s8, 12
	s_add_u32 s0, s0, s8
	s_addc_u32 s1, s1, 0
	global_load_dwordx4 v[0:3], v120, s[0:1]
	global_load_dwordx4 v[4:7], v120, s[0:1] offset:1024
	global_load_dwordx4 v[8:11], v120, s[0:1] offset:2048
	global_load_dwordx4 v[12:15], v120, s[0:1] offset:3072
	s_add_u32 s101, s101, s68
	s_cmp_gt_u32 s101, 8191
	s_cbranch_scc1 .Lnf_n2i_exit
	s_waitcnt vmcnt(32)
	s_add_u32 s100, s101, s68
	s_cmp_le_u32 s100, 8191
	s_cselect_b32 s100, s100, s101
	s_lshr_b32 s42, s100, 8
	s_lshr_b32 vcc_lo, s42, 2
	s_lshr_b32 vcc_hi, vcc_lo, 1
	s_lshl_b32 vcc_hi, vcc_hi, 2
	s_lshl_b32 vcc_lo, vcc_lo, 4
	s_add_u32 vcc_lo, vcc_lo, vcc_hi
	s_and_b32 s42, s42, 3
	s_add_u32 vcc_lo, vcc_lo, s42
	s_add_u32 vcc_lo, vcc_lo, 16
	s_and_b32 s43, s100, 0xff
	s_lshl_b32 vcc_lo, vcc_lo, 8
	s_or_b32 s43, s43, vcc_lo
	s_lshr_b32 s8, s43, 8
	s_mul_i32 s8, s8, 57
	s_lshr_b32 s8, s8, 9
	s_mul_i32 s9, s8, 0x900
	s_sub_u32 s9, s43, s9
	s_cmp_lt_u32 s9, 0x100
	s_cselect_b32 s8, 16, s8
	s_mul_i32 s8, s8, 0x6000
	s_add_u32 s0, s24, s8
	s_addc_u32 s1, s25, 0
	global_load_dwordx4 v[130:133], v120, s[0:1] offset:-4096
	global_load_dwordx4 v[134:137], v120, s[0:1] offset:-3072
	global_load_dwordx4 v[138:141], v120, s[0:1] offset:-2048
	global_load_dwordx4 v[142:145], v120, s[0:1] offset:-1024
	global_load_dwordx4 v[146:149], v120, s[0:1]
	global_load_dwordx4 v[150:153], v120, s[0:1] offset:1024
	global_load_dwordx4 v[154:157], v120, s[0:1] offset:2048
	global_load_dwordx4 v[158:161], v120, s[0:1] offset:3072
	v_mul_f32_e32 v32, v17, v17
	v_mul_f32_e32 v33, v19, v19
	v_fmac_f32_e32 v32, v16, v16
	v_fmac_f32_e32 v33, v18, v18
	v_add_f32_e32 v34, v32, v33
	v_mul_f32_e32 v32, v21, v21
	v_mul_f32_e32 v33, v23, v23
	v_fmac_f32_e32 v32, v20, v20
	v_fmac_f32_e32 v33, v22, v22
	v_add_f32_e32 v32, v32, v33
	v_add_f32_e32 v34, v34, v32
	v_mul_f32_e32 v32, v25, v25
	v_mul_f32_e32 v33, v27, v27
	v_fmac_f32_e32 v32, v24, v24
	v_fmac_f32_e32 v33, v26, v26
	v_add_f32_e32 v32, v32, v33
	v_add_f32_e32 v34, v34, v32
	v_mul_f32_e32 v32, v29, v29
	v_mul_f32_e32 v33, v31, v31
	v_fmac_f32_e32 v32, v28, v28
	v_fmac_f32_e32 v33, v30, v30
	v_add_f32_e32 v32, v32, v33
	v_add_f32_e32 v34, v34, v32
	ds_bpermute_b32 v32, v122, v34
	s_waitcnt lgkmcnt(0)
	v_add_f32_e32 v34, v34, v32
	ds_bpermute_b32 v32, v123, v34
	s_waitcnt lgkmcnt(0)
	v_add_f32_e32 v34, v34, v32
	ds_bpermute_b32 v32, v124, v34
	s_waitcnt lgkmcnt(0)
	v_add_f32_e32 v34, v34, v32
	ds_bpermute_b32 v32, v125, v34
	s_waitcnt lgkmcnt(0)
	v_add_f32_e32 v34, v34, v32
	ds_bpermute_b32 v32, v126, v34
	s_waitcnt lgkmcnt(0)
	v_add_f32_e32 v34, v34, v32
	ds_bpermute_b32 v32, v127, v34
	s_waitcnt lgkmcnt(0)
	v_add_f32_e32 v34, v34, v32
	v_fmamk_f32 v34, v34, 0x3a800000, v201
	v_cmp_gt_f32_e32 vcc, 0xf800000, v34
	v_mul_f32_e32 v32, 0x4f800000, v34
	s_nop 0
	v_cndmask_b32_e32 v34, v34, v32, vcc
	v_sqrt_f32_e32 v32, v34
	s_nop 0
	v_add_u32_e32 v35, -1, v32
	v_fma_f32 v36, -v35, v32, v34
	v_cmp_ge_f32_e64 s[42:43], 0, v36
	v_add_u32_e32 v36, 1, v32
	s_nop 0
	v_cndmask_b32_e64 v35, v32, v35, s[42:43]
	v_fma_f32 v32, -v36, v32, v34
	v_cmp_lt_f32_e64 s[42:43], 0, v32
	s_nop 1
	v_cndmask_b32_e64 v32, v35, v36, s[42:43]
	v_mul_f32_e32 v35, 0x37800000, v32
	v_cndmask_b32_e32 v32, v32, v35, vcc
	v_cmp_class_f32_e32 vcc, v34, v202
	s_nop 1
	v_cndmask_b32_e32 v34, v32, v34, vcc
	v_div_scale_f32 v32, s[42:43], v34, v34, 1.0
	v_rcp_f32_e32 v35, v32
	s_nop 0
	v_fma_f32 v36, -v32, v35, 1.0
	v_fmac_f32_e32 v35, v36, v35
	v_div_scale_f32 v36, vcc, 1.0, v34, 1.0
	v_mul_f32_e32 v37, v36, v35
	v_fma_f32 v178, -v32, v37, v36
	v_fmac_f32_e32 v37, v178, v35
	v_fma_f32 v32, -v32, v37, v36
	v_div_fmas_f32 v32, v32, v35, v37
	v_div_fixup_f32 v179, v32, v34, 1.0
	s_lshr_b32 s42, s101, 8
	s_lshr_b32 vcc_lo, s42, 2
	s_lshr_b32 vcc_hi, vcc_lo, 1
	s_lshl_b32 vcc_hi, vcc_hi, 2
	s_lshl_b32 vcc_lo, vcc_lo, 4
	s_add_u32 vcc_lo, vcc_lo, vcc_hi
	s_and_b32 s42, s42, 3
	s_add_u32 vcc_lo, vcc_lo, s42
	s_add_u32 vcc_lo, vcc_lo, 16
	s_and_b32 s43, s101, 0xff
	s_lshl_b32 vcc_lo, vcc_lo, 8
	s_or_b32 s43, s43, vcc_lo
	s_lshl_b32 s8, s43, 11
	s_add_u32 s0, s46, s8
	s_addc_u32 s1, s47, 0
	s_add_u32 s0, s0, 0x5500000
	s_addc_u32 s1, s1, 0
	s_waitcnt vmcnt(16)
; __device__ __forceinline__ unsigned pk2(float lo, float hi) { f32x2_t v = {lo, hi}; bf16x2_t b = __builtin_convertvector(v, bf16x2_t); return __builtin_bit_cast(unsigned, b); }
; __device__ __forceinline__ void phase_norm(const Params& P, int l, int which, bool first) {
;     ...
;     for (int r = gw; r < ROWS; r += NGW) {
;         const int b = r / TT, t = r - b * TT; const int bb = (t < CTX) ? 16 : b;
;         float* xr = xrow_ptr(P, r);
;         const float* src = first ? ((t < CTX) ? P.ctx + ((size_t)b * CTX + t) * DM : P.x + ((size_t)b * SEQ + (t - CTX)) * DM) : xr;
;         f32x4 v[4]; float s2 = 0.f;
; #pragma unroll
;         for (int j = 0; j < 4; ++j) { v[j] = *((const f32x4*)src + lane + 64 * j); s2 += (v[j].x * v[j].x + v[j].y * v[j].y) + (v[j].z * v[j].z + v[j].w * v[j].w); }
;         if (first) {
; #pragma unroll
;             for (int j = 0; j < 4; ++j) *((f32x4*)xr + lane + 64 * j) = v[j];
;         }
;         const float rstd = 1.0f / sqrtf(wave_sum(s2, lane) * (1.0f / DM) + RMS_EPS);
;         const float* mrow = mod + (size_t)bb * MODW;
; #pragma unroll
;         for (int j = 0; j < 4; ++j) {
;             const int c0 = 4 * (lane + 64 * j);
;             const f32x4 g = *(const f32x4*)(gain + c0), sh = *(const f32x4*)(mrow + c0), scl = *(const f32x4*)(mrow + DM + c0);
;             const f32x4 y = v[j] * rstd * g * (scl + 1.0f) + sh;
;             u32x2 w; w.x = pk2(y.x, y.y); w.y = pk2(y.z, y.w);
;             *(u32x2*)(H + (size_t)r * DM + c0) = w;
;         }
;     }
	v_mul_f32_e32 v193, v16, v179
	v_add_f32_e32 v192, 1.0, v104
	v_mul_f32_e32 v193, v162, v193
	v_fma_f32 v180, v192, v193, v88
	v_mul_f32_e32 v193, v17, v179
	v_add_f32_e32 v192, 1.0, v105
	v_mul_f32_e32 v193, v163, v193
	v_fma_f32 v181, v192, v193, v89
	v_mul_f32_e32 v193, v18, v179
	v_add_f32_e32 v192, 1.0, v106
	v_mul_f32_e32 v193, v164, v193
	v_fma_f32 v182, v192, v193, v90
	v_mul_f32_e32 v193, v19, v179
	v_add_f32_e32 v192, 1.0, v107
	v_mul_f32_e32 v193, v165, v193
	v_fma_f32 v183, v192, v193, v91
	v_cvt_pk_bf16_f32 v184, v180, v181
	v_cvt_pk_bf16_f32 v185, v182, v183
	global_store_dwordx2 v121, v[184:185], s[0:1]
	v_mul_f32_e32 v193, v20, v179
	v_add_f32_e32 v192, 1.0, v108
	v_mul_f32_e32 v193, v166, v193
	v_fma_f32 v180, v192, v193, v92
	v_mul_f32_e32 v193, v21, v179
	v_add_f32_e32 v192, 1.0, v109
	v_mul_f32_e32 v193, v167, v193
	v_fma_f32 v181, v192, v193, v93
	v_mul_f32_e32 v193, v22, v179
	v_add_f32_e32 v192, 1.0, v110
	v_mul_f32_e32 v193, v168, v193
	v_fma_f32 v182, v192, v193, v94
	v_mul_f32_e32 v193, v23, v179
	v_add_f32_e32 v192, 1.0, v111
	v_mul_f32_e32 v193, v169, v193
	v_fma_f32 v183, v192, v193, v95
	v_cvt_pk_bf16_f32 v186, v180, v181
	v_cvt_pk_bf16_f32 v187, v182, v183
	global_store_dwordx2 v121, v[186:187], s[0:1] offset:512
	v_mul_f32_e32 v193, v24, v179
	v_add_f32_e32 v192, 1.0, v112
	v_mul_f32_e32 v193, v170, v193
	v_fma_f32 v180, v192, v193, v96
	v_mul_f32_e32 v193, v25, v179
	v_add_f32_e32 v192, 1.0, v113
	v_mul_f32_e32 v193, v171, v193
	v_fma_f32 v181, v192, v193, v97
	v_mul_f32_e32 v193, v26, v179
	v_add_f32_e32 v192, 1.0, v114
	v_mul_f32_e32 v193, v172, v193
	v_fma_f32 v182, v192, v193, v98
	v_mul_f32_e32 v193, v27, v179
	v_add_f32_e32 v192, 1.0, v115
	v_mul_f32_e32 v193, v173, v193
	v_fma_f32 v183, v192, v193, v99
	v_cvt_pk_bf16_f32 v188, v180, v181
	v_cvt_pk_bf16_f32 v189, v182, v183
	global_store_dwordx2 v121, v[188:189], s[0:1] offset:1024
	v_mul_f32_e32 v193, v28, v179
	v_add_f32_e32 v192, 1.0, v116
	v_mul_f32_e32 v193, v174, v193
	v_fma_f32 v180, v192, v193, v100
	v_mul_f32_e32 v193, v29, v179
	v_add_f32_e32 v192, 1.0, v117
	v_mul_f32_e32 v193, v175, v193
	v_fma_f32 v181, v192, v193, v101
	v_mul_f32_e32 v193, v30, v179
	v_add_f32_e32 v192, 1.0, v118
	v_mul_f32_e32 v193, v176, v193
	v_fma_f32 v182, v192, v193, v102
	v_mul_f32_e32 v193, v31, v179
	v_add_f32_e32 v192, 1.0, v119
	v_mul_f32_e32 v193, v177, v193
	v_fma_f32 v183, v192, v193, v103
	v_cvt_pk_bf16_f32 v190, v180, v181
	v_cvt_pk_bf16_f32 v191, v182, v183
	global_store_dwordx2 v121, v[190:191], s[0:1] offset:1536
	s_mul_i32 s100, s68, 3
	s_add_u32 s100, s100, s101
	s_cmp_le_u32 s100, 8191
	s_cselect_b32 s100, s100, s101
	s_lshr_b32 s42, s100, 8
	s_lshr_b32 vcc_lo, s42, 2
	s_lshr_b32 vcc_hi, vcc_lo, 1
	s_lshl_b32 vcc_hi, vcc_hi, 2
	s_lshl_b32 vcc_lo, vcc_lo, 4
	s_add_u32 vcc_lo, vcc_lo, vcc_hi
	s_and_b32 s42, s42, 3
	s_add_u32 vcc_lo, vcc_lo, s42
	s_add_u32 vcc_lo, vcc_lo, 16
	s_and_b32 s43, s100, 0xff
	s_lshl_b32 vcc_lo, vcc_lo, 8
	s_or_b32 s43, s43, vcc_lo
	s_lshr_b32 s8, s43, 8
	s_mul_i32 s8, s8, 57
	s_lshr_b32 s8, s8, 9
	s_mul_i32 s9, s8, 0x900
	s_sub_u32 s9, s43, s9
	s_lshl_b32 s0, s8, 11
	s_add_u32 s0, s0, s9
	s_sub_u32 s0, s0, 0x100
	s_lshl_b32 s8, s8, 8
	s_add_u32 s8, s8, s9
	s_cmp_lt_u32 s9, 0x100
	s_cselect_b32 s8, s8, s0
	s_cselect_b32 s0, s36, s44
	s_cselect_b32 s1, s37, s45
	s_lshl_b32 s8, s8, 12
	s_add_u32 s0, s0, s8
	s_addc_u32 s1, s1, 0
	global_load_dwordx4 v[16:19], v120, s[0:1]
	global_load_dwordx4 v[20:23], v120, s[0:1] offset:1024
	global_load_dwordx4 v[24:27], v120, s[0:1] offset:2048
	global_load_dwordx4 v[28:31], v120, s[0:1] offset:3072
	s_add_u32 s101, s101, s68
	s_cmp_gt_u32 s101, 8191
	s_cbranch_scc1 .Lnf_n2i_exit
	s_waitcnt vmcnt(32)
	s_add_u32 s100, s101, s68
	s_cmp_le_u32 s100, 8191
	s_cselect_b32 s100, s100, s101
	s_lshr_b32 s42, s100, 8
	s_lshr_b32 vcc_lo, s42, 2
	s_lshr_b32 vcc_hi, vcc_lo, 1
	s_lshl_b32 vcc_hi, vcc_hi, 2
	s_lshl_b32 vcc_lo, vcc_lo, 4
	s_add_u32 vcc_lo, vcc_lo, vcc_hi
	s_and_b32 s42, s42, 3
	s_add_u32 vcc_lo, vcc_lo, s42
	s_add_u32 vcc_lo, vcc_lo, 16
	s_and_b32 s43, s100, 0xff
	s_lshl_b32 vcc_lo, vcc_lo, 8
	s_or_b32 s43, s43, vcc_lo
	s_lshr_b32 s8, s43, 8
	s_mul_i32 s8, s8, 57
	s_lshr_b32 s8, s8, 9
	s_mul_i32 s9, s8, 0x900
	s_sub_u32 s9, s43, s9
	s_cmp_lt_u32 s9, 0x100
	s_cselect_b32 s8, 16, s8
	s_mul_i32 s8, s8, 0x6000
	s_add_u32 s0, s24, s8
	s_addc_u32 s1, s25, 0
	global_load_dwordx4 v[56:59], v120, s[0:1] offset:-4096
	global_load_dwordx4 v[60:63], v120, s[0:1] offset:-3072
	global_load_dwordx4 v[64:67], v120, s[0:1] offset:-2048
	global_load_dwordx4 v[68:71], v120, s[0:1] offset:-1024
	global_load_dwordx4 v[72:75], v120, s[0:1]
	global_load_dwordx4 v[76:79], v120, s[0:1] offset:1024
	global_load_dwordx4 v[80:83], v120, s[0:1] offset:2048
	global_load_dwordx4 v[84:87], v120, s[0:1] offset:3072
	v_mul_f32_e32 v32, v41, v41
	v_mul_f32_e32 v33, v43, v43
	v_fmac_f32_e32 v32, v40, v40
	v_fmac_f32_e32 v33, v42, v42
	v_add_f32_e32 v34, v32, v33
	v_mul_f32_e32 v32, v45, v45
	v_mul_f32_e32 v33, v47, v47
	v_fmac_f32_e32 v32, v44, v44
	v_fmac_f32_e32 v33, v46, v46
	v_add_f32_e32 v32, v32, v33
	v_add_f32_e32 v34, v34, v32
	v_mul_f32_e32 v32, v49, v49
	v_mul_f32_e32 v33, v51, v51
	v_fmac_f32_e32 v32, v48, v48
	v_fmac_f32_e32 v33, v50, v50
	v_add_f32_e32 v32, v32, v33
	v_add_f32_e32 v34, v34, v32
	v_mul_f32_e32 v32, v53, v53
	v_mul_f32_e32 v33, v55, v55
	v_fmac_f32_e32 v32, v52, v52
	v_fmac_f32_e32 v33, v54, v54
	v_add_f32_e32 v32, v32, v33
	v_add_f32_e32 v34, v34, v32
	ds_bpermute_b32 v32, v122, v34
	s_waitcnt lgkmcnt(0)
	v_add_f32_e32 v34, v34, v32
	ds_bpermute_b32 v32, v123, v34
	s_waitcnt lgkmcnt(0)
; __device__ __forceinline__ unsigned pk2(float lo, float hi) { f32x2_t v = {lo, hi}; bf16x2_t b = __builtin_convertvector(v, bf16x2_t); return __builtin_bit_cast(unsigned, b); }
; __device__ __forceinline__ void phase_norm(const Params& P, int l, int which, bool first) {
;     ...
;     for (int r = gw; r < ROWS; r += NGW) {
;         const int b = r / TT, t = r - b * TT; const int bb = (t < CTX) ? 16 : b;
;         float* xr = xrow_ptr(P, r);
;         const float* src = first ? ((t < CTX) ? P.ctx + ((size_t)b * CTX + t) * DM : P.x + ((size_t)b * SEQ + (t - CTX)) * DM) : xr;
;         f32x4 v[4]; float s2 = 0.f;
; #pragma unroll
;         for (int j = 0; j < 4; ++j) { v[j] = *((const f32x4*)src + lane + 64 * j); s2 += (v[j].x * v[j].x + v[j].y * v[j].y) + (v[j].z * v[j].z + v[j].w * v[j].w); }
;         if (first) {
; #pragma unroll
;             for (int j = 0; j < 4; ++j) *((f32x4*)xr + lane + 64 * j) = v[j];
;         }
;         const float rstd = 1.0f / sqrtf(wave_sum(s2, lane) * (1.0f / DM) + RMS_EPS);
;         const float* mrow = mod + (size_t)bb * MODW;
; #pragma unroll
;         for (int j = 0; j < 4; ++j) {
;             const int c0 = 4 * (lane + 64 * j);
;             const f32x4 g = *(const f32x4*)(gain + c0), sh = *(const f32x4*)(mrow + c0), scl = *(const f32x4*)(mrow + DM + c0);
;             const f32x4 y = v[j] * rstd * g * (scl + 1.0f) + sh;
;             u32x2 w; w.x = pk2(y.x, y.y); w.y = pk2(y.z, y.w);
;             *(u32x2*)(H + (size_t)r * DM + c0) = w;
;         }
;     }
	v_add_f32_e32 v34, v34, v32
	ds_bpermute_b32 v32, v124, v34
	s_waitcnt lgkmcnt(0)
	v_add_f32_e32 v34, v34, v32
	ds_bpermute_b32 v32, v125, v34
	s_waitcnt lgkmcnt(0)
	v_add_f32_e32 v34, v34, v32
	ds_bpermute_b32 v32, v126, v34
	s_waitcnt lgkmcnt(0)
	v_add_f32_e32 v34, v34, v32
	ds_bpermute_b32 v32, v127, v34
	s_waitcnt lgkmcnt(0)
	v_add_f32_e32 v34, v34, v32
	v_fmamk_f32 v34, v34, 0x3a800000, v201
	v_cmp_gt_f32_e32 vcc, 0xf800000, v34
	v_mul_f32_e32 v32, 0x4f800000, v34
	s_nop 0
	v_cndmask_b32_e32 v34, v34, v32, vcc
	v_sqrt_f32_e32 v32, v34
	s_nop 0
	v_add_u32_e32 v35, -1, v32
	v_fma_f32 v36, -v35, v32, v34
	v_cmp_ge_f32_e64 s[42:43], 0, v36
	v_add_u32_e32 v36, 1, v32
	s_nop 0
	v_cndmask_b32_e64 v35, v32, v35, s[42:43]
	v_fma_f32 v32, -v36, v32, v34
	v_cmp_lt_f32_e64 s[42:43], 0, v32
	s_nop 1
	v_cndmask_b32_e64 v32, v35, v36, s[42:43]
	v_mul_f32_e32 v35, 0x37800000, v32
	v_cndmask_b32_e32 v32, v32, v35, vcc
	v_cmp_class_f32_e32 vcc, v34, v202
	s_nop 1
	v_cndmask_b32_e32 v34, v32, v34, vcc
	v_div_scale_f32 v32, s[42:43], v34, v34, 1.0
	v_rcp_f32_e32 v35, v32
	s_nop 0
	v_fma_f32 v36, -v32, v35, 1.0
	v_fmac_f32_e32 v35, v36, v35
	v_div_scale_f32 v36, vcc, 1.0, v34, 1.0
	v_mul_f32_e32 v37, v36, v35
	v_fma_f32 v178, -v32, v37, v36
	v_fmac_f32_e32 v37, v178, v35
	v_fma_f32 v32, -v32, v37, v36
	v_div_fmas_f32 v32, v32, v35, v37
	v_div_fixup_f32 v179, v32, v34, 1.0
	s_lshr_b32 s42, s101, 8
	s_lshr_b32 vcc_lo, s42, 2
	s_lshr_b32 vcc_hi, vcc_lo, 1
	s_lshl_b32 vcc_hi, vcc_hi, 2
	s_lshl_b32 vcc_lo, vcc_lo, 4
	s_add_u32 vcc_lo, vcc_lo, vcc_hi
	s_and_b32 s42, s42, 3
	s_add_u32 vcc_lo, vcc_lo, s42
	s_add_u32 vcc_lo, vcc_lo, 16
	s_and_b32 s43, s101, 0xff
	s_lshl_b32 vcc_lo, vcc_lo, 8
	s_or_b32 s43, s43, vcc_lo
	s_lshl_b32 s8, s43, 11
	s_add_u32 s0, s46, s8
	s_addc_u32 s1, s47, 0
	s_add_u32 s0, s0, 0x5500000
	s_addc_u32 s1, s1, 0
	s_waitcnt vmcnt(16)
	v_mul_f32_e32 v193, v40, v179
	v_add_f32_e32 v192, 1.0, v146
	v_mul_f32_e32 v193, v162, v193
	v_fma_f32 v180, v192, v193, v130
	v_mul_f32_e32 v193, v41, v179
	v_add_f32_e32 v192, 1.0, v147
	v_mul_f32_e32 v193, v163, v193
	v_fma_f32 v181, v192, v193, v131
	v_mul_f32_e32 v193, v42, v179
	v_add_f32_e32 v192, 1.0, v148
	v_mul_f32_e32 v193, v164, v193
	v_fma_f32 v182, v192, v193, v132
	v_mul_f32_e32 v193, v43, v179
	v_add_f32_e32 v192, 1.0, v149
	v_mul_f32_e32 v193, v165, v193
	v_fma_f32 v183, v192, v193, v133
	v_cvt_pk_bf16_f32 v184, v180, v181
	v_cvt_pk_bf16_f32 v185, v182, v183
	global_store_dwordx2 v121, v[184:185], s[0:1]
	v_mul_f32_e32 v193, v44, v179
	v_add_f32_e32 v192, 1.0, v150
	v_mul_f32_e32 v193, v166, v193
	v_fma_f32 v180, v192, v193, v134
	v_mul_f32_e32 v193, v45, v179
	v_add_f32_e32 v192, 1.0, v151
	v_mul_f32_e32 v193, v167, v193
	v_fma_f32 v181, v192, v193, v135
	v_mul_f32_e32 v193, v46, v179
	v_add_f32_e32 v192, 1.0, v152
	v_mul_f32_e32 v193, v168, v193
	v_fma_f32 v182, v192, v193, v136
	v_mul_f32_e32 v193, v47, v179
	v_add_f32_e32 v192, 1.0, v153
	v_mul_f32_e32 v193, v169, v193
	v_fma_f32 v183, v192, v193, v137
	v_cvt_pk_bf16_f32 v186, v180, v181
	v_cvt_pk_bf16_f32 v187, v182, v183
	global_store_dwordx2 v121, v[186:187], s[0:1] offset:512
	v_mul_f32_e32 v193, v48, v179
	v_add_f32_e32 v192, 1.0, v154
	v_mul_f32_e32 v193, v170, v193
	v_fma_f32 v180, v192, v193, v138
	v_mul_f32_e32 v193, v49, v179
	v_add_f32_e32 v192, 1.0, v155
	v_mul_f32_e32 v193, v171, v193
	v_fma_f32 v181, v192, v193, v139
	v_mul_f32_e32 v193, v50, v179
	v_add_f32_e32 v192, 1.0, v156
	v_mul_f32_e32 v193, v172, v193
	v_fma_f32 v182, v192, v193, v140
	v_mul_f32_e32 v193, v51, v179
	v_add_f32_e32 v192, 1.0, v157
	v_mul_f32_e32 v193, v173, v193
	v_fma_f32 v183, v192, v193, v141
	v_cvt_pk_bf16_f32 v188, v180, v181
	v_cvt_pk_bf16_f32 v189, v182, v183
	global_store_dwordx2 v121, v[188:189], s[0:1] offset:1024
	v_mul_f32_e32 v193, v52, v179
	v_add_f32_e32 v192, 1.0, v158
	v_mul_f32_e32 v193, v174, v193
	v_fma_f32 v180, v192, v193, v142
	v_mul_f32_e32 v193, v53, v179
	v_add_f32_e32 v192, 1.0, v159
	v_mul_f32_e32 v193, v175, v193
	v_fma_f32 v181, v192, v193, v143
	v_mul_f32_e32 v193, v54, v179
	v_add_f32_e32 v192, 1.0, v160
	v_mul_f32_e32 v193, v176, v193
	v_fma_f32 v182, v192, v193, v144
	v_mul_f32_e32 v193, v55, v179
	v_add_f32_e32 v192, 1.0, v161
	v_mul_f32_e32 v193, v177, v193
	v_fma_f32 v183, v192, v193, v145
	v_cvt_pk_bf16_f32 v190, v180, v181
	v_cvt_pk_bf16_f32 v191, v182, v183
	global_store_dwordx2 v121, v[190:191], s[0:1] offset:1536
	s_mul_i32 s100, s68, 3
	s_add_u32 s100, s100, s101
	s_cmp_le_u32 s100, 8191
	s_cselect_b32 s100, s100, s101
	s_lshr_b32 s42, s100, 8
	s_lshr_b32 vcc_lo, s42, 2
	s_lshr_b32 vcc_hi, vcc_lo, 1
	s_lshl_b32 vcc_hi, vcc_hi, 2
	s_lshl_b32 vcc_lo, vcc_lo, 4
	s_add_u32 vcc_lo, vcc_lo, vcc_hi
	s_and_b32 s42, s42, 3
	s_add_u32 vcc_lo, vcc_lo, s42
	s_add_u32 vcc_lo, vcc_lo, 16
	s_and_b32 s43, s100, 0xff
	s_lshl_b32 vcc_lo, vcc_lo, 8
	s_or_b32 s43, s43, vcc_lo
	s_lshr_b32 s8, s43, 8
	s_mul_i32 s8, s8, 57
	s_lshr_b32 s8, s8, 9
	s_mul_i32 s9, s8, 0x900
	s_sub_u32 s9, s43, s9
	s_lshl_b32 s0, s8, 11
	s_add_u32 s0, s0, s9
	s_sub_u32 s0, s0, 0x100
	s_lshl_b32 s8, s8, 8
	s_add_u32 s8, s8, s9
	s_cmp_lt_u32 s9, 0x100
	s_cselect_b32 s8, s8, s0
	s_cselect_b32 s0, s36, s44
	s_cselect_b32 s1, s37, s45
	s_lshl_b32 s8, s8, 12
	s_add_u32 s0, s0, s8
	s_addc_u32 s1, s1, 0
	global_load_dwordx4 v[40:43], v120, s[0:1]
	global_load_dwordx4 v[44:47], v120, s[0:1] offset:1024
	global_load_dwordx4 v[48:51], v120, s[0:1] offset:2048
	global_load_dwordx4 v[52:55], v120, s[0:1] offset:3072
	s_add_u32 s101, s101, s68
	s_cmp_gt_u32 s101, 8191
	s_cbranch_scc1 .Lnf_n2i_exit
	s_branch .Lnf_n2i_loop

; __device__ __forceinline__ int opaque_tid() { int t = threadIdx.x; asm volatile("" : "+v"(t)); return t; }
; __device__ __forceinline__ unsigned pk2(float lo, float hi) { f32x2_t v = {lo, hi}; bf16x2_t b = __builtin_convertvector(v, bf16x2_t); return __builtin_bit_cast(unsigned, b); }
; __device__ __forceinline__ void phase_norm(const Params& P, int l, int which, bool first) {
;     const int tid = opaque_tid(), lane = tid & 63, wave = tid >> 6;
;     const int gw = blockIdx.x * 8 + wave, NGW = gridDim.x * 8;
;     const float* gain = (which == 0 ? P.norm1 : P.norm2) + (size_t)l * DM;
;     const float* mod = (const float*)(P.ws + WS_MOD) + (size_t)l * 17 * MODW + (which == 0 ? 0 : 3 * DM);
;     bf16_t* H = (bf16_t*)(P.ws + WS_H);
;     for (int r = gw; r < ROWS; r += NGW) {
;         const int b = r / TT, t = r - b * TT; const int bb = (t < CTX) ? 16 : b;
;         float* xr = xrow_ptr(P, r);
;         const float* src = first ? ((t < CTX) ? P.ctx + ((size_t)b * CTX + t) * DM : P.x + ((size_t)b * SEQ + (t - CTX)) * DM) : xr;
;         f32x4 v[4]; float s2 = 0.f;
; #pragma unroll
;         for (int j = 0; j < 4; ++j) { v[j] = *((const f32x4*)src + lane + 64 * j); s2 += (v[j].x * v[j].x + v[j].y * v[j].y) + (v[j].z * v[j].z + v[j].w * v[j].w); }
;         if (first) {
; #pragma unroll
;             for (int j = 0; j < 4; ++j) *((f32x4*)xr + lane + 64 * j) = v[j];
;         }
;         const float rstd = 1.0f / sqrtf(wave_sum(s2, lane) * (1.0f / DM) + RMS_EPS);
;         const float* mrow = mod + (size_t)bb * MODW;
; #pragma unroll
;         for (int j = 0; j < 4; ++j) {
;             const int c0 = 4 * (lane + 64 * j);
;             const f32x4 g = *(const f32x4*)(gain + c0), sh = *(const f32x4*)(mrow + c0), scl = *(const f32x4*)(mrow + DM + c0);
;             const f32x4 y = v[j] * rstd * g * (scl + 1.0f) + sh;
;             u32x2 w; w.x = pk2(y.x, y.y); w.y = pk2(y.z, y.w);
;             *(u32x2*)(H + (size_t)r * DM + c0) = w;
;         }
;     }
.Lnf_n2_full:
	s_load_dwordx4 s[44:47], s[24:25], 0x98
	s_load_dwordx2 s[0:1], s[24:25], 0x78
	v_readlane_b32 s8, v255, 2
	v_readlane_b32 s9, v254, 63
	v_readlane_b32 s100, v255, 0
	v_readfirstlane_b32 s101, v20
	v_and_b32_e32 v120, 63, v200
	v_lshlrev_b32_e32 v121, 3, v120
	v_lshlrev_b32_e32 v32, 2, v120
	v_xor_b32_e32 v122, 4, v32
	v_xor_b32_e32 v123, 8, v32
	v_xor_b32_e32 v124, 16, v32
	v_xor_b32_e32 v125, 32, v32
	v_xor_b32_e32 v126, 64, v32
	v_xor_b32_e32 v127, 0x80, v32
	v_lshlrev_b32_e32 v120, 4, v120
	s_waitcnt lgkmcnt(0)
	s_add_u32 s8, s46, s8
	s_addc_u32 s9, s47, s9
	s_add_u32 s24, s8, 0x104000
	s_addc_u32 s25, s9, 0
	s_lshl_b32 s100, s100, 12
	s_add_u32 s0, s0, s100
	s_addc_u32 s1, s1, 0
	s_add_u32 s36, s46, 0x4500000
	s_addc_u32 s37, s47, 0
	global_load_dwordx4 v[162:165], v120, s[0:1]
	global_load_dwordx4 v[166:169], v120, s[0:1] offset:1024
	global_load_dwordx4 v[170:173], v120, s[0:1] offset:2048
	global_load_dwordx4 v[174:177], v120, s[0:1] offset:3072
	s_lshr_b32 s8, s101, 8
	s_mul_i32 s8, s8, 57
	s_lshr_b32 s8, s8, 9
	s_mul_i32 s9, s8, 0x900
	s_sub_u32 s9, s101, s9
	s_lshl_b32 s0, s8, 11
	s_add_u32 s0, s0, s9
	s_sub_u32 s0, s0, 0x100
	s_lshl_b32 s8, s8, 8
	s_add_u32 s8, s8, s9
	s_cmp_lt_u32 s9, 0x100
	s_cselect_b32 s8, s8, s0
	s_cselect_b32 s0, s36, s44
	s_cselect_b32 s1, s37, s45
	s_lshl_b32 s8, s8, 12
	s_add_u32 s0, s0, s8
	s_addc_u32 s1, s1, 0
	global_load_dwordx4 v[0:3], v120, s[0:1]
	global_load_dwordx4 v[4:7], v120, s[0:1] offset:1024
	global_load_dwordx4 v[8:11], v120, s[0:1] offset:2048
	global_load_dwordx4 v[12:15], v120, s[0:1] offset:3072
	s_add_u32 s100, s101, s68
	s_cmp_le_u32 s100, s71
	s_cselect_b32 s100, s100, s101
	s_lshr_b32 s8, s100, 8
	s_mul_i32 s8, s8, 57
	s_lshr_b32 s8, s8, 9
	s_mul_i32 s9, s8, 0x900
	s_sub_u32 s9, s100, s9
	s_lshl_b32 s0, s8, 11
	s_add_u32 s0, s0, s9
	s_sub_u32 s0, s0, 0x100
	s_lshl_b32 s8, s8, 8
	s_add_u32 s8, s8, s9
	s_cmp_lt_u32 s9, 0x100
	s_cselect_b32 s8, s8, s0
	s_cselect_b32 s0, s36, s44
	s_cselect_b32 s1, s37, s45
	s_lshl_b32 s8, s8, 12
	s_add_u32 s0, s0, s8
	s_addc_u32 s1, s1, 0
	global_load_dwordx4 v[16:19], v120, s[0:1]
	global_load_dwordx4 v[20:23], v120, s[0:1] offset:1024
	global_load_dwordx4 v[24:27], v120, s[0:1] offset:2048
	global_load_dwordx4 v[28:31], v120, s[0:1] offset:3072
	s_mul_i32 s100, s68, 2
	s_add_u32 s100, s100, s101
	s_cmp_le_u32 s100, s71
	s_cselect_b32 s100, s100, s101
	s_lshr_b32 s8, s100, 8
	s_mul_i32 s8, s8, 57
	s_lshr_b32 s8, s8, 9
	s_mul_i32 s9, s8, 0x900
	s_sub_u32 s9, s100, s9
	s_lshl_b32 s0, s8, 11
	s_add_u32 s0, s0, s9
	s_sub_u32 s0, s0, 0x100
	s_lshl_b32 s8, s8, 8
	s_add_u32 s8, s8, s9
	s_cmp_lt_u32 s9, 0x100
	s_cselect_b32 s8, s8, s0
	s_cselect_b32 s0, s36, s44
	s_cselect_b32 s1, s37, s45
	s_lshl_b32 s8, s8, 12
	s_add_u32 s0, s0, s8
	s_addc_u32 s1, s1, 0
	global_load_dwordx4 v[40:43], v120, s[0:1]
	global_load_dwordx4 v[44:47], v120, s[0:1] offset:1024
	global_load_dwordx4 v[48:51], v120, s[0:1] offset:2048
	global_load_dwordx4 v[52:55], v120, s[0:1] offset:3072
	s_lshr_b32 s8, s101, 8
	s_mul_i32 s8, s8, 57
	s_lshr_b32 s8, s8, 9
	s_mul_i32 s9, s8, 0x900
	s_sub_u32 s9, s101, s9
	s_cmp_lt_u32 s9, 0x100
	s_cselect_b32 s8, 16, s8
	s_mul_i32 s8, s8, 0x6000
	s_add_u32 s0, s24, s8
	s_addc_u32 s1, s25, 0
	global_load_dwordx4 v[56:59], v120, s[0:1] offset:-4096
	global_load_dwordx4 v[60:63], v120, s[0:1] offset:-3072
	global_load_dwordx4 v[64:67], v120, s[0:1] offset:-2048
	global_load_dwordx4 v[68:71], v120, s[0:1] offset:-1024
	global_load_dwordx4 v[72:75], v120, s[0:1]
	global_load_dwordx4 v[76:79], v120, s[0:1] offset:1024
	global_load_dwordx4 v[80:83], v120, s[0:1] offset:2048
	global_load_dwordx4 v[84:87], v120, s[0:1] offset:3072
	s_waitcnt vmcnt(16)
	s_add_u32 s100, s101, s68
	s_cmp_le_u32 s100, s71
	s_cselect_b32 s100, s100, s101
	s_lshr_b32 s8, s100, 8
	s_mul_i32 s8, s8, 57
	s_lshr_b32 s8, s8, 9
	s_mul_i32 s9, s8, 0x900
	s_sub_u32 s9, s100, s9
	s_cmp_lt_u32 s9, 0x100
	s_cselect_b32 s8, 16, s8
	s_mul_i32 s8, s8, 0x6000
	s_add_u32 s0, s24, s8
	s_addc_u32 s1, s25, 0
	global_load_dwordx4 v[88:91], v120, s[0:1] offset:-4096
	global_load_dwordx4 v[92:95], v120, s[0:1] offset:-3072
	global_load_dwordx4 v[96:99], v120, s[0:1] offset:-2048
	global_load_dwordx4 v[100:103], v120, s[0:1] offset:-1024
	global_load_dwordx4 v[104:107], v120, s[0:1]
	global_load_dwordx4 v[108:111], v120, s[0:1] offset:1024
	global_load_dwordx4 v[112:115], v120, s[0:1] offset:2048
	global_load_dwordx4 v[116:119], v120, s[0:1] offset:3072
	v_mul_f32_e32 v32, v1, v1
	v_mul_f32_e32 v33, v3, v3
	v_fmac_f32_e32 v32, v0, v0
	v_fmac_f32_e32 v33, v2, v2
	v_add_f32_e32 v34, v32, v33
	v_mul_f32_e32 v32, v5, v5
	v_mul_f32_e32 v33, v7, v7
	v_fmac_f32_e32 v32, v4, v4
	v_fmac_f32_e32 v33, v6, v6
	v_add_f32_e32 v32, v32, v33
	v_add_f32_e32 v34, v34, v32
	v_mul_f32_e32 v32, v9, v9
	v_mul_f32_e32 v33, v11, v11
	v_fmac_f32_e32 v32, v8, v8
	v_fmac_f32_e32 v33, v10, v10
	v_add_f32_e32 v32, v32, v33
	v_add_f32_e32 v34, v34, v32
	v_mul_f32_e32 v32, v13, v13
	v_mul_f32_e32 v33, v15, v15
	v_fmac_f32_e32 v32, v12, v12
	v_fmac_f32_e32 v33, v14, v14
	v_add_f32_e32 v32, v32, v33
	v_add_f32_e32 v34, v34, v32
	ds_bpermute_b32 v32, v122, v34
	s_waitcnt lgkmcnt(0)
	v_add_f32_e32 v34, v34, v32
	ds_bpermute_b32 v32, v123, v34
	s_waitcnt lgkmcnt(0)
	v_add_f32_e32 v34, v34, v32
	ds_bpermute_b32 v32, v124, v34
	s_waitcnt lgkmcnt(0)
	v_add_f32_e32 v34, v34, v32
	ds_bpermute_b32 v32, v125, v34
	s_waitcnt lgkmcnt(0)
	v_add_f32_e32 v34, v34, v32
	ds_bpermute_b32 v32, v126, v34
	s_waitcnt lgkmcnt(0)
	v_add_f32_e32 v34, v34, v32
	ds_bpermute_b32 v32, v127, v34
	s_waitcnt lgkmcnt(0)
; __device__ __forceinline__ unsigned pk2(float lo, float hi) { f32x2_t v = {lo, hi}; bf16x2_t b = __builtin_convertvector(v, bf16x2_t); return __builtin_bit_cast(unsigned, b); }
; __device__ __forceinline__ void phase_norm(const Params& P, int l, int which, bool first) {
;     ...
;     for (int r = gw; r < ROWS; r += NGW) {
;         const int b = r / TT, t = r - b * TT; const int bb = (t < CTX) ? 16 : b;
;         float* xr = xrow_ptr(P, r);
;         const float* src = first ? ((t < CTX) ? P.ctx + ((size_t)b * CTX + t) * DM : P.x + ((size_t)b * SEQ + (t - CTX)) * DM) : xr;
;         f32x4 v[4]; float s2 = 0.f;
; #pragma unroll
;         for (int j = 0; j < 4; ++j) { v[j] = *((const f32x4*)src + lane + 64 * j); s2 += (v[j].x * v[j].x + v[j].y * v[j].y) + (v[j].z * v[j].z + v[j].w * v[j].w); }
;         if (first) {
; #pragma unroll
;             for (int j = 0; j < 4; ++j) *((f32x4*)xr + lane + 64 * j) = v[j];
;         }
;         const float rstd = 1.0f / sqrtf(wave_sum(s2, lane) * (1.0f / DM) + RMS_EPS);
;         const float* mrow = mod + (size_t)bb * MODW;
; #pragma unroll
;         for (int j = 0; j < 4; ++j) {
;             const int c0 = 4 * (lane + 64 * j);
;             const f32x4 g = *(const f32x4*)(gain + c0), sh = *(const f32x4*)(mrow + c0), scl = *(const f32x4*)(mrow + DM + c0);
;             const f32x4 y = v[j] * rstd * g * (scl + 1.0f) + sh;
;             u32x2 w; w.x = pk2(y.x, y.y); w.y = pk2(y.z, y.w);
;             *(u32x2*)(H + (size_t)r * DM + c0) = w;
;         }
;     }
	v_add_f32_e32 v34, v34, v32
	v_fmamk_f32 v34, v34, 0x3a800000, v201
	v_cmp_gt_f32_e32 vcc, 0xf800000, v34
	v_mul_f32_e32 v32, 0x4f800000, v34
	s_nop 0
	v_cndmask_b32_e32 v34, v34, v32, vcc
	v_sqrt_f32_e32 v32, v34
	s_nop 0
	v_add_u32_e32 v35, -1, v32
	v_fma_f32 v36, -v35, v32, v34
	v_cmp_ge_f32_e64 s[42:43], 0, v36
	v_add_u32_e32 v36, 1, v32
	s_nop 0
	v_cndmask_b32_e64 v35, v32, v35, s[42:43]
	v_fma_f32 v32, -v36, v32, v34
	v_cmp_lt_f32_e64 s[42:43], 0, v32
	s_nop 1
	v_cndmask_b32_e64 v32, v35, v36, s[42:43]
	v_mul_f32_e32 v35, 0x37800000, v32
	v_cndmask_b32_e32 v32, v32, v35, vcc
	v_cmp_class_f32_e32 vcc, v34, v202
	s_nop 1
	v_cndmask_b32_e32 v34, v32, v34, vcc
	v_div_scale_f32 v32, s[42:43], v34, v34, 1.0
	v_rcp_f32_e32 v35, v32
	s_nop 0
	v_fma_f32 v36, -v32, v35, 1.0
	v_fmac_f32_e32 v35, v36, v35
	v_div_scale_f32 v36, vcc, 1.0, v34, 1.0
	v_mul_f32_e32 v37, v36, v35
	v_fma_f32 v178, -v32, v37, v36
	v_fmac_f32_e32 v37, v178, v35
	v_fma_f32 v32, -v32, v37, v36
	v_div_fmas_f32 v32, v32, v35, v37
	v_div_fixup_f32 v179, v32, v34, 1.0
	s_lshl_b32 s8, s101, 11
	s_add_u32 s0, s46, s8
	s_addc_u32 s1, s47, 0
	s_add_u32 s0, s0, 0x5500000
	s_addc_u32 s1, s1, 0
	s_waitcnt vmcnt(8)
	v_mul_f32_e32 v193, v0, v179
	v_add_f32_e32 v192, 1.0, v72
	v_mul_f32_e32 v193, v162, v193
	v_fma_f32 v180, v192, v193, v56
	v_mul_f32_e32 v193, v1, v179
	v_add_f32_e32 v192, 1.0, v73
	v_mul_f32_e32 v193, v163, v193
	v_fma_f32 v181, v192, v193, v57
	v_mul_f32_e32 v193, v2, v179
	v_add_f32_e32 v192, 1.0, v74
	v_mul_f32_e32 v193, v164, v193
	v_fma_f32 v182, v192, v193, v58
	v_mul_f32_e32 v193, v3, v179
	v_add_f32_e32 v192, 1.0, v75
	v_mul_f32_e32 v193, v165, v193
	v_fma_f32 v183, v192, v193, v59
	v_cvt_pk_bf16_f32 v184, v180, v181
	v_cvt_pk_bf16_f32 v185, v182, v183
	global_store_dwordx2 v121, v[184:185], s[0:1]
	v_mul_f32_e32 v193, v4, v179
	v_add_f32_e32 v192, 1.0, v76
	v_mul_f32_e32 v193, v166, v193
	v_fma_f32 v180, v192, v193, v60
	v_mul_f32_e32 v193, v5, v179
	v_add_f32_e32 v192, 1.0, v77
	v_mul_f32_e32 v193, v167, v193
	v_fma_f32 v181, v192, v193, v61
	v_mul_f32_e32 v193, v6, v179
	v_add_f32_e32 v192, 1.0, v78
	v_mul_f32_e32 v193, v168, v193
	v_fma_f32 v182, v192, v193, v62
	v_mul_f32_e32 v193, v7, v179
	v_add_f32_e32 v192, 1.0, v79
	v_mul_f32_e32 v193, v169, v193
	v_fma_f32 v183, v192, v193, v63
	v_cvt_pk_bf16_f32 v186, v180, v181
	v_cvt_pk_bf16_f32 v187, v182, v183
	global_store_dwordx2 v121, v[186:187], s[0:1] offset:512
	v_mul_f32_e32 v193, v8, v179
	v_add_f32_e32 v192, 1.0, v80
	v_mul_f32_e32 v193, v170, v193
	v_fma_f32 v180, v192, v193, v64
	v_mul_f32_e32 v193, v9, v179
	v_add_f32_e32 v192, 1.0, v81
	v_mul_f32_e32 v193, v171, v193
	v_fma_f32 v181, v192, v193, v65
	v_mul_f32_e32 v193, v10, v179
	v_add_f32_e32 v192, 1.0, v82
	v_mul_f32_e32 v193, v172, v193
	v_fma_f32 v182, v192, v193, v66
	v_mul_f32_e32 v193, v11, v179
	v_add_f32_e32 v192, 1.0, v83
	v_mul_f32_e32 v193, v173, v193
	v_fma_f32 v183, v192, v193, v67
	v_cvt_pk_bf16_f32 v188, v180, v181
	v_cvt_pk_bf16_f32 v189, v182, v183
	global_store_dwordx2 v121, v[188:189], s[0:1] offset:1024
	v_mul_f32_e32 v193, v12, v179
	v_add_f32_e32 v192, 1.0, v84
	v_mul_f32_e32 v193, v174, v193
	v_fma_f32 v180, v192, v193, v68
	v_mul_f32_e32 v193, v13, v179
	v_add_f32_e32 v192, 1.0, v85
	v_mul_f32_e32 v193, v175, v193
	v_fma_f32 v181, v192, v193, v69
	v_mul_f32_e32 v193, v14, v179
	v_add_f32_e32 v192, 1.0, v86
	v_mul_f32_e32 v193, v176, v193
	v_fma_f32 v182, v192, v193, v70
	v_mul_f32_e32 v193, v15, v179
	v_add_f32_e32 v192, 1.0, v87
	v_mul_f32_e32 v193, v177, v193
	v_fma_f32 v183, v192, v193, v71
	v_cvt_pk_bf16_f32 v190, v180, v181
	v_cvt_pk_bf16_f32 v191, v182, v183
	global_store_dwordx2 v121, v[190:191], s[0:1] offset:1536
	s_mul_i32 s100, s68, 3
	s_add_u32 s100, s100, s101
	s_cmp_le_u32 s100, s71
	s_cselect_b32 s100, s100, s101
	s_lshr_b32 s8, s100, 8
	s_mul_i32 s8, s8, 57
	s_lshr_b32 s8, s8, 9
	s_mul_i32 s9, s8, 0x900
	s_sub_u32 s9, s100, s9
	s_lshl_b32 s0, s8, 11
	s_add_u32 s0, s0, s9
	s_sub_u32 s0, s0, 0x100
	s_lshl_b32 s8, s8, 8
	s_add_u32 s8, s8, s9
	s_cmp_lt_u32 s9, 0x100
	s_cselect_b32 s8, s8, s0
	s_cselect_b32 s0, s36, s44
	s_cselect_b32 s1, s37, s45
	s_lshl_b32 s8, s8, 12
	s_add_u32 s0, s0, s8
	s_addc_u32 s1, s1, 0
	global_load_dwordx4 v[0:3], v120, s[0:1]
	global_load_dwordx4 v[4:7], v120, s[0:1] offset:1024
	global_load_dwordx4 v[8:11], v120, s[0:1] offset:2048
	global_load_dwordx4 v[12:15], v120, s[0:1] offset:3072
	s_add_u32 s101, s101, s68
	s_cmp_gt_u32 s101, s71
	s_cbranch_scc1 .Lnf_n2_exit
; __device__ __forceinline__ unsigned pk2(float lo, float hi) { f32x2_t v = {lo, hi}; bf16x2_t b = __builtin_convertvector(v, bf16x2_t); return __builtin_bit_cast(unsigned, b); }
; __device__ __forceinline__ void phase_norm(const Params& P, int l, int which, bool first) {
;     ...
;     for (int r = gw; r < ROWS; r += NGW) {
;         const int b = r / TT, t = r - b * TT; const int bb = (t < CTX) ? 16 : b;
;         float* xr = xrow_ptr(P, r);
;         const float* src = first ? ((t < CTX) ? P.ctx + ((size_t)b * CTX + t) * DM : P.x + ((size_t)b * SEQ + (t - CTX)) * DM) : xr;
;         f32x4 v[4]; float s2 = 0.f;
; #pragma unroll
;         for (int j = 0; j < 4; ++j) { v[j] = *((const f32x4*)src + lane + 64 * j); s2 += (v[j].x * v[j].x + v[j].y * v[j].y) + (v[j].z * v[j].z + v[j].w * v[j].w); }
;         if (first) {
; #pragma unroll
;             for (int j = 0; j < 4; ++j) *((f32x4*)xr + lane + 64 * j) = v[j];
;         }
;         const float rstd = 1.0f / sqrtf(wave_sum(s2, lane) * (1.0f / DM) + RMS_EPS);
;         const float* mrow = mod + (size_t)bb * MODW;
; #pragma unroll
;         for (int j = 0; j < 4; ++j) {
;             const int c0 = 4 * (lane + 64 * j);
;             const f32x4 g = *(const f32x4*)(gain + c0), sh = *(const f32x4*)(mrow + c0), scl = *(const f32x4*)(mrow + DM + c0);
;             const f32x4 y = v[j] * rstd * g * (scl + 1.0f) + sh;
;             u32x2 w; w.x = pk2(y.x, y.y); w.y = pk2(y.z, y.w);
;             *(u32x2*)(H + (size_t)r * DM + c0) = w;
;         }
;     }
	s_waitcnt vmcnt(28)
	s_add_u32 s100, s101, s68
	s_cmp_le_u32 s100, s71
	s_cselect_b32 s100, s100, s101
	s_lshr_b32 s8, s100, 8
	s_mul_i32 s8, s8, 57
	s_lshr_b32 s8, s8, 9
	s_mul_i32 s9, s8, 0x900
	s_sub_u32 s9, s100, s9
	s_cmp_lt_u32 s9, 0x100
	s_cselect_b32 s8, 16, s8
	s_mul_i32 s8, s8, 0x6000
	s_add_u32 s0, s24, s8
	s_addc_u32 s1, s25, 0
	global_load_dwordx4 v[130:133], v120, s[0:1] offset:-4096
	global_load_dwordx4 v[134:137], v120, s[0:1] offset:-3072
	global_load_dwordx4 v[138:141], v120, s[0:1] offset:-2048
	global_load_dwordx4 v[142:145], v120, s[0:1] offset:-1024
	global_load_dwordx4 v[146:149], v120, s[0:1]
	global_load_dwordx4 v[150:153], v120, s[0:1] offset:1024
	global_load_dwordx4 v[154:157], v120, s[0:1] offset:2048
	global_load_dwordx4 v[158:161], v120, s[0:1] offset:3072
	v_mul_f32_e32 v32, v17, v17
	v_mul_f32_e32 v33, v19, v19
	v_fmac_f32_e32 v32, v16, v16
	v_fmac_f32_e32 v33, v18, v18
	v_add_f32_e32 v34, v32, v33
	v_mul_f32_e32 v32, v21, v21
	v_mul_f32_e32 v33, v23, v23
	v_fmac_f32_e32 v32, v20, v20
	v_fmac_f32_e32 v33, v22, v22
	v_add_f32_e32 v32, v32, v33
	v_add_f32_e32 v34, v34, v32
	v_mul_f32_e32 v32, v25, v25
	v_mul_f32_e32 v33, v27, v27
	v_fmac_f32_e32 v32, v24, v24
	v_fmac_f32_e32 v33, v26, v26
	v_add_f32_e32 v32, v32, v33
	v_add_f32_e32 v34, v34, v32
	v_mul_f32_e32 v32, v29, v29
	v_mul_f32_e32 v33, v31, v31
	v_fmac_f32_e32 v32, v28, v28
	v_fmac_f32_e32 v33, v30, v30
	v_add_f32_e32 v32, v32, v33
	v_add_f32_e32 v34, v34, v32
	ds_bpermute_b32 v32, v122, v34
	s_waitcnt lgkmcnt(0)
	v_add_f32_e32 v34, v34, v32
	ds_bpermute_b32 v32, v123, v34
	s_waitcnt lgkmcnt(0)
	v_add_f32_e32 v34, v34, v32
	ds_bpermute_b32 v32, v124, v34
	s_waitcnt lgkmcnt(0)
	v_add_f32_e32 v34, v34, v32
	ds_bpermute_b32 v32, v125, v34
	s_waitcnt lgkmcnt(0)
	v_add_f32_e32 v34, v34, v32
	ds_bpermute_b32 v32, v126, v34
	s_waitcnt lgkmcnt(0)
	v_add_f32_e32 v34, v34, v32
	ds_bpermute_b32 v32, v127, v34
	s_waitcnt lgkmcnt(0)
	v_add_f32_e32 v34, v34, v32
	v_fmamk_f32 v34, v34, 0x3a800000, v201
	v_cmp_gt_f32_e32 vcc, 0xf800000, v34
	v_mul_f32_e32 v32, 0x4f800000, v34
	s_nop 0
	v_cndmask_b32_e32 v34, v34, v32, vcc
	v_sqrt_f32_e32 v32, v34
	s_nop 0
	v_add_u32_e32 v35, -1, v32
	v_fma_f32 v36, -v35, v32, v34
	v_cmp_ge_f32_e64 s[42:43], 0, v36
	v_add_u32_e32 v36, 1, v32
	s_nop 0
	v_cndmask_b32_e64 v35, v32, v35, s[42:43]
	v_fma_f32 v32, -v36, v32, v34
	v_cmp_lt_f32_e64 s[42:43], 0, v32
	s_nop 1
	v_cndmask_b32_e64 v32, v35, v36, s[42:43]
	v_mul_f32_e32 v35, 0x37800000, v32
	v_cndmask_b32_e32 v32, v32, v35, vcc
	v_cmp_class_f32_e32 vcc, v34, v202
	s_nop 1
	v_cndmask_b32_e32 v34, v32, v34, vcc
	v_div_scale_f32 v32, s[42:43], v34, v34, 1.0
	v_rcp_f32_e32 v35, v32
	s_nop 0
	v_fma_f32 v36, -v32, v35, 1.0
	v_fmac_f32_e32 v35, v36, v35
	v_div_scale_f32 v36, vcc, 1.0, v34, 1.0
	v_mul_f32_e32 v37, v36, v35
	v_fma_f32 v178, -v32, v37, v36
	v_fmac_f32_e32 v37, v178, v35
	v_fma_f32 v32, -v32, v37, v36
	v_div_fmas_f32 v32, v32, v35, v37
	v_div_fixup_f32 v179, v32, v34, 1.0
	s_lshl_b32 s8, s101, 11
	s_add_u32 s0, s46, s8
	s_addc_u32 s1, s47, 0
	s_add_u32 s0, s0, 0x5500000
	s_addc_u32 s1, s1, 0
	s_waitcnt vmcnt(16)
	v_mul_f32_e32 v193, v16, v179
	v_add_f32_e32 v192, 1.0, v104
	v_mul_f32_e32 v193, v162, v193
	v_fma_f32 v180, v192, v193, v88
	v_mul_f32_e32 v193, v17, v179
	v_add_f32_e32 v192, 1.0, v105
	v_mul_f32_e32 v193, v163, v193
	v_fma_f32 v181, v192, v193, v89
	v_mul_f32_e32 v193, v18, v179
	v_add_f32_e32 v192, 1.0, v106
	v_mul_f32_e32 v193, v164, v193
	v_fma_f32 v182, v192, v193, v90
	v_mul_f32_e32 v193, v19, v179
	v_add_f32_e32 v192, 1.0, v107
	v_mul_f32_e32 v193, v165, v193
	v_fma_f32 v183, v192, v193, v91
	v_cvt_pk_bf16_f32 v184, v180, v181
	v_cvt_pk_bf16_f32 v185, v182, v183
	global_store_dwordx2 v121, v[184:185], s[0:1]
	v_mul_f32_e32 v193, v20, v179
	v_add_f32_e32 v192, 1.0, v108
	v_mul_f32_e32 v193, v166, v193
	v_fma_f32 v180, v192, v193, v92
	v_mul_f32_e32 v193, v21, v179
	v_add_f32_e32 v192, 1.0, v109
	v_mul_f32_e32 v193, v167, v193
	v_fma_f32 v181, v192, v193, v93
	v_mul_f32_e32 v193, v22, v179
	v_add_f32_e32 v192, 1.0, v110
	v_mul_f32_e32 v193, v168, v193
	v_fma_f32 v182, v192, v193, v94
	v_mul_f32_e32 v193, v23, v179
	v_add_f32_e32 v192, 1.0, v111
	v_mul_f32_e32 v193, v169, v193
	v_fma_f32 v183, v192, v193, v95
	v_cvt_pk_bf16_f32 v186, v180, v181
	v_cvt_pk_bf16_f32 v187, v182, v183
	global_store_dwordx2 v121, v[186:187], s[0:1] offset:512
	v_mul_f32_e32 v193, v24, v179
	v_add_f32_e32 v192, 1.0, v112
	v_mul_f32_e32 v193, v170, v193
	v_fma_f32 v180, v192, v193, v96
	v_mul_f32_e32 v193, v25, v179
	v_add_f32_e32 v192, 1.0, v113
	v_mul_f32_e32 v193, v171, v193
	v_fma_f32 v181, v192, v193, v97
	v_mul_f32_e32 v193, v26, v179
	v_add_f32_e32 v192, 1.0, v114
	v_mul_f32_e32 v193, v172, v193
	v_fma_f32 v182, v192, v193, v98
	v_mul_f32_e32 v193, v27, v179
	v_add_f32_e32 v192, 1.0, v115
	v_mul_f32_e32 v193, v173, v193
	v_fma_f32 v183, v192, v193, v99
	v_cvt_pk_bf16_f32 v188, v180, v181
	v_cvt_pk_bf16_f32 v189, v182, v183
	global_store_dwordx2 v121, v[188:189], s[0:1] offset:1024
	v_mul_f32_e32 v193, v28, v179
	v_add_f32_e32 v192, 1.0, v116
	v_mul_f32_e32 v193, v174, v193
	v_fma_f32 v180, v192, v193, v100
	v_mul_f32_e32 v193, v29, v179
	v_add_f32_e32 v192, 1.0, v117
	v_mul_f32_e32 v193, v175, v193
	v_fma_f32 v181, v192, v193, v101
	v_mul_f32_e32 v193, v30, v179
	v_add_f32_e32 v192, 1.0, v118
	v_mul_f32_e32 v193, v176, v193
	v_fma_f32 v182, v192, v193, v102
	v_mul_f32_e32 v193, v31, v179
	v_add_f32_e32 v192, 1.0, v119
	v_mul_f32_e32 v193, v177, v193
	v_fma_f32 v183, v192, v193, v103
	v_cvt_pk_bf16_f32 v190, v180, v181
	v_cvt_pk_bf16_f32 v191, v182, v183
	global_store_dwordx2 v121, v[190:191], s[0:1] offset:1536
	s_mul_i32 s100, s68, 3
	s_add_u32 s100, s100, s101
	s_cmp_le_u32 s100, s71
	s_cselect_b32 s100, s100, s101
	s_lshr_b32 s8, s100, 8
	s_mul_i32 s8, s8, 57
	s_lshr_b32 s8, s8, 9
	s_mul_i32 s9, s8, 0x900
	s_sub_u32 s9, s100, s9
	s_lshl_b32 s0, s8, 11
	s_add_u32 s0, s0, s9
	s_sub_u32 s0, s0, 0x100
	s_lshl_b32 s8, s8, 8
	s_add_u32 s8, s8, s9
	s_cmp_lt_u32 s9, 0x100
	s_cselect_b32 s8, s8, s0
	s_cselect_b32 s0, s36, s44
	s_cselect_b32 s1, s37, s45
	s_lshl_b32 s8, s8, 12
	s_add_u32 s0, s0, s8
	s_addc_u32 s1, s1, 0
	global_load_dwordx4 v[16:19], v120, s[0:1]
	global_load_dwordx4 v[20:23], v120, s[0:1] offset:1024
	global_load_dwordx4 v[24:27], v120, s[0:1] offset:2048
	global_load_dwordx4 v[28:31], v120, s[0:1] offset:3072
	s_add_u32 s101, s101, s68
	s_cmp_gt_u32 s101, s71
	s_cbranch_scc1 .Lnf_n2_exit
; __device__ __forceinline__ unsigned pk2(float lo, float hi) { f32x2_t v = {lo, hi}; bf16x2_t b = __builtin_convertvector(v, bf16x2_t); return __builtin_bit_cast(unsigned, b); }
; __device__ __forceinline__ void phase_norm(const Params& P, int l, int which, bool first) {
;     ...
;     for (int r = gw; r < ROWS; r += NGW) {
;         const int b = r / TT, t = r - b * TT; const int bb = (t < CTX) ? 16 : b;
;         float* xr = xrow_ptr(P, r);
;         const float* src = first ? ((t < CTX) ? P.ctx + ((size_t)b * CTX + t) * DM : P.x + ((size_t)b * SEQ + (t - CTX)) * DM) : xr;
;         f32x4 v[4]; float s2 = 0.f;
; #pragma unroll
;         for (int j = 0; j < 4; ++j) { v[j] = *((const f32x4*)src + lane + 64 * j); s2 += (v[j].x * v[j].x + v[j].y * v[j].y) + (v[j].z * v[j].z + v[j].w * v[j].w); }
;         if (first) {
; #pragma unroll
;             for (int j = 0; j < 4; ++j) *((f32x4*)xr + lane + 64 * j) = v[j];
;         }
;         const float rstd = 1.0f / sqrtf(wave_sum(s2, lane) * (1.0f / DM) + RMS_EPS);
;         const float* mrow = mod + (size_t)bb * MODW;
; #pragma unroll
;         for (int j = 0; j < 4; ++j) {
;             const int c0 = 4 * (lane + 64 * j);
;             const f32x4 g = *(const f32x4*)(gain + c0), sh = *(const f32x4*)(mrow + c0), scl = *(const f32x4*)(mrow + DM + c0);
;             const f32x4 y = v[j] * rstd * g * (scl + 1.0f) + sh;
;             u32x2 w; w.x = pk2(y.x, y.y); w.y = pk2(y.z, y.w);
;             *(u32x2*)(H + (size_t)r * DM + c0) = w;
;         }
;     }
	s_waitcnt vmcnt(32)
	s_add_u32 s100, s101, s68
	s_cmp_le_u32 s100, s71
	s_cselect_b32 s100, s100, s101
	s_lshr_b32 s8, s100, 8
	s_mul_i32 s8, s8, 57
	s_lshr_b32 s8, s8, 9
	s_mul_i32 s9, s8, 0x900
	s_sub_u32 s9, s100, s9
	s_cmp_lt_u32 s9, 0x100
	s_cselect_b32 s8, 16, s8
	s_mul_i32 s8, s8, 0x6000
	s_add_u32 s0, s24, s8
	s_addc_u32 s1, s25, 0
	global_load_dwordx4 v[56:59], v120, s[0:1] offset:-4096
	global_load_dwordx4 v[60:63], v120, s[0:1] offset:-3072
	global_load_dwordx4 v[64:67], v120, s[0:1] offset:-2048
	global_load_dwordx4 v[68:71], v120, s[0:1] offset:-1024
	global_load_dwordx4 v[72:75], v120, s[0:1]
	global_load_dwordx4 v[76:79], v120, s[0:1] offset:1024
	global_load_dwordx4 v[80:83], v120, s[0:1] offset:2048
	global_load_dwordx4 v[84:87], v120, s[0:1] offset:3072
	v_mul_f32_e32 v32, v41, v41
	v_mul_f32_e32 v33, v43, v43
	v_fmac_f32_e32 v32, v40, v40
	v_fmac_f32_e32 v33, v42, v42
	v_add_f32_e32 v34, v32, v33
	v_mul_f32_e32 v32, v45, v45
	v_mul_f32_e32 v33, v47, v47
	v_fmac_f32_e32 v32, v44, v44
	v_fmac_f32_e32 v33, v46, v46
	v_add_f32_e32 v32, v32, v33
	v_add_f32_e32 v34, v34, v32
	v_mul_f32_e32 v32, v49, v49
	v_mul_f32_e32 v33, v51, v51
	v_fmac_f32_e32 v32, v48, v48
	v_fmac_f32_e32 v33, v50, v50
	v_add_f32_e32 v32, v32, v33
	v_add_f32_e32 v34, v34, v32
	v_mul_f32_e32 v32, v53, v53
	v_mul_f32_e32 v33, v55, v55
	v_fmac_f32_e32 v32, v52, v52
	v_fmac_f32_e32 v33, v54, v54
	v_add_f32_e32 v32, v32, v33
	v_add_f32_e32 v34, v34, v32
	ds_bpermute_b32 v32, v122, v34
	s_waitcnt lgkmcnt(0)
	v_add_f32_e32 v34, v34, v32
	ds_bpermute_b32 v32, v123, v34
	s_waitcnt lgkmcnt(0)
	v_add_f32_e32 v34, v34, v32
	ds_bpermute_b32 v32, v124, v34
	s_waitcnt lgkmcnt(0)
	v_add_f32_e32 v34, v34, v32
	ds_bpermute_b32 v32, v125, v34
	s_waitcnt lgkmcnt(0)
	v_add_f32_e32 v34, v34, v32
	ds_bpermute_b32 v32, v126, v34
	s_waitcnt lgkmcnt(0)
	v_add_f32_e32 v34, v34, v32
	ds_bpermute_b32 v32, v127, v34
	s_waitcnt lgkmcnt(0)
	v_add_f32_e32 v34, v34, v32
	v_fmamk_f32 v34, v34, 0x3a800000, v201
	v_cmp_gt_f32_e32 vcc, 0xf800000, v34
	v_mul_f32_e32 v32, 0x4f800000, v34
	s_nop 0
	v_cndmask_b32_e32 v34, v34, v32, vcc
	v_sqrt_f32_e32 v32, v34
	s_nop 0
	v_add_u32_e32 v35, -1, v32
	v_fma_f32 v36, -v35, v32, v34
	v_cmp_ge_f32_e64 s[42:43], 0, v36
	v_add_u32_e32 v36, 1, v32
	s_nop 0
	v_cndmask_b32_e64 v35, v32, v35, s[42:43]
	v_fma_f32 v32, -v36, v32, v34
	v_cmp_lt_f32_e64 s[42:43], 0, v32
	s_nop 1
	v_cndmask_b32_e64 v32, v35, v36, s[42:43]
	v_mul_f32_e32 v35, 0x37800000, v32
	v_cndmask_b32_e32 v32, v32, v35, vcc
	v_cmp_class_f32_e32 vcc, v34, v202
	s_nop 1
	v_cndmask_b32_e32 v34, v32, v34, vcc
	v_div_scale_f32 v32, s[42:43], v34, v34, 1.0
	v_rcp_f32_e32 v35, v32
	s_nop 0
	v_fma_f32 v36, -v32, v35, 1.0
	v_fmac_f32_e32 v35, v36, v35
	v_div_scale_f32 v36, vcc, 1.0, v34, 1.0
	v_mul_f32_e32 v37, v36, v35
	v_fma_f32 v178, -v32, v37, v36
	v_fmac_f32_e32 v37, v178, v35
	v_fma_f32 v32, -v32, v37, v36
	v_div_fmas_f32 v32, v32, v35, v37
	v_div_fixup_f32 v179, v32, v34, 1.0
	s_lshl_b32 s8, s101, 11
	s_add_u32 s0, s46, s8
	s_addc_u32 s1, s47, 0
	s_add_u32 s0, s0, 0x5500000
	s_addc_u32 s1, s1, 0
	s_waitcnt vmcnt(16)
	v_mul_f32_e32 v193, v40, v179
	v_add_f32_e32 v192, 1.0, v146
	v_mul_f32_e32 v193, v162, v193
	v_fma_f32 v180, v192, v193, v130
	v_mul_f32_e32 v193, v41, v179
	v_add_f32_e32 v192, 1.0, v147
	v_mul_f32_e32 v193, v163, v193
	v_fma_f32 v181, v192, v193, v131
	v_mul_f32_e32 v193, v42, v179
	v_add_f32_e32 v192, 1.0, v148
	v_mul_f32_e32 v193, v164, v193
	v_fma_f32 v182, v192, v193, v132
	v_mul_f32_e32 v193, v43, v179
	v_add_f32_e32 v192, 1.0, v149
	v_mul_f32_e32 v193, v165, v193
	v_fma_f32 v183, v192, v193, v133
	v_cvt_pk_bf16_f32 v184, v180, v181
	v_cvt_pk_bf16_f32 v185, v182, v183
	global_store_dwordx2 v121, v[184:185], s[0:1]
	v_mul_f32_e32 v193, v44, v179
	v_add_f32_e32 v192, 1.0, v150
	v_mul_f32_e32 v193, v166, v193
	v_fma_f32 v180, v192, v193, v134
	v_mul_f32_e32 v193, v45, v179
	v_add_f32_e32 v192, 1.0, v151
	v_mul_f32_e32 v193, v167, v193
	v_fma_f32 v181, v192, v193, v135
	v_mul_f32_e32 v193, v46, v179
	v_add_f32_e32 v192, 1.0, v152
	v_mul_f32_e32 v193, v168, v193
	v_fma_f32 v182, v192, v193, v136
	v_mul_f32_e32 v193, v47, v179
	v_add_f32_e32 v192, 1.0, v153
	v_mul_f32_e32 v193, v169, v193
	v_fma_f32 v183, v192, v193, v137
	v_cvt_pk_bf16_f32 v186, v180, v181
	v_cvt_pk_bf16_f32 v187, v182, v183
	global_store_dwordx2 v121, v[186:187], s[0:1] offset:512
	v_mul_f32_e32 v193, v48, v179
	v_add_f32_e32 v192, 1.0, v154
	v_mul_f32_e32 v193, v170, v193
	v_fma_f32 v180, v192, v193, v138
	v_mul_f32_e32 v193, v49, v179
	v_add_f32_e32 v192, 1.0, v155
	v_mul_f32_e32 v193, v171, v193
	v_fma_f32 v181, v192, v193, v139
	v_mul_f32_e32 v193, v50, v179
	v_add_f32_e32 v192, 1.0, v156
	v_mul_f32_e32 v193, v172, v193
	v_fma_f32 v182, v192, v193, v140
	v_mul_f32_e32 v193, v51, v179
	v_add_f32_e32 v192, 1.0, v157
	v_mul_f32_e32 v193, v173, v193
	v_fma_f32 v183, v192, v193, v141
	v_cvt_pk_bf16_f32 v188, v180, v181
	v_cvt_pk_bf16_f32 v189, v182, v183
	global_store_dwordx2 v121, v[188:189], s[0:1] offset:1024
	v_mul_f32_e32 v193, v52, v179
	v_add_f32_e32 v192, 1.0, v158
	v_mul_f32_e32 v193, v174, v193
	v_fma_f32 v180, v192, v193, v142
	v_mul_f32_e32 v193, v53, v179
	v_add_f32_e32 v192, 1.0, v159
	v_mul_f32_e32 v193, v175, v193
	v_fma_f32 v181, v192, v193, v143
	v_mul_f32_e32 v193, v54, v179
	v_add_f32_e32 v192, 1.0, v160
	v_mul_f32_e32 v193, v176, v193
	v_fma_f32 v182, v192, v193, v144
	v_mul_f32_e32 v193, v55, v179
	v_add_f32_e32 v192, 1.0, v161
	v_mul_f32_e32 v193, v177, v193
	v_fma_f32 v183, v192, v193, v145
	v_cvt_pk_bf16_f32 v190, v180, v181
	v_cvt_pk_bf16_f32 v191, v182, v183
	global_store_dwordx2 v121, v[190:191], s[0:1] offset:1536
	s_mul_i32 s100, s68, 3
	s_add_u32 s100, s100, s101
	s_cmp_le_u32 s100, s71
	s_cselect_b32 s100, s100, s101
	s_lshr_b32 s8, s100, 8
	s_mul_i32 s8, s8, 57
	s_lshr_b32 s8, s8, 9
	s_mul_i32 s9, s8, 0x900
	s_sub_u32 s9, s100, s9
	s_lshl_b32 s0, s8, 11
	s_add_u32 s0, s0, s9
	s_sub_u32 s0, s0, 0x100
	s_lshl_b32 s8, s8, 8
	s_add_u32 s8, s8, s9
	s_cmp_lt_u32 s9, 0x100
	s_cselect_b32 s8, s8, s0
	s_cselect_b32 s0, s36, s44
	s_cselect_b32 s1, s37, s45
	s_lshl_b32 s8, s8, 12
	s_add_u32 s0, s0, s8
	s_addc_u32 s1, s1, 0
	global_load_dwordx4 v[40:43], v120, s[0:1]
	global_load_dwordx4 v[44:47], v120, s[0:1] offset:1024
	global_load_dwordx4 v[48:51], v120, s[0:1] offset:2048
	global_load_dwordx4 v[52:55], v120, s[0:1] offset:3072
	s_add_u32 s101, s101, s68
	s_cmp_gt_u32 s101, s71
	s_cbranch_scc1 .Lnf_n2_exit

; __device__ __forceinline__ void xcd_barrier(const XcdBarrier& b) {
;     asm volatile("s_waitcnt vmcnt(0)" ::: "memory");
;     __syncthreads();
;     if (threadIdx.x == 0) {
;         unsigned* bar = b.bar;
;         __builtin_amdgcn_s_waitcnt(0);
;         unsigned nloc = b.st[0], nx = b.st[1];
;         if (nloc == 0u) { xcd_barrier_complete(bar, b.x, nloc, nx); b.st[0] = nloc; b.st[1] = nx; }
.Lnf_n2_join:
.LBB0_940:
	s_mov_b32 s7, 0xf800000
	s_or_b64 exec, exec, s[10:11]
	s_waitcnt vmcnt(0)
	s_barrier
	s_mov_b64 s[10:11], exec
	v_readlane_b32 s0, v253, 0
	v_readlane_b32 s1, v253, 1
	s_and_b64 s[0:1], s[10:11], s[0:1]
	s_mov_b64 exec, s[0:1]
	s_cbranch_execz .LBB0_992
	v_readlane_b32 s0, v254, 24
	s_waitcnt vmcnt(0) expcnt(0) lgkmcnt(0)
	s_nop 0
	v_mov_b32_e32 v0, s0
	ds_read_b32 v2, v0
	v_readlane_b32 s0, v254, 25
	s_waitcnt lgkmcnt(0)
	v_cmp_ne_u32_e32 vcc, 0, v2
	v_mov_b32_e32 v0, s0
	ds_read_b32 v0, v0
	s_cbranch_vccnz .LBB0_956
	s_mov_b32 s0, 1
	s_branch .LBB0_944
